# dilated-attention walks: fp8 K and V fragments stored as 16-byte fragment pairs (projection epilogues re-addressed) and fetched with dwordx4 loads, 8 per step instead of 16 dwordx2; counted vmcnt upda
# speedup vs baseline: 1.0817x; 1.0094x over previous
; #define PG8_STAGE(bufoff, gbase, voff) do { _Pragma("unroll") for (int _i = 0; _i < 2; ++_i) \
;         __builtin_amdgcn_global_load_lds((const unsigned*)((const char*)(gbase) + (voff)[_i]), (LAS unsigned*)(lds + (bufoff) + ldsw + _i * 8192), 16, 0, 0); } while (0)
; #define PG8_WAIT_V(n) asm volatile("s_waitcnt vmcnt(" #n ")" ::: "memory")
; #define PG8_BAR __builtin_amdgcn_s_barrier()
; template <class Epi, bool FP8 = false>
; __device__ __forceinline__ void gemm_phase(LAS unsigned char* lds, const Gemm g, const StaticOrder& S_, const Epi& E, const int tid) {
;     const int wid = __builtin_amdgcn_readfirstlane(tid >> 6), lane = tid & 63, wr = wid >> 2, wc = wid & 3, fr = lane & 15, fq = lane >> 4;
;     const int K = g.K, nt = K / BK;
;     unsigned voffA[2], voffB[2];
; #pragma unroll
;     for (int i = 0; i < 2; ++i) { int R, C; stage_rc(tid * 16 + i * 8192, R, C); const int Rb = Epi::PERM ? ((R & ~31) + perm32(R & 31)) : R;
;         voffA[i] = (unsigned)(R * g.lda + C) * 2u; voffB[i] = (unsigned)(Rb * g.ldb + C) * 2u; }
;     const size_t kstep = (size_t)(BK * 2);
;     const size_t hstepA = (size_t)HALF * g.lda * 2, hstepB = (size_t)HALF * g.ldb * 2;
;     const size_t tstepA = 2 * hstepA, tstepB = 2 * hstepB;
;     const unsigned ldsw = (unsigned)wid * 1024u;
;     const int aoff = lds_byte(wr * 64 + fr, fq * 8), boff = lds_byte(wc * 32 + fr, fq * 8);
;     ...
;     Unit cur, nxt; int ui = 0;
;     if (!S_.next(0, cur)) return;
;     Acc acc;
; #pragma unroll
;     for (int a = 0; a < 2; ++a)
; #pragma unroll
;         for (int b = 0; b < 2; ++b)
; #pragma unroll
;             for (int m = 0; m < 4; ++m)
; #pragma unroll
;                 for (int n = 0; n < 2; ++n) acc[a][b][m][n] = (f32x4){0.f, 0.f, 0.f, 0.f};
;     bf16x8 At[4][2], B0[2][2], B1[2][2];
;     const char* cA = (const char*)g.A + (size_t)cur.pm * tstepA; const char* cB = (const char*)g.Bt + (size_t)cur.pn * tstepB;
;     PG8_STAGE(PG8_SB(0, 0), cB, voffB); PG8_STAGE(PG8_SB(0, 1), cB + hstepB, voffB); PG8_STAGE(PG8_SA(0, 0), cA, voffA); PG8_STAGE(PG8_SA(0, 1), cA + hstepA, voffA);
;     if (wr == 1) PG8_BAR;
;     PG8_WAIT_V(2); PG8_BAR;
;     PG8_STAGE(PG8_SB(1, 0), cB + kstep, voffB); PG8_STAGE(PG8_SA(1, 0), cA + kstep, voffA); PG8_STAGE(PG8_SB(1, 1), cB + hstepB + kstep, voffB);
;     PG8_WAIT_V(6); PG8_BAR;
.LBB0_451:
	s_add_u32 s12, s4, 0xe000000
	s_addc_u32 s13, s5, 0
	s_add_u32 s24, s4, 0x1a000000
	s_addc_u32 s25, s5, 0
	v_bfe_u32 v15, v8, 4, 2
	s_add_u32 s76, s4, 0x14000000
	v_and_b32_e32 v155, 15, v8
	v_lshlrev_b32_e32 v17, 4, v15
	v_lshlrev_b32_e32 v18, 2, v8
	s_addc_u32 s77, s5, 0
	s_and_b32 s7, s22, 3
	s_lshl_b32 s78, s14, 6
	v_lshl_or_b32 v17, v155, 6, v17
	s_lshl_b32 s14, s14, 13
	v_and_b32_e32 v19, 32, v18
	v_bitop3_b32 v20, v17, s14, v19 bitop3:0xde
	s_lshl_b32 s14, s7, 12
	v_bitop3_b32 v163, s14, v17, v19 bitop3:0xf6
	s_mov_b64 s[14:15], 0x80
	s_add_i32 m0, s71, 0x18000
	v_lshl_add_u64 v[6:7], v[6:7], 0, s[14:15]
	s_lshl_b32 s20, s7, 5
	s_waitcnt vmcnt(2)
	s_barrier
	global_load_lds_dwordx4 v[6:7], off
	v_lshl_add_u64 v[4:5], v[4:5], 0, s[14:15]
	s_add_i32 m0, s71, 0x1a000
	s_add_i32 s79, s71, 0x8000
	s_add_i32 s80, s71, 0xa000
	global_load_lds_dwordx4 v[4:5], off
	v_lshl_add_u64 v[0:1], v[0:1], 0, s[14:15]
	s_mov_b32 m0, s79
	s_add_u32 s18, s56, 0x80080
	global_load_lds_dwordx4 v[0:1], off
	v_lshl_add_u64 v[0:1], v[2:3], 0, s[14:15]
	s_mov_b32 m0, s80
	s_addc_u32 s19, s57, 0
	global_load_lds_dwordx4 v[0:1], off
	s_add_i32 m0, s71, 0x1c000
	v_lshl_add_u64 v[0:1], s[18:19], 0, v[146:147]
	global_load_lds_dwordx4 v[0:1], off
	v_lshl_add_u64 v[0:1], s[18:19], 0, v[150:151]
	s_add_i32 m0, s71, 0x1e000
	s_cmpk_lt_u32 s16, 0x100
	global_load_lds_dwordx4 v[0:1], off
	s_cselect_b64 s[16:17], -1, 0
	s_cmp_eq_u32 s7, 0
	v_lshlrev_b32_e32 v16, 3, v15
	s_cselect_b64 s[18:19], -1, 0
	v_lshlrev_b32_e32 v0, 5, v8
	s_bfe_u32 s81, s22, 0x10001
	s_lshl_b32 s7, s22, 9
	v_or_b32_e32 v154, s20, v16
	v_and_b32_e32 v152, 0x180, v0
	v_bitop3_b32 v162, s20, 56, v16 bitop3:0xc8
	s_lshl_b32 s20, s81, 10
	s_and_b32 s22, s7, 0x200
	s_lshl_b32 s82, s81, 7
	s_ashr_i32 s83, s2, 31
	v_lshlrev_b32_e32 v0, 5, v154
	v_lshlrev_b32_e32 v189, 8, v15
	v_lshl_add_u64 v[166:167], s[24:25], 0, v[152:153]
	s_lshr_b32 s98, s22, 6
	v_mov_b32_e32 v246, s98
	v_mov_b32_e32 v247, 0
	s_add_u32 s24, s24, s98
	v_and_b32_e32 v158, 0xe00, v0
	v_lshlrev_b32_e32 v0, 8, v15
	v_lshl_or_b32 v0, v155, 4, v0
	v_mov_b32_e32 v1, v153
	s_addc_u32 s25, s25, 0
	v_lshlrev_b32_e32 v152, 2, v162
	v_lshl_add_u64 v[168:169], s[24:25], 0, v[0:1]
	v_lshl_add_u64 v[0:1], s[4:5], 0, v[152:153]
	s_mov_b64 s[24:25], 0x1c000000
	v_lshlrev_b32_e32 v2, 1, v154
	v_mov_b32_e32 v3, v153
	v_lshl_add_u64 v[170:171], v[0:1], 0, s[24:25]
	s_add_u32 s24, s4, 0x15800000
	v_lshl_add_u64 v[2:3], s[4:5], 0, v[2:3]
	s_addc_u32 s25, s5, 0
	s_mov_b64 s[4:5], 0x1c400000
	v_lshl_add_u64 v[172:173], v[0:1], 0, s[4:5]
	v_lshlrev_b32_e32 v0, 15, v9
	v_and_b32_e32 v0, 0xffff0000, v0
	v_lshl_add_u32 v0, v10, 12, v0
	v_and_b32_e32 v1, 1, v9
	v_lshl_or_b32 v0, v1, 6, v0
	v_lshl_add_u32 v174, v11, 1, v0
	v_lshlrev_b32_e32 v0, 15, v12
	v_and_b32_e32 v0, 0xffff0000, v0
	s_waitcnt vmcnt(6)
	v_lshl_add_u32 v0, v13, 12, v0
	v_and_b32_e32 v1, 1, v12
	s_mov_b64 s[26:27], 0x1b00000
	v_lshl_or_b32 v0, v1, 6, v0
	s_add_i32 s85, 0, 0x10000
	s_add_i32 s86, 0, 0x14000
	v_and_b32_e32 v156, 3, v8
	v_mov_b32_e32 v157, v153
	v_mov_b32_e32 v159, v153
	v_and_b32_e32 v160, 64, v18
	v_mov_b32_e32 v161, v153
	v_and_b32_e32 v188, 8, v16
	s_mov_b32 s21, s9
	s_mov_b32 s23, s9
	v_lshl_add_u64 v[164:165], v[2:3], 0, s[26:27]
	v_mov_b32_e32 v175, v153
	v_lshl_add_u32 v176, v14, 1, v0
	v_mov_b32_e32 v177, v153
	v_mov_b64_e32 v[178:179], 0x500
	s_movk_i32 s84, 0xa1
	v_add_u32_e32 v190, s85, v163
	v_add_u32_e32 v191, 0, v20
	s_movk_i32 s87, 0xd000
	s_mov_b32 s88, 0xfc000
	s_mov_b32 s89, 0x11c000
	s_mov_b32 s90, 0x13c000
	s_mov_b32 s91, 0x15c000
	s_mov_b32 s92, 0x800000
	s_mov_b32 s93, 0x200000
	s_movk_i32 s94, 0x1800
	s_movk_i32 s95, 0xf0
	v_mov_b64_e32 v[180:181], 0x4ff
	v_add_u32_e32 v192, s86, v163
	s_mov_b32 s96, 0
	s_barrier
	s_branch .LBB0_454

;     __device__ __forceinline__ void operator()(const pg8::Acc& acc, const pg8::Unit& u, int wr, int wc, int fr, int fq) const {
;     ...
;                         } else if (tile >= 16) {
;                             const int hd = 2 * (tile - 16) + head, sh = 2 * (hd >> 2), tp = ((row & ((1 << sh) - 1)) << (14 - sh)) + (row >> sh);
;                             unsigned char* kb = (unsigned char*)kbf + ((size_t)hd * 1024 + (tp >> 4)) * 2048 + (size_t)(d >> 5) * 512 + (size_t)(((d >> 3) & 3) * 16 + (tp & 15)) * 8;
;                             *(u32x2*)kb = pack8_fp8(o1[0], o1[1]); *(u32x2*)(kb + 1024) = pack8_fp8(o2[0], o2[1]);
.LBB0_493:
	s_andn2_b64 vcc, exec, s[58:59]
	s_cbranch_vccnz .LBB0_495
	v_lshlrev_b32_e32 v120, s97, v182
	v_and_b32_e32 v120, 0x3fff, v120
	v_ashrrev_i32_e32 v121, s66, v182
	v_add_u32_e32 v122, v120, v121
	v_ashrrev_i32_e32 v120, 4, v122
	v_lshlrev_b32_e32 v130, 4, v122
	v_mov_b32_e32 v122, v153
	v_mov_b32_e32 v123, v153
	v_cvt_pk_fp8_f32 v122, v186, v187
	v_cvt_pk_fp8_f32 v123, v126, v127
	v_mov_b32_e32 v128, v153
	v_mov_b32_e32 v129, v153
	v_cvt_pk_fp8_f32 v128, v116, v117
	v_cvt_pk_fp8_f32 v129, v112, v113
	v_ashrrev_i32_e32 v121, 31, v120
	s_add_u32 s42, s76, s56
	v_lshlrev_b64 v[120:121], 11, v[120:121]
	s_addc_u32 s43, s77, s57
	v_cvt_pk_fp8_f32 v122, v184, v185 op_sel:[0,0,1]
	v_cvt_pk_fp8_f32 v123, v124, v125 op_sel:[0,0,1]
	v_lshl_add_u64 v[120:121], s[42:43], 0, v[120:121]
	v_cvt_pk_fp8_f32 v128, v118, v119 op_sel:[0,0,1]
	v_cvt_pk_fp8_f32 v129, v114, v115 op_sel:[0,0,1]
	v_lshl_add_u64 v[120:121], v[120:121], 0, v[246:247]
	v_and_or_b32 v152, v130, s95, v189
	v_lshl_add_u64 v[120:121], v[120:121], 0, v[152:153]
	global_store_dwordx2 v[120:121], v[122:123], off
	global_store_dwordx2 v[120:121], v[128:129], off offset:1024

;     __device__ __forceinline__ void operator()(const pg8::Acc& acc, const pg8::Unit& u, int wr, int wc, int fr, int fq) const {
;     ...
;                         } else if (tile >= 16) {
;                             const int hd = 2 * (tile - 16) + head, sh = 2 * (hd >> 2), tp = ((row & ((1 << sh) - 1)) << (14 - sh)) + (row >> sh);
;                             unsigned char* kb = (unsigned char*)kbf + ((size_t)hd * 1024 + (tp >> 4)) * 2048 + (size_t)(d >> 5) * 512 + (size_t)(((d >> 3) & 3) * 16 + (tp & 15)) * 8;
;                             *(u32x2*)kb = pack8_fp8(o1[0], o1[1]); *(u32x2*)(kb + 1024) = pack8_fp8(o2[0], o2[1]);
.LBB0_505:
	s_andn2_b64 vcc, exec, s[58:59]
	s_cbranch_vccnz .LBB0_507
	v_lshlrev_b32_e32 v104, s97, v130
	v_and_b32_e32 v104, 0x3fff, v104
	v_ashrrev_i32_e32 v105, s66, v130
	v_add_u32_e32 v106, v104, v105
	v_ashrrev_i32_e32 v104, 4, v106
	v_lshlrev_b32_e32 v114, 4, v106
	v_mov_b32_e32 v106, v153
	v_mov_b32_e32 v107, v153
	v_cvt_pk_fp8_f32 v106, v134, v135
	v_cvt_pk_fp8_f32 v107, v110, v111
	v_mov_b32_e32 v112, v153
	v_mov_b32_e32 v113, v153
	v_cvt_pk_fp8_f32 v112, v100, v101
	v_cvt_pk_fp8_f32 v113, v96, v97
	v_ashrrev_i32_e32 v105, 31, v104
	s_add_u32 s42, s76, s56
	v_lshlrev_b64 v[104:105], 11, v[104:105]
	s_addc_u32 s43, s77, s57
	v_cvt_pk_fp8_f32 v106, v132, v133 op_sel:[0,0,1]
	v_cvt_pk_fp8_f32 v107, v108, v109 op_sel:[0,0,1]
	v_lshl_add_u64 v[104:105], s[42:43], 0, v[104:105]
	v_cvt_pk_fp8_f32 v112, v102, v103 op_sel:[0,0,1]
	v_cvt_pk_fp8_f32 v113, v98, v99 op_sel:[0,0,1]
	v_lshl_add_u64 v[104:105], v[104:105], 0, v[246:247]
	v_and_or_b32 v152, v114, s95, v189
	v_lshl_add_u64 v[104:105], v[104:105], 0, v[152:153]
	global_store_dwordx2 v[104:105], v[106:107], off
	global_store_dwordx2 v[104:105], v[112:113], off offset:1024

;     __device__ __forceinline__ void operator()(const pg8::Acc& acc, const pg8::Unit& u, int wr, int wc, int fr, int fq) const {
;     ...
;                         } else if (tile >= 16) {
;                             const int hd = 2 * (tile - 16) + head, sh = 2 * (hd >> 2), tp = ((row & ((1 << sh) - 1)) << (14 - sh)) + (row >> sh);
;                             unsigned char* kb = (unsigned char*)kbf + ((size_t)hd * 1024 + (tp >> 4)) * 2048 + (size_t)(d >> 5) * 512 + (size_t)(((d >> 3) & 3) * 16 + (tp & 15)) * 8;
;                             *(u32x2*)kb = pack8_fp8(o1[0], o1[1]); *(u32x2*)(kb + 1024) = pack8_fp8(o2[0], o2[1]);
.LBB0_517:
	s_andn2_b64 vcc, exec, s[58:59]
	s_cbranch_vccnz .LBB0_519
	v_lshlrev_b32_e32 v88, s97, v112
	v_and_b32_e32 v88, 0x3fff, v88
	v_ashrrev_i32_e32 v89, s66, v112
	v_add_u32_e32 v90, v88, v89
	v_ashrrev_i32_e32 v88, 4, v90
	v_lshlrev_b32_e32 v98, 4, v90
	v_mov_b32_e32 v90, v153
	v_mov_b32_e32 v91, v153
	v_cvt_pk_fp8_f32 v90, v116, v117
	v_cvt_pk_fp8_f32 v91, v94, v95
	v_mov_b32_e32 v96, v153
	v_mov_b32_e32 v97, v153
	v_cvt_pk_fp8_f32 v96, v84, v85
	v_cvt_pk_fp8_f32 v97, v80, v81
	v_ashrrev_i32_e32 v89, 31, v88
	s_add_u32 s42, s76, s56
	v_lshlrev_b64 v[88:89], 11, v[88:89]
	s_addc_u32 s43, s77, s57
	v_cvt_pk_fp8_f32 v90, v114, v115 op_sel:[0,0,1]
	v_cvt_pk_fp8_f32 v91, v92, v93 op_sel:[0,0,1]
	v_lshl_add_u64 v[88:89], s[42:43], 0, v[88:89]
	v_cvt_pk_fp8_f32 v96, v86, v87 op_sel:[0,0,1]
	v_cvt_pk_fp8_f32 v97, v82, v83 op_sel:[0,0,1]
	v_lshl_add_u64 v[88:89], v[88:89], 0, v[246:247]
	v_and_or_b32 v152, v98, s95, v189
	v_lshl_add_u64 v[88:89], v[88:89], 0, v[152:153]
	global_store_dwordx2 v[88:89], v[90:91], off
	global_store_dwordx2 v[88:89], v[96:97], off offset:1024

;     __device__ __forceinline__ void operator()(const pg8::Acc& acc, const pg8::Unit& u, int wr, int wc, int fr, int fq) const {
;     ...
;                         } else if (tile >= 16) {
;                             const int hd = 2 * (tile - 16) + head, sh = 2 * (hd >> 2), tp = ((row & ((1 << sh) - 1)) << (14 - sh)) + (row >> sh);
;                             unsigned char* kb = (unsigned char*)kbf + ((size_t)hd * 1024 + (tp >> 4)) * 2048 + (size_t)(d >> 5) * 512 + (size_t)(((d >> 3) & 3) * 16 + (tp & 15)) * 8;
;                             *(u32x2*)kb = pack8_fp8(o1[0], o1[1]); *(u32x2*)(kb + 1024) = pack8_fp8(o2[0], o2[1]);
.LBB0_529:
	s_andn2_b64 vcc, exec, s[58:59]
	s_cbranch_vccnz .LBB0_531
	v_lshlrev_b32_e32 v72, s97, v96
	v_and_b32_e32 v72, 0x3fff, v72
	v_ashrrev_i32_e32 v73, s66, v96
	v_add_u32_e32 v74, v72, v73
	v_ashrrev_i32_e32 v72, 4, v74
	v_lshlrev_b32_e32 v82, 4, v74
	v_mov_b32_e32 v74, v153
	v_mov_b32_e32 v75, v153
	v_cvt_pk_fp8_f32 v74, v100, v101
	v_cvt_pk_fp8_f32 v75, v78, v79
	v_mov_b32_e32 v80, v153
	v_mov_b32_e32 v81, v153
	v_cvt_pk_fp8_f32 v80, v68, v69
	v_cvt_pk_fp8_f32 v81, v64, v65
	v_ashrrev_i32_e32 v73, 31, v72
	s_add_u32 s42, s76, s56
	v_lshlrev_b64 v[72:73], 11, v[72:73]
	s_addc_u32 s43, s77, s57
	v_cvt_pk_fp8_f32 v74, v98, v99 op_sel:[0,0,1]
	v_cvt_pk_fp8_f32 v75, v76, v77 op_sel:[0,0,1]
	v_lshl_add_u64 v[72:73], s[42:43], 0, v[72:73]
	v_cvt_pk_fp8_f32 v80, v70, v71 op_sel:[0,0,1]
	v_cvt_pk_fp8_f32 v81, v66, v67 op_sel:[0,0,1]
	v_lshl_add_u64 v[72:73], v[72:73], 0, v[246:247]
	v_and_or_b32 v152, v82, s95, v189
	v_lshl_add_u64 v[72:73], v[72:73], 0, v[152:153]
	global_store_dwordx2 v[72:73], v[74:75], off
	global_store_dwordx2 v[72:73], v[80:81], off offset:1024

;     __device__ __forceinline__ void operator()(const pg8::Acc& acc, const pg8::Unit& u, int wr, int wc, int fr, int fq) const {
;     ...
;                         } else if (tile >= 16) {
;                             const int hd = 2 * (tile - 16) + head, sh = 2 * (hd >> 2), tp = ((row & ((1 << sh) - 1)) << (14 - sh)) + (row >> sh);
;                             unsigned char* kb = (unsigned char*)kbf + ((size_t)hd * 1024 + (tp >> 4)) * 2048 + (size_t)(d >> 5) * 512 + (size_t)(((d >> 3) & 3) * 16 + (tp & 15)) * 8;
;                             *(u32x2*)kb = pack8_fp8(o1[0], o1[1]); *(u32x2*)(kb + 1024) = pack8_fp8(o2[0], o2[1]);
.LBB0_541:
	s_andn2_b64 vcc, exec, s[58:59]
	s_cbranch_vccnz .LBB0_543
	v_lshlrev_b32_e32 v56, s97, v80
	v_and_b32_e32 v56, 0x3fff, v56
	v_ashrrev_i32_e32 v57, s66, v80
	v_add_u32_e32 v58, v56, v57
	v_ashrrev_i32_e32 v56, 4, v58
	v_lshlrev_b32_e32 v66, 4, v58
	v_mov_b32_e32 v58, v153
	v_mov_b32_e32 v59, v153
	v_cvt_pk_fp8_f32 v58, v84, v85
	v_cvt_pk_fp8_f32 v59, v62, v63
	v_mov_b32_e32 v64, v153
	v_mov_b32_e32 v65, v153
	v_cvt_pk_fp8_f32 v64, v52, v53
	v_cvt_pk_fp8_f32 v65, v48, v49
	v_ashrrev_i32_e32 v57, 31, v56
	s_add_u32 s42, s76, s56
	v_lshlrev_b64 v[56:57], 11, v[56:57]
	s_addc_u32 s43, s77, s57
	v_cvt_pk_fp8_f32 v58, v82, v83 op_sel:[0,0,1]
	v_cvt_pk_fp8_f32 v59, v60, v61 op_sel:[0,0,1]
	v_lshl_add_u64 v[56:57], s[42:43], 0, v[56:57]
	v_cvt_pk_fp8_f32 v64, v54, v55 op_sel:[0,0,1]
	v_cvt_pk_fp8_f32 v65, v50, v51 op_sel:[0,0,1]
	v_lshl_add_u64 v[56:57], v[56:57], 0, v[246:247]
	v_and_or_b32 v152, v66, s95, v189
	v_lshl_add_u64 v[56:57], v[56:57], 0, v[152:153]
	global_store_dwordx2 v[56:57], v[58:59], off
	global_store_dwordx2 v[56:57], v[64:65], off offset:1024

;     __device__ __forceinline__ void operator()(const pg8::Acc& acc, const pg8::Unit& u, int wr, int wc, int fr, int fq) const {
;     ...
;                         } else if (tile >= 16) {
;                             const int hd = 2 * (tile - 16) + head, sh = 2 * (hd >> 2), tp = ((row & ((1 << sh) - 1)) << (14 - sh)) + (row >> sh);
;                             unsigned char* kb = (unsigned char*)kbf + ((size_t)hd * 1024 + (tp >> 4)) * 2048 + (size_t)(d >> 5) * 512 + (size_t)(((d >> 3) & 3) * 16 + (tp & 15)) * 8;
;                             *(u32x2*)kb = pack8_fp8(o1[0], o1[1]); *(u32x2*)(kb + 1024) = pack8_fp8(o2[0], o2[1]);
.LBB0_553:
	s_andn2_b64 vcc, exec, s[58:59]
	s_cbranch_vccnz .LBB0_555
	v_lshlrev_b32_e32 v40, s97, v64
	v_and_b32_e32 v40, 0x3fff, v40
	v_ashrrev_i32_e32 v41, s66, v64
	v_add_u32_e32 v42, v40, v41
	v_ashrrev_i32_e32 v40, 4, v42
	v_lshlrev_b32_e32 v50, 4, v42
	v_mov_b32_e32 v42, v153
	v_mov_b32_e32 v43, v153
	v_cvt_pk_fp8_f32 v42, v68, v69
	v_cvt_pk_fp8_f32 v43, v46, v47
	v_mov_b32_e32 v48, v153
	v_mov_b32_e32 v49, v153
	v_cvt_pk_fp8_f32 v48, v36, v37
	v_cvt_pk_fp8_f32 v49, v32, v33
	v_ashrrev_i32_e32 v41, 31, v40
	s_add_u32 s42, s76, s56
	v_lshlrev_b64 v[40:41], 11, v[40:41]
	s_addc_u32 s43, s77, s57
	v_cvt_pk_fp8_f32 v42, v66, v67 op_sel:[0,0,1]
	v_cvt_pk_fp8_f32 v43, v44, v45 op_sel:[0,0,1]
	v_lshl_add_u64 v[40:41], s[42:43], 0, v[40:41]
	v_cvt_pk_fp8_f32 v48, v38, v39 op_sel:[0,0,1]
	v_cvt_pk_fp8_f32 v49, v34, v35 op_sel:[0,0,1]
	v_lshl_add_u64 v[40:41], v[40:41], 0, v[246:247]
	v_and_or_b32 v152, v50, s95, v189
	v_lshl_add_u64 v[40:41], v[40:41], 0, v[152:153]
	global_store_dwordx2 v[40:41], v[42:43], off
	global_store_dwordx2 v[40:41], v[48:49], off offset:1024

;     __device__ __forceinline__ void operator()(const pg8::Acc& acc, const pg8::Unit& u, int wr, int wc, int fr, int fq) const {
;     ...
;                         } else if (tile >= 16) {
;                             const int hd = 2 * (tile - 16) + head, sh = 2 * (hd >> 2), tp = ((row & ((1 << sh) - 1)) << (14 - sh)) + (row >> sh);
;                             unsigned char* kb = (unsigned char*)kbf + ((size_t)hd * 1024 + (tp >> 4)) * 2048 + (size_t)(d >> 5) * 512 + (size_t)(((d >> 3) & 3) * 16 + (tp & 15)) * 8;
;                             *(u32x2*)kb = pack8_fp8(o1[0], o1[1]); *(u32x2*)(kb + 1024) = pack8_fp8(o2[0], o2[1]);
.LBB0_565:
	s_andn2_b64 vcc, exec, s[58:59]
	s_cbranch_vccnz .LBB0_567
	v_lshlrev_b32_e32 v24, s97, v48
	v_and_b32_e32 v24, 0x3fff, v24
	v_ashrrev_i32_e32 v25, s66, v48
	v_add_u32_e32 v26, v24, v25
	v_ashrrev_i32_e32 v24, 4, v26
	v_lshlrev_b32_e32 v34, 4, v26
	v_mov_b32_e32 v26, v153
	v_mov_b32_e32 v27, v153
	v_cvt_pk_fp8_f32 v26, v52, v53
	v_cvt_pk_fp8_f32 v27, v30, v31
	v_mov_b32_e32 v32, v153
	v_mov_b32_e32 v33, v153
	v_cvt_pk_fp8_f32 v32, v20, v21
	v_cvt_pk_fp8_f32 v33, v16, v17
	v_ashrrev_i32_e32 v25, 31, v24
	s_add_u32 s42, s76, s56
	v_lshlrev_b64 v[24:25], 11, v[24:25]
	s_addc_u32 s43, s77, s57
	v_cvt_pk_fp8_f32 v26, v50, v51 op_sel:[0,0,1]
	v_cvt_pk_fp8_f32 v27, v28, v29 op_sel:[0,0,1]
	v_lshl_add_u64 v[24:25], s[42:43], 0, v[24:25]
	v_cvt_pk_fp8_f32 v32, v22, v23 op_sel:[0,0,1]
	v_cvt_pk_fp8_f32 v33, v18, v19 op_sel:[0,0,1]
	v_lshl_add_u64 v[24:25], v[24:25], 0, v[246:247]
	v_and_or_b32 v152, v34, s95, v189
	v_lshl_add_u64 v[24:25], v[24:25], 0, v[152:153]
	global_store_dwordx2 v[24:25], v[26:27], off
	global_store_dwordx2 v[24:25], v[32:33], off offset:1024

;     __device__ __forceinline__ void operator()(const pg8::Acc& acc, const pg8::Unit& u, int wr, int wc, int fr, int fq) const {
;     ...
;                         } else if (tile >= 16) {
;                             const int hd = 2 * (tile - 16) + head, sh = 2 * (hd >> 2), tp = ((row & ((1 << sh) - 1)) << (14 - sh)) + (row >> sh);
;                             unsigned char* kb = (unsigned char*)kbf + ((size_t)hd * 1024 + (tp >> 4)) * 2048 + (size_t)(d >> 5) * 512 + (size_t)(((d >> 3) & 3) * 16 + (tp & 15)) * 8;
;                             *(u32x2*)kb = pack8_fp8(o1[0], o1[1]); *(u32x2*)(kb + 1024) = pack8_fp8(o2[0], o2[1]);
.LBB0_577:
	s_andn2_b64 vcc, exec, s[6:7]
	s_cbranch_vccnz .LBB0_579
	v_lshlrev_b32_e32 v8, s97, v32
	v_and_b32_e32 v8, 0x3fff, v8
	v_ashrrev_i32_e32 v9, s66, v32
	v_add_u32_e32 v10, v8, v9
	v_ashrrev_i32_e32 v8, 4, v10
	v_lshlrev_b32_e32 v18, 4, v10
	v_mov_b32_e32 v10, v153
	v_mov_b32_e32 v11, v153
	v_cvt_pk_fp8_f32 v10, v36, v37
	v_cvt_pk_fp8_f32 v11, v14, v15
	v_mov_b32_e32 v16, v153
	v_mov_b32_e32 v17, v153
	v_cvt_pk_fp8_f32 v16, v4, v5
	v_cvt_pk_fp8_f32 v17, v0, v1
	v_ashrrev_i32_e32 v9, 31, v8
	s_add_u32 s6, s76, s56
	v_lshlrev_b64 v[8:9], 11, v[8:9]
	s_addc_u32 s7, s77, s57
	v_cvt_pk_fp8_f32 v10, v34, v35 op_sel:[0,0,1]
	v_cvt_pk_fp8_f32 v11, v12, v13 op_sel:[0,0,1]
	v_lshl_add_u64 v[8:9], s[6:7], 0, v[8:9]
	v_cvt_pk_fp8_f32 v16, v6, v7 op_sel:[0,0,1]
	v_cvt_pk_fp8_f32 v17, v2, v3 op_sel:[0,0,1]
	v_lshl_add_u64 v[8:9], v[8:9], 0, v[246:247]
	v_and_or_b32 v152, v18, s95, v189
	v_lshl_add_u64 v[8:9], v[8:9], 0, v[152:153]
	global_store_dwordx2 v[8:9], v[10:11], off
	global_store_dwordx2 v[8:9], v[16:17], off offset:1024

; #define PG8_STAGE(bufoff, gbase, voff) do { _Pragma("unroll") for (int _i = 0; _i < 2; ++_i) \
;         __builtin_amdgcn_global_load_lds((const unsigned*)((const char*)(gbase) + (voff)[_i]), (LAS unsigned*)(lds + (bufoff) + ldsw + _i * 8192), 16, 0, 0); } while (0)
; #define PG8_WAIT_V(n) asm volatile("s_waitcnt vmcnt(" #n ")" ::: "memory")
; #define PG8_BAR __builtin_amdgcn_s_barrier()
; template <class Epi, bool FP8 = false>
; __device__ __forceinline__ void gemm_phase(LAS unsigned char* lds, const Gemm g, const StaticOrder& S_, const Epi& E, const int tid) {
;     const int wid = __builtin_amdgcn_readfirstlane(tid >> 6), lane = tid & 63, wr = wid >> 2, wc = wid & 3, fr = lane & 15, fq = lane >> 4;
;     const int K = g.K, nt = K / BK;
;     unsigned voffA[2], voffB[2];
; #pragma unroll
;     for (int i = 0; i < 2; ++i) { int R, C; stage_rc(tid * 16 + i * 8192, R, C); const int Rb = Epi::PERM ? ((R & ~31) + perm32(R & 31)) : R;
;         voffA[i] = (unsigned)(R * g.lda + C) * 2u; voffB[i] = (unsigned)(Rb * g.ldb + C) * 2u; }
;     const size_t kstep = (size_t)(BK * 2);
;     const size_t hstepA = (size_t)HALF * g.lda * 2, hstepB = (size_t)HALF * g.ldb * 2;
;     const size_t tstepA = 2 * hstepA, tstepB = 2 * hstepB;
;     const unsigned ldsw = (unsigned)wid * 1024u;
;     const int aoff = lds_byte(wr * 64 + fr, fq * 8), boff = lds_byte(wc * 32 + fr, fq * 8);
;     ...
;     Unit cur, nxt; int ui = 0;
;     if (!S_.next(0, cur)) return;
;     Acc acc;
; #pragma unroll
;     for (int a = 0; a < 2; ++a)
; #pragma unroll
;         for (int b = 0; b < 2; ++b)
; #pragma unroll
;             for (int m = 0; m < 4; ++m)
; #pragma unroll
;                 for (int n = 0; n < 2; ++n) acc[a][b][m][n] = (f32x4){0.f, 0.f, 0.f, 0.f};
;     bf16x8 At[4][2], B0[2][2], B1[2][2];
;     const char* cA = (const char*)g.A + (size_t)cur.pm * tstepA; const char* cB = (const char*)g.Bt + (size_t)cur.pn * tstepB;
;     PG8_STAGE(PG8_SB(0, 0), cB, voffB); PG8_STAGE(PG8_SB(0, 1), cB + hstepB, voffB); PG8_STAGE(PG8_SA(0, 0), cA, voffA); PG8_STAGE(PG8_SA(0, 1), cA + hstepA, voffA);
;     if (wr == 1) PG8_BAR;
;     PG8_WAIT_V(2); PG8_BAR;
;     PG8_STAGE(PG8_SB(1, 0), cB + kstep, voffB); PG8_STAGE(PG8_SA(1, 0), cA + kstep, voffA); PG8_STAGE(PG8_SB(1, 1), cB + hstepB + kstep, voffB);
;     PG8_WAIT_V(6); PG8_BAR;
.LBB0_590:
	s_lshl_b32 s10, s10, 5
	s_lshl_b32 s71, s11, 6
	s_lshl_b32 s16, s11, 13
	s_and_b32 s17, s10, 0x60
	s_mov_b64 s[10:11], 0x80
	s_add_i32 m0, s63, 0x18000
	v_lshl_add_u64 v[6:7], v[6:7], 0, s[10:11]
	s_lshl_b32 s18, s17, 7
	s_waitcnt vmcnt(2)
	s_barrier
	global_load_lds_dwordx4 v[6:7], off
	v_lshl_add_u64 v[4:5], v[4:5], 0, s[10:11]
	s_add_i32 m0, s63, 0x1a000
	s_add_i32 s72, s63, 0x8000
	s_add_i32 s73, s63, 0xa000
	global_load_lds_dwordx4 v[4:5], off
	v_lshl_add_u64 v[0:1], v[0:1], 0, s[10:11]
	s_mov_b32 m0, s72
	s_add_u32 s14, s54, 0x40080
	global_load_lds_dwordx4 v[0:1], off
	v_lshl_add_u64 v[0:1], v[2:3], 0, s[10:11]
	s_mov_b32 m0, s73
	s_addc_u32 s15, s55, 0
	global_load_lds_dwordx4 v[0:1], off
	s_add_i32 m0, s63, 0x1c000
	v_lshl_add_u64 v[0:1], s[14:15], 0, v[160:161]
	global_load_lds_dwordx4 v[0:1], off
	v_lshl_add_u64 v[0:1], s[14:15], 0, v[162:163]
	s_add_i32 m0, s63, 0x1e000
	v_and_b32_e32 v194, 15, v9
	global_load_lds_dwordx4 v[0:1], off
	v_bfe_u32 v0, v9, 4, 2
	v_lshlrev_b32_e32 v1, 3, v0
	v_lshlrev_b32_e32 v0, 4, v0
	v_lshlrev_b32_e32 v2, 2, v9
	v_lshl_or_b32 v0, v194, 6, v0
	v_and_b32_e32 v3, 32, v2
	v_bitop3_b32 v4, v0, s16, v3 bitop3:0xde
	v_bitop3_b32 v195, s18, v0, v3 bitop3:0xf6
	v_or_b32_e32 v0, s17, v1
	v_and_b32_e32 v196, 8, v1
	v_lshlrev_b32_e32 v1, 5, v0
	v_and_b32_e32 v170, 0xe00, v1
	v_lshlrev_b32_e32 v1, 5, v9
	v_mov_b32_e32 v169, 0
	v_and_b32_e32 v168, 0x180, v1
	v_lshlrev_b32_e32 v1, 14, v13
	v_and_b32_e32 v174, 64, v2
	v_and_b32_e32 v242, 0xc00, v170
	v_lshrrev_b32_e32 v243, 6, v170
	v_and_b32_e32 v243, 8, v243
	v_or_b32_e32 v242, v242, v243
	v_add_u32_e32 v242, v242, v168
	v_mov_b32_e32 v243, 0
	v_lshlrev_b32_e32 v244, 1, v174
	v_mov_b32_e32 v245, 0
	v_and_b32_e32 v246, 0xc00, v170
	v_lshrrev_b32_e32 v247, 6, v170
	v_and_b32_e32 v247, 8, v247
	v_or_b32_e32 v246, v246, v247
	v_mov_b32_e32 v247, 0
	v_lshl_add_u64 v[2:3], s[4:5], 0, v[168:169]
	s_mov_b64 s[14:15], 0x1a000000
	v_and_b32_e32 v1, 0xffff8000, v1
	v_lshl_add_u64 v[176:177], v[2:3], 0, s[14:15]
	v_lshl_add_u32 v1, v12, 11, v1
	v_and_b32_e32 v2, 1, v13
	v_lshl_or_b32 v1, v2, 6, v1
	v_lshl_add_u32 v178, v14, 1, v1
	v_lshlrev_b32_e32 v1, 14, v8
	s_cmpk_lt_u32 s13, 0x100
	v_and_b32_e32 v1, 0xffff8000, v1
	s_sext_i32_i16 s83, s12
	s_waitcnt vmcnt(6)
	s_cselect_b64 s[12:13], -1, 0
	s_add_u32 s14, s4, 0x15800000
	v_lshl_add_u32 v1, v10, 11, v1
	v_and_b32_e32 v2, 1, v8
	s_addc_u32 s15, s5, 0
	v_lshl_or_b32 v1, v2, 6, v1
	s_add_i32 s74, 0, 0x10000
	s_add_i32 s75, 0, 0x14000
	v_mov_b32_e32 v171, v169
	v_and_b32_e32 v172, 3, v9
	v_mov_b32_e32 v173, v169
	v_mov_b32_e32 v175, v169
	v_mov_b32_e32 v179, v169
	v_lshl_add_u32 v180, v11, 1, v1
	v_mov_b32_e32 v181, v169
	v_mov_b64_e32 v[182:183], 0x600
	v_mov_b64_e32 v[184:185], 0x5ff
	v_add_u32_e32 v197, s74, v195
	v_add_u32_e32 v198, s75, v195
	v_add_u32_e32 v199, 0, v4
	v_lshlrev_b32_e32 v168, 1, v0
	s_mov_b64 s[16:17], 0x100000
	s_mov_b32 s76, 0x100000
	s_mov_b64 s[18:19], 0x120000
	s_mov_b32 s77, 0x120000
	s_mov_b64 s[20:21], 0x140000
	s_mov_b32 s78, 0x140000
	s_mov_b64 s[22:23], 0x160000
	s_mov_b32 s79, 0x160000
	s_mov_b32 s80, 0x800000
	s_mov_b32 s81, 0x200000
	s_mov_b32 s82, 0
	s_barrier
	s_branch .LBB0_593

;     __device__ __forceinline__ void operator()(const pg8::Acc& acc, const pg8::Unit& u, int wr, int wc, int fr, int fq) const {
;     ...
;         } else if (pn < 8) {
;             unsigned char* VB = (unsigned char*)kbf + ((size_t)24 << 20);
; #pragma unroll
;             for (int ai = 0; ai < 2; ++ai)
; #pragma unroll
;                 for (int m = 0; m < 4; ++m) {
;                     const int row = row0 + ai * 128 + m * 16;
; #pragma unroll
;                     for (int bj = 0; bj < 2; ++bj) {
;                         const int hd = 2 * (pn - 2) + bj, sh = 2 * (hd >> 2), tp = ((row & ((1 << sh) - 1)) << (14 - sh)) + (row >> sh), kp = tp & 31;
;                         const u32x2 w = pack8_fp8(acc[ai][bj][m][0], acc[ai][bj][m][1]);
;                         unsigned char* vb = VB + (((size_t)hd * 512 + (tp >> 5)) * 8 + (cw >> 4)) * 512 + (size_t)(((kp >> 2) & 3) * 16 + (cw & 15)) * 8 + 4 * (kp >> 4) + (kp & 3);
;                         vb[0] = (unsigned char)(w.x & 0xffu); vb[8] = (unsigned char)((w.x >> 8) & 0xffu); vb[16] = (unsigned char)((w.x >> 16) & 0xffu); vb[24] = (unsigned char)(w.x >> 24);
;                         vb[32] = (unsigned char)(w.y & 0xffu); vb[40] = (unsigned char)((w.y >> 8) & 0xffu); vb[48] = (unsigned char)((w.y >> 16) & 0xffu); vb[56] = (unsigned char)(w.y >> 24);
;                     }
;                 }
.LBB0_604:
	s_andn2_b64 vcc, exec, s[52:53]
	s_cbranch_vccnz .LBB0_606
	s_lshl_b32 s43, s83, 1
	s_add_i32 s6, s43, -4
	s_lshr_b32 s27, s6, 1
	s_and_b32 s27, s27, 0x7ffffffe
	s_sub_i32 s42, 14, s27
	v_lshlrev_b32_e32 v129, s42, v128
	v_and_b32_e32 v129, 0x3fff, v129
	v_ashrrev_i32_e32 v130, s27, v128
	v_add_u32_e32 v129, v129, v130
	v_lshlrev_b32_e32 v132, 2, v129
	v_and_or_b32 v132, v132, 48, v196
	v_lshlrev_b32_e32 v132, 4, v132
	v_mov_b32_e32 v133, v169
	v_lshrrev_b32_e32 v134, 2, v129
	v_lshl_add_u64 v[132:133], s[14:15], 0, v[132:133]
	v_and_b32_e32 v134, 4, v134
	v_mov_b32_e32 v135, v169
	v_ashrrev_i32_e32 v130, 5, v129
	v_lshl_add_u64 v[132:133], v[132:133], 0, v[134:135]
	v_and_b32_e32 v134, 3, v129
	v_mov_b32_e32 v129, v169
	v_cvt_pk_fp8_f32 v129, v124, v125
	v_mov_b32_e32 v136, v169
	v_cvt_pk_fp8_f32 v136, v120, v121
	v_ashrrev_i32_e32 v131, 31, v130
	v_cvt_pk_fp8_f32 v129, v126, v127 op_sel:[0,0,1]
	v_lshl_add_u64 v[132:133], v[132:133], 0, v[134:135]
	s_lshl_b64 s[52:53], s[6:7], 21
	v_cvt_pk_fp8_f32 v136, v122, v123 op_sel:[0,0,1]
	v_lshlrev_b64 v[130:131], 12, v[130:131]
	v_lshl_add_u64 v[134:135], v[132:133], 0, s[52:53]
	v_lshl_add_u64 v[134:135], v[134:135], 0, v[130:131]
	v_lshl_add_u64 v[134:135], v[134:135], 0, v[246:247]
	v_lshrrev_b32_e32 v137, 8, v129
	global_store_byte v[134:135], v129, off
	global_store_byte v[134:135], v137, off offset:16
	global_store_byte_d16_hi v[134:135], v129, off offset:32
	v_lshrrev_b32_e32 v129, 24, v129
	global_store_byte v[134:135], v129, off offset:48
	global_store_byte v[134:135], v136, off offset:64
	v_lshrrev_b32_e32 v129, 8, v136
	global_store_byte v[134:135], v129, off offset:80
	global_store_byte_d16_hi v[134:135], v136, off offset:96
	v_lshrrev_b32_e32 v129, 24, v136
	v_mov_b32_e32 v136, v169
	v_cvt_pk_fp8_f32 v136, v116, v117
	v_mov_b32_e32 v137, v169
	v_cvt_pk_fp8_f32 v137, v108, v109
	s_add_i32 s6, s43, -3
	v_cvt_pk_fp8_f32 v136, v118, v119 op_sel:[0,0,1]
	s_lshl_b64 s[54:55], s[6:7], 21
	v_cvt_pk_fp8_f32 v137, v110, v111 op_sel:[0,0,1]
	v_lshl_add_u64 v[132:133], v[132:133], 0, s[54:55]
	v_lshl_add_u64 v[130:131], v[132:133], 0, v[130:131]
	global_store_byte v[134:135], v129, off offset:112
	v_lshl_add_u64 v[130:131], v[130:131], 0, v[246:247]
	v_lshrrev_b32_e32 v129, 8, v136
	global_store_byte v[130:131], v136, off
	global_store_byte v[130:131], v129, off offset:16
	global_store_byte_d16_hi v[130:131], v136, off offset:32
	v_lshrrev_b32_e32 v129, 24, v136
	global_store_byte v[130:131], v129, off offset:48
	global_store_byte v[130:131], v137, off offset:64
	v_lshrrev_b32_e32 v129, 8, v137
	global_store_byte v[130:131], v129, off offset:80
	global_store_byte_d16_hi v[130:131], v137, off offset:96
	v_lshrrev_b32_e32 v129, 24, v137
	global_store_byte v[130:131], v129, off offset:112
	v_or_b32_e32 v129, 16, v128
	v_lshlrev_b32_e32 v130, s42, v129
	v_and_b32_e32 v130, 0x3fff, v130
	v_ashrrev_i32_e32 v129, s27, v129
	v_add_u32_e32 v129, v130, v129
	v_lshlrev_b32_e32 v132, 2, v129
	v_and_or_b32 v132, v132, 48, v196
	v_lshlrev_b32_e32 v132, 4, v132
	v_mov_b32_e32 v133, v169
	v_lshrrev_b32_e32 v134, 2, v129
	v_lshl_add_u64 v[132:133], s[14:15], 0, v[132:133]
	v_and_b32_e32 v134, 4, v134
	v_mov_b32_e32 v135, v169
	v_ashrrev_i32_e32 v130, 5, v129
	v_lshl_add_u64 v[132:133], v[132:133], 0, v[134:135]
	v_and_b32_e32 v134, 3, v129
	v_mov_b32_e32 v129, v169
	v_cvt_pk_fp8_f32 v129, v112, v113
	v_mov_b32_e32 v136, v169
	v_cvt_pk_fp8_f32 v136, v104, v105
	v_ashrrev_i32_e32 v131, 31, v130
	v_cvt_pk_fp8_f32 v129, v114, v115 op_sel:[0,0,1]
	v_lshl_add_u64 v[132:133], v[132:133], 0, v[134:135]
	v_cvt_pk_fp8_f32 v136, v106, v107 op_sel:[0,0,1]
	v_lshlrev_b64 v[130:131], 12, v[130:131]
	v_lshl_add_u64 v[134:135], v[132:133], 0, s[52:53]
	v_lshl_add_u64 v[134:135], v[134:135], 0, v[130:131]
	v_lshl_add_u64 v[134:135], v[134:135], 0, v[246:247]
	v_lshrrev_b32_e32 v137, 8, v129
	global_store_byte v[134:135], v129, off
	global_store_byte v[134:135], v137, off offset:16
	global_store_byte_d16_hi v[134:135], v129, off offset:32
	v_lshrrev_b32_e32 v129, 24, v129
	global_store_byte v[134:135], v129, off offset:48
	global_store_byte v[134:135], v136, off offset:64
	v_lshrrev_b32_e32 v129, 8, v136
	global_store_byte v[134:135], v129, off offset:80
	global_store_byte_d16_hi v[134:135], v136, off offset:96
	v_mov_b32_e32 v129, v169
	v_cvt_pk_fp8_f32 v129, v100, v101
	v_mov_b32_e32 v137, v169
	v_cvt_pk_fp8_f32 v137, v92, v93
	v_lshl_add_u64 v[132:133], v[132:133], 0, s[54:55]
	v_cvt_pk_fp8_f32 v129, v102, v103 op_sel:[0,0,1]
	v_lshl_add_u64 v[130:131], v[132:133], 0, v[130:131]
	v_cvt_pk_fp8_f32 v137, v94, v95 op_sel:[0,0,1]
	v_lshrrev_b32_e32 v136, 24, v136
	v_lshl_add_u64 v[130:131], v[130:131], 0, v[246:247]
	v_lshrrev_b32_e32 v132, 8, v129
	global_store_byte v[134:135], v136, off offset:112
	global_store_byte v[130:131], v129, off
	global_store_byte v[130:131], v132, off offset:16
	global_store_byte_d16_hi v[130:131], v129, off offset:32
	v_lshrrev_b32_e32 v129, 24, v129
	global_store_byte v[130:131], v129, off offset:48
	global_store_byte v[130:131], v137, off offset:64
	v_lshrrev_b32_e32 v129, 8, v137
	global_store_byte v[130:131], v129, off offset:80
	global_store_byte_d16_hi v[130:131], v137, off offset:96
	v_lshrrev_b32_e32 v129, 24, v137
	global_store_byte v[130:131], v129, off offset:112
	v_or_b32_e32 v129, 32, v128
	v_lshlrev_b32_e32 v130, s42, v129
	v_and_b32_e32 v130, 0x3fff, v130
	v_ashrrev_i32_e32 v129, s27, v129
	v_add_u32_e32 v129, v130, v129
	v_lshlrev_b32_e32 v132, 2, v129
	v_and_or_b32 v132, v132, 48, v196
	v_lshlrev_b32_e32 v132, 4, v132
	v_mov_b32_e32 v133, v169
	v_lshrrev_b32_e32 v134, 2, v129
;     __device__ __forceinline__ void operator()(const pg8::Acc& acc, const pg8::Unit& u, int wr, int wc, int fr, int fq) const {
;     ...
;         } else if (pn < 8) {
;             unsigned char* VB = (unsigned char*)kbf + ((size_t)24 << 20);
; #pragma unroll
;             for (int ai = 0; ai < 2; ++ai)
; #pragma unroll
;                 for (int m = 0; m < 4; ++m) {
;                     const int row = row0 + ai * 128 + m * 16;
; #pragma unroll
;                     for (int bj = 0; bj < 2; ++bj) {
;                         const int hd = 2 * (pn - 2) + bj, sh = 2 * (hd >> 2), tp = ((row & ((1 << sh) - 1)) << (14 - sh)) + (row >> sh), kp = tp & 31;
;                         const u32x2 w = pack8_fp8(acc[ai][bj][m][0], acc[ai][bj][m][1]);
;                         unsigned char* vb = VB + (((size_t)hd * 512 + (tp >> 5)) * 8 + (cw >> 4)) * 512 + (size_t)(((kp >> 2) & 3) * 16 + (cw & 15)) * 8 + 4 * (kp >> 4) + (kp & 3);
;                         vb[0] = (unsigned char)(w.x & 0xffu); vb[8] = (unsigned char)((w.x >> 8) & 0xffu); vb[16] = (unsigned char)((w.x >> 16) & 0xffu); vb[24] = (unsigned char)(w.x >> 24);
;                         vb[32] = (unsigned char)(w.y & 0xffu); vb[40] = (unsigned char)((w.y >> 8) & 0xffu); vb[48] = (unsigned char)((w.y >> 16) & 0xffu); vb[56] = (unsigned char)(w.y >> 24);
;                     }
;                 }
	v_lshl_add_u64 v[132:133], s[14:15], 0, v[132:133]
	v_and_b32_e32 v134, 4, v134
	v_mov_b32_e32 v135, v169
	v_ashrrev_i32_e32 v130, 5, v129
	v_lshl_add_u64 v[132:133], v[132:133], 0, v[134:135]
	v_and_b32_e32 v134, 3, v129
	v_mov_b32_e32 v129, v169
	v_cvt_pk_fp8_f32 v129, v96, v97
	v_mov_b32_e32 v136, v169
	v_cvt_pk_fp8_f32 v136, v88, v89
	v_ashrrev_i32_e32 v131, 31, v130
	v_cvt_pk_fp8_f32 v129, v98, v99 op_sel:[0,0,1]
	v_lshl_add_u64 v[132:133], v[132:133], 0, v[134:135]
	v_cvt_pk_fp8_f32 v136, v90, v91 op_sel:[0,0,1]
	v_lshlrev_b64 v[130:131], 12, v[130:131]
	v_lshl_add_u64 v[134:135], v[132:133], 0, s[52:53]
	v_lshl_add_u64 v[134:135], v[134:135], 0, v[130:131]
	v_lshl_add_u64 v[134:135], v[134:135], 0, v[246:247]
	v_lshrrev_b32_e32 v137, 8, v129
	global_store_byte v[134:135], v129, off
	global_store_byte v[134:135], v137, off offset:16
	global_store_byte_d16_hi v[134:135], v129, off offset:32
	v_lshrrev_b32_e32 v129, 24, v129
	global_store_byte v[134:135], v129, off offset:48
	global_store_byte v[134:135], v136, off offset:64
	v_lshrrev_b32_e32 v129, 8, v136
	global_store_byte v[134:135], v129, off offset:80
	global_store_byte_d16_hi v[134:135], v136, off offset:96
	v_mov_b32_e32 v129, v169
	v_cvt_pk_fp8_f32 v129, v80, v81
	v_mov_b32_e32 v137, v169
	v_cvt_pk_fp8_f32 v137, v76, v77
	v_lshl_add_u64 v[132:133], v[132:133], 0, s[54:55]
	v_cvt_pk_fp8_f32 v129, v82, v83 op_sel:[0,0,1]
	v_lshl_add_u64 v[130:131], v[132:133], 0, v[130:131]
	v_cvt_pk_fp8_f32 v137, v78, v79 op_sel:[0,0,1]
	v_lshrrev_b32_e32 v136, 24, v136
	v_lshl_add_u64 v[130:131], v[130:131], 0, v[246:247]
	v_lshrrev_b32_e32 v132, 8, v129
	global_store_byte v[134:135], v136, off offset:112
	global_store_byte v[130:131], v129, off
	global_store_byte v[130:131], v132, off offset:16
	global_store_byte_d16_hi v[130:131], v129, off offset:32
	v_lshrrev_b32_e32 v129, 24, v129
	global_store_byte v[130:131], v129, off offset:48
	global_store_byte v[130:131], v137, off offset:64
	v_lshrrev_b32_e32 v129, 8, v137
	global_store_byte v[130:131], v129, off offset:80
	global_store_byte_d16_hi v[130:131], v137, off offset:96
	v_lshrrev_b32_e32 v129, 24, v137
	global_store_byte v[130:131], v129, off offset:112
	v_or_b32_e32 v129, 48, v128
	v_lshlrev_b32_e32 v130, s42, v129
	v_and_b32_e32 v130, 0x3fff, v130
	v_ashrrev_i32_e32 v129, s27, v129
	v_add_u32_e32 v129, v130, v129
	v_lshlrev_b32_e32 v132, 2, v129
	v_and_or_b32 v132, v132, 48, v196
	v_lshlrev_b32_e32 v132, 4, v132
	v_mov_b32_e32 v133, v169
	v_lshrrev_b32_e32 v134, 2, v129
	v_lshl_add_u64 v[132:133], s[14:15], 0, v[132:133]
	v_and_b32_e32 v134, 4, v134
	v_mov_b32_e32 v135, v169
	v_ashrrev_i32_e32 v130, 5, v129
	v_lshl_add_u64 v[132:133], v[132:133], 0, v[134:135]
	v_and_b32_e32 v134, 3, v129
	v_mov_b32_e32 v129, v169
	v_cvt_pk_fp8_f32 v129, v84, v85
	v_mov_b32_e32 v136, v169
	v_cvt_pk_fp8_f32 v136, v72, v73
	v_ashrrev_i32_e32 v131, 31, v130
	v_cvt_pk_fp8_f32 v129, v86, v87 op_sel:[0,0,1]
	v_lshl_add_u64 v[132:133], v[132:133], 0, v[134:135]
	v_cvt_pk_fp8_f32 v136, v74, v75 op_sel:[0,0,1]
	v_lshlrev_b64 v[130:131], 12, v[130:131]
	v_lshl_add_u64 v[134:135], v[132:133], 0, s[52:53]
	v_lshl_add_u64 v[134:135], v[134:135], 0, v[130:131]
	v_lshl_add_u64 v[134:135], v[134:135], 0, v[246:247]
	v_lshrrev_b32_e32 v137, 8, v129
	global_store_byte v[134:135], v129, off
	global_store_byte v[134:135], v137, off offset:16
	global_store_byte_d16_hi v[134:135], v129, off offset:32
	v_lshrrev_b32_e32 v129, 24, v129
	global_store_byte v[134:135], v129, off offset:48
	global_store_byte v[134:135], v136, off offset:64
	v_lshrrev_b32_e32 v129, 8, v136
	global_store_byte v[134:135], v129, off offset:80
	global_store_byte_d16_hi v[134:135], v136, off offset:96
	v_mov_b32_e32 v129, v169
	v_cvt_pk_fp8_f32 v129, v68, v69
	v_mov_b32_e32 v137, v169
	v_cvt_pk_fp8_f32 v137, v64, v65
	v_lshl_add_u64 v[132:133], v[132:133], 0, s[54:55]
	v_cvt_pk_fp8_f32 v129, v70, v71 op_sel:[0,0,1]
	v_lshl_add_u64 v[130:131], v[132:133], 0, v[130:131]
	v_cvt_pk_fp8_f32 v137, v66, v67 op_sel:[0,0,1]
	v_lshrrev_b32_e32 v136, 24, v136
	v_lshl_add_u64 v[130:131], v[130:131], 0, v[246:247]
	v_lshrrev_b32_e32 v132, 8, v129
	global_store_byte v[134:135], v136, off offset:112
	global_store_byte v[130:131], v129, off
	global_store_byte v[130:131], v132, off offset:16
	global_store_byte_d16_hi v[130:131], v129, off offset:32
	v_lshrrev_b32_e32 v129, 24, v129
	global_store_byte v[130:131], v129, off offset:48
	global_store_byte v[130:131], v137, off offset:64
	v_lshrrev_b32_e32 v129, 8, v137
	global_store_byte v[130:131], v129, off offset:80
	global_store_byte_d16_hi v[130:131], v137, off offset:96
	v_lshrrev_b32_e32 v129, 24, v137
	global_store_byte v[130:131], v129, off offset:112
	v_add_u32_e32 v129, 0x80, v128
	v_lshlrev_b32_e32 v130, s42, v129
	v_and_b32_e32 v130, 0x3fff, v130
	v_ashrrev_i32_e32 v129, s27, v129
	v_add_u32_e32 v129, v130, v129
	v_lshlrev_b32_e32 v132, 2, v129
	v_and_or_b32 v132, v132, 48, v196
	v_lshlrev_b32_e32 v132, 4, v132
	v_mov_b32_e32 v133, v169
	v_lshrrev_b32_e32 v134, 2, v129
	v_lshl_add_u64 v[132:133], s[14:15], 0, v[132:133]
	v_and_b32_e32 v134, 4, v134
	v_mov_b32_e32 v135, v169
	v_ashrrev_i32_e32 v130, 5, v129
	v_lshl_add_u64 v[132:133], v[132:133], 0, v[134:135]
	v_and_b32_e32 v134, 3, v129
	v_mov_b32_e32 v129, v169
	v_cvt_pk_fp8_f32 v129, v60, v61
	v_mov_b32_e32 v136, v169
	v_cvt_pk_fp8_f32 v136, v56, v57
	v_ashrrev_i32_e32 v131, 31, v130
	v_cvt_pk_fp8_f32 v129, v62, v63 op_sel:[0,0,1]
	v_lshl_add_u64 v[132:133], v[132:133], 0, v[134:135]
	v_cvt_pk_fp8_f32 v136, v58, v59 op_sel:[0,0,1]
	v_lshlrev_b64 v[130:131], 12, v[130:131]
	v_lshl_add_u64 v[134:135], v[132:133], 0, s[52:53]
;     __device__ __forceinline__ void operator()(const pg8::Acc& acc, const pg8::Unit& u, int wr, int wc, int fr, int fq) const {
;     ...
;         } else if (pn < 8) {
;             unsigned char* VB = (unsigned char*)kbf + ((size_t)24 << 20);
; #pragma unroll
;             for (int ai = 0; ai < 2; ++ai)
; #pragma unroll
;                 for (int m = 0; m < 4; ++m) {
;                     const int row = row0 + ai * 128 + m * 16;
; #pragma unroll
;                     for (int bj = 0; bj < 2; ++bj) {
;                         const int hd = 2 * (pn - 2) + bj, sh = 2 * (hd >> 2), tp = ((row & ((1 << sh) - 1)) << (14 - sh)) + (row >> sh), kp = tp & 31;
;                         const u32x2 w = pack8_fp8(acc[ai][bj][m][0], acc[ai][bj][m][1]);
;                         unsigned char* vb = VB + (((size_t)hd * 512 + (tp >> 5)) * 8 + (cw >> 4)) * 512 + (size_t)(((kp >> 2) & 3) * 16 + (cw & 15)) * 8 + 4 * (kp >> 4) + (kp & 3);
;                         vb[0] = (unsigned char)(w.x & 0xffu); vb[8] = (unsigned char)((w.x >> 8) & 0xffu); vb[16] = (unsigned char)((w.x >> 16) & 0xffu); vb[24] = (unsigned char)(w.x >> 24);
;                         vb[32] = (unsigned char)(w.y & 0xffu); vb[40] = (unsigned char)((w.y >> 8) & 0xffu); vb[48] = (unsigned char)((w.y >> 16) & 0xffu); vb[56] = (unsigned char)(w.y >> 24);
;                     }
;                 }
	v_lshl_add_u64 v[134:135], v[134:135], 0, v[130:131]
	v_lshl_add_u64 v[134:135], v[134:135], 0, v[246:247]
	v_lshrrev_b32_e32 v137, 8, v129
	global_store_byte v[134:135], v129, off
	global_store_byte v[134:135], v137, off offset:16
	global_store_byte_d16_hi v[134:135], v129, off offset:32
	v_lshrrev_b32_e32 v129, 24, v129
	global_store_byte v[134:135], v129, off offset:48
	global_store_byte v[134:135], v136, off offset:64
	v_lshrrev_b32_e32 v129, 8, v136
	global_store_byte v[134:135], v129, off offset:80
	global_store_byte_d16_hi v[134:135], v136, off offset:96
	v_mov_b32_e32 v129, v169
	v_cvt_pk_fp8_f32 v129, v52, v53
	v_mov_b32_e32 v137, v169
	v_cvt_pk_fp8_f32 v137, v44, v45
	v_lshl_add_u64 v[132:133], v[132:133], 0, s[54:55]
	v_cvt_pk_fp8_f32 v129, v54, v55 op_sel:[0,0,1]
	v_lshl_add_u64 v[130:131], v[132:133], 0, v[130:131]
	v_cvt_pk_fp8_f32 v137, v46, v47 op_sel:[0,0,1]
	v_lshrrev_b32_e32 v136, 24, v136
	v_lshl_add_u64 v[130:131], v[130:131], 0, v[246:247]
	v_lshrrev_b32_e32 v132, 8, v129
	global_store_byte v[134:135], v136, off offset:112
	global_store_byte v[130:131], v129, off
	global_store_byte v[130:131], v132, off offset:16
	global_store_byte_d16_hi v[130:131], v129, off offset:32
	v_lshrrev_b32_e32 v129, 24, v129
	global_store_byte v[130:131], v129, off offset:48
	global_store_byte v[130:131], v137, off offset:64
	v_lshrrev_b32_e32 v129, 8, v137
	global_store_byte v[130:131], v129, off offset:80
	global_store_byte_d16_hi v[130:131], v137, off offset:96
	v_lshrrev_b32_e32 v129, 24, v137
	global_store_byte v[130:131], v129, off offset:112
	v_add_u32_e32 v129, 0x90, v128
	v_lshlrev_b32_e32 v130, s42, v129
	v_and_b32_e32 v130, 0x3fff, v130
	v_ashrrev_i32_e32 v129, s27, v129
	v_add_u32_e32 v129, v130, v129
	v_lshlrev_b32_e32 v132, 2, v129
	v_and_or_b32 v132, v132, 48, v196
	v_lshlrev_b32_e32 v132, 4, v132
	v_mov_b32_e32 v133, v169
	v_lshrrev_b32_e32 v134, 2, v129
	v_lshl_add_u64 v[132:133], s[14:15], 0, v[132:133]
	v_and_b32_e32 v134, 4, v134
	v_mov_b32_e32 v135, v169
	v_ashrrev_i32_e32 v130, 5, v129
	v_lshl_add_u64 v[132:133], v[132:133], 0, v[134:135]
	v_and_b32_e32 v134, 3, v129
	v_mov_b32_e32 v129, v169
	v_cvt_pk_fp8_f32 v129, v48, v49
	v_mov_b32_e32 v136, v169
	v_cvt_pk_fp8_f32 v136, v40, v41
	v_ashrrev_i32_e32 v131, 31, v130
	v_cvt_pk_fp8_f32 v129, v50, v51 op_sel:[0,0,1]
	v_lshl_add_u64 v[132:133], v[132:133], 0, v[134:135]
	v_cvt_pk_fp8_f32 v136, v42, v43 op_sel:[0,0,1]
	v_lshlrev_b64 v[130:131], 12, v[130:131]
	v_lshl_add_u64 v[134:135], v[132:133], 0, s[52:53]
	v_lshl_add_u64 v[134:135], v[134:135], 0, v[130:131]
	v_lshl_add_u64 v[134:135], v[134:135], 0, v[246:247]
	v_lshrrev_b32_e32 v137, 8, v129
	global_store_byte v[134:135], v129, off
	global_store_byte v[134:135], v137, off offset:16
	global_store_byte_d16_hi v[134:135], v129, off offset:32
	v_lshrrev_b32_e32 v129, 24, v129
	global_store_byte v[134:135], v129, off offset:48
	global_store_byte v[134:135], v136, off offset:64
	v_lshrrev_b32_e32 v129, 8, v136
	global_store_byte v[134:135], v129, off offset:80
	global_store_byte_d16_hi v[134:135], v136, off offset:96
	v_mov_b32_e32 v129, v169
	v_cvt_pk_fp8_f32 v129, v36, v37
	v_mov_b32_e32 v137, v169
	v_cvt_pk_fp8_f32 v137, v28, v29
	v_lshl_add_u64 v[132:133], v[132:133], 0, s[54:55]
	v_cvt_pk_fp8_f32 v129, v38, v39 op_sel:[0,0,1]
	v_lshl_add_u64 v[130:131], v[132:133], 0, v[130:131]
	v_cvt_pk_fp8_f32 v137, v30, v31 op_sel:[0,0,1]
	v_lshrrev_b32_e32 v136, 24, v136
	v_lshl_add_u64 v[130:131], v[130:131], 0, v[246:247]
	v_lshrrev_b32_e32 v132, 8, v129
	global_store_byte v[134:135], v136, off offset:112
	global_store_byte v[130:131], v129, off
	global_store_byte v[130:131], v132, off offset:16
	global_store_byte_d16_hi v[130:131], v129, off offset:32
	v_lshrrev_b32_e32 v129, 24, v129
	global_store_byte v[130:131], v129, off offset:48
	global_store_byte v[130:131], v137, off offset:64
	v_lshrrev_b32_e32 v129, 8, v137
	global_store_byte v[130:131], v129, off offset:80
	global_store_byte_d16_hi v[130:131], v137, off offset:96
	v_lshrrev_b32_e32 v129, 24, v137
	global_store_byte v[130:131], v129, off offset:112
	v_add_u32_e32 v129, 0xa0, v128
	v_lshlrev_b32_e32 v130, s42, v129
	v_and_b32_e32 v130, 0x3fff, v130
	v_ashrrev_i32_e32 v129, s27, v129
	v_add_u32_e32 v129, v130, v129
	v_lshlrev_b32_e32 v132, 2, v129
	v_and_or_b32 v132, v132, 48, v196
	v_lshlrev_b32_e32 v132, 4, v132
	v_mov_b32_e32 v133, v169
	v_lshrrev_b32_e32 v134, 2, v129
	v_lshl_add_u64 v[132:133], s[14:15], 0, v[132:133]
	v_and_b32_e32 v134, 4, v134
	v_mov_b32_e32 v135, v169
	v_ashrrev_i32_e32 v130, 5, v129
;     __device__ __forceinline__ void operator()(const pg8::Acc& acc, const pg8::Unit& u, int wr, int wc, int fr, int fq) const {
;     ...
;         } else if (pn < 8) {
;             unsigned char* VB = (unsigned char*)kbf + ((size_t)24 << 20);
; #pragma unroll
;             for (int ai = 0; ai < 2; ++ai)
; #pragma unroll
;                 for (int m = 0; m < 4; ++m) {
;                     const int row = row0 + ai * 128 + m * 16;
; #pragma unroll
;                     for (int bj = 0; bj < 2; ++bj) {
;                         const int hd = 2 * (pn - 2) + bj, sh = 2 * (hd >> 2), tp = ((row & ((1 << sh) - 1)) << (14 - sh)) + (row >> sh), kp = tp & 31;
;                         const u32x2 w = pack8_fp8(acc[ai][bj][m][0], acc[ai][bj][m][1]);
;                         unsigned char* vb = VB + (((size_t)hd * 512 + (tp >> 5)) * 8 + (cw >> 4)) * 512 + (size_t)(((kp >> 2) & 3) * 16 + (cw & 15)) * 8 + 4 * (kp >> 4) + (kp & 3);
;                         vb[0] = (unsigned char)(w.x & 0xffu); vb[8] = (unsigned char)((w.x >> 8) & 0xffu); vb[16] = (unsigned char)((w.x >> 16) & 0xffu); vb[24] = (unsigned char)(w.x >> 24);
;                         vb[32] = (unsigned char)(w.y & 0xffu); vb[40] = (unsigned char)((w.y >> 8) & 0xffu); vb[48] = (unsigned char)((w.y >> 16) & 0xffu); vb[56] = (unsigned char)(w.y >> 24);
;                     }
;                 }
	v_lshl_add_u64 v[132:133], v[132:133], 0, v[134:135]
	v_and_b32_e32 v134, 3, v129
	v_mov_b32_e32 v129, v169
	v_cvt_pk_fp8_f32 v129, v32, v33
	v_mov_b32_e32 v136, v169
	v_cvt_pk_fp8_f32 v136, v24, v25
	v_ashrrev_i32_e32 v131, 31, v130
	v_cvt_pk_fp8_f32 v129, v34, v35 op_sel:[0,0,1]
	v_lshl_add_u64 v[132:133], v[132:133], 0, v[134:135]
	v_cvt_pk_fp8_f32 v136, v26, v27 op_sel:[0,0,1]
	v_lshlrev_b64 v[130:131], 12, v[130:131]
	v_lshl_add_u64 v[134:135], v[132:133], 0, s[52:53]
	v_lshl_add_u64 v[134:135], v[134:135], 0, v[130:131]
	v_lshl_add_u64 v[134:135], v[134:135], 0, v[246:247]
	v_lshrrev_b32_e32 v137, 8, v129
	global_store_byte v[134:135], v129, off
	global_store_byte v[134:135], v137, off offset:16
	global_store_byte_d16_hi v[134:135], v129, off offset:32
	v_lshrrev_b32_e32 v129, 24, v129
	global_store_byte v[134:135], v129, off offset:48
	global_store_byte v[134:135], v136, off offset:64
	v_lshrrev_b32_e32 v129, 8, v136
	global_store_byte v[134:135], v129, off offset:80
	global_store_byte_d16_hi v[134:135], v136, off offset:96
	v_mov_b32_e32 v129, v169
	v_cvt_pk_fp8_f32 v129, v20, v21
	v_mov_b32_e32 v137, v169
	v_cvt_pk_fp8_f32 v137, v12, v13
	v_lshl_add_u64 v[132:133], v[132:133], 0, s[54:55]
	v_cvt_pk_fp8_f32 v129, v22, v23 op_sel:[0,0,1]
	v_lshl_add_u64 v[130:131], v[132:133], 0, v[130:131]
	v_cvt_pk_fp8_f32 v137, v14, v15 op_sel:[0,0,1]
	v_lshrrev_b32_e32 v136, 24, v136
	v_lshl_add_u64 v[130:131], v[130:131], 0, v[246:247]
	v_lshrrev_b32_e32 v132, 8, v129
	global_store_byte v[134:135], v136, off offset:112
	global_store_byte v[130:131], v129, off
	global_store_byte v[130:131], v132, off offset:16
	global_store_byte_d16_hi v[130:131], v129, off offset:32
	v_lshrrev_b32_e32 v129, 24, v129
	global_store_byte v[130:131], v129, off offset:48
	global_store_byte v[130:131], v137, off offset:64
	v_lshrrev_b32_e32 v129, 8, v137
	global_store_byte v[130:131], v129, off offset:80
	global_store_byte_d16_hi v[130:131], v137, off offset:96
	v_lshrrev_b32_e32 v129, 24, v137
	v_add_u32_e32 v128, 0xb0, v128
	global_store_byte v[130:131], v129, off offset:112
	v_lshlrev_b32_e32 v129, s42, v128
	v_and_b32_e32 v129, 0x3fff, v129
	v_ashrrev_i32_e32 v128, s27, v128
	v_add_u32_e32 v134, v129, v128
	v_lshlrev_b32_e32 v130, 2, v134
	v_and_or_b32 v130, v130, 48, v196
	v_lshlrev_b32_e32 v130, 4, v130
	v_mov_b32_e32 v131, v169
	v_lshrrev_b32_e32 v132, 2, v134
	v_lshl_add_u64 v[130:131], s[14:15], 0, v[130:131]
	v_and_b32_e32 v132, 4, v132
	v_mov_b32_e32 v133, v169
	v_ashrrev_i32_e32 v128, 5, v134
	v_lshl_add_u64 v[130:131], v[130:131], 0, v[132:133]
	v_and_b32_e32 v132, 3, v134
	v_mov_b32_e32 v134, v169
	v_cvt_pk_fp8_f32 v134, v16, v17
	v_mov_b32_e32 v135, v169
	v_cvt_pk_fp8_f32 v135, v8, v9
	v_ashrrev_i32_e32 v129, 31, v128
	v_cvt_pk_fp8_f32 v134, v18, v19 op_sel:[0,0,1]
	v_lshl_add_u64 v[130:131], v[130:131], 0, v[132:133]
	v_cvt_pk_fp8_f32 v135, v10, v11 op_sel:[0,0,1]
	v_lshlrev_b64 v[128:129], 12, v[128:129]
	v_lshl_add_u64 v[132:133], v[130:131], 0, s[52:53]
	v_lshl_add_u64 v[132:133], v[132:133], 0, v[128:129]
	v_lshl_add_u64 v[132:133], v[132:133], 0, v[246:247]
	v_lshrrev_b32_e32 v136, 8, v134
	global_store_byte v[132:133], v134, off
	global_store_byte v[132:133], v136, off offset:16
	global_store_byte_d16_hi v[132:133], v134, off offset:32
	v_lshrrev_b32_e32 v134, 24, v134
	global_store_byte v[132:133], v134, off offset:48
	global_store_byte v[132:133], v135, off offset:64
	v_lshrrev_b32_e32 v134, 8, v135
	global_store_byte v[132:133], v134, off offset:80
	global_store_byte_d16_hi v[132:133], v135, off offset:96
	v_mov_b32_e32 v134, v169
	v_cvt_pk_fp8_f32 v134, v4, v5
	v_mov_b32_e32 v136, v169
	v_cvt_pk_fp8_f32 v136, v0, v1
	v_lshl_add_u64 v[130:131], v[130:131], 0, s[54:55]
	v_cvt_pk_fp8_f32 v134, v6, v7 op_sel:[0,0,1]
	v_lshl_add_u64 v[128:129], v[130:131], 0, v[128:129]
	v_cvt_pk_fp8_f32 v136, v2, v3 op_sel:[0,0,1]
	v_lshrrev_b32_e32 v135, 24, v135
	v_lshl_add_u64 v[128:129], v[128:129], 0, v[246:247]
	v_lshrrev_b32_e32 v130, 8, v134
	global_store_byte v[132:133], v135, off offset:112
	global_store_byte v[128:129], v134, off
	global_store_byte v[128:129], v130, off offset:16
	global_store_byte_d16_hi v[128:129], v134, off offset:32
	v_lshrrev_b32_e32 v130, 24, v134
	global_store_byte v[128:129], v130, off offset:48
	global_store_byte v[128:129], v136, off offset:64
	v_lshrrev_b32_e32 v130, 8, v136
	global_store_byte v[128:129], v130, off offset:80
	global_store_byte_d16_hi v[128:129], v136, off offset:96
	v_lshrrev_b32_e32 v130, 24, v136
	global_store_byte v[128:129], v130, off offset:112

; __device__ __forceinline__ float bf2f(unsigned short b) { return __uint_as_float(((unsigned)b) << 16); }
; template <bool SLC, class Desc>
; __device__ __forceinline__ void attn_run_frag8(const i64_t (&qf)[4], const unsigned char* __restrict__ KF, const unsigned char* __restrict__ VF, const Desc& desc, int n,
;                                                int lo_in, int hi, int qi, AState& st, int lane) {
;     if (n <= 0) return;
;     Frag8 fa, fb, fc;
;     constexpr int NM = ~(1 << 30);
;     int d0 = desc(0), d1 = desc(n > 1 ? 1 : 0);
;     load_frag8(fa, KF, VF, SLC ? (d0 & 0xfffff) : (d0 & NM), lane);
;     load_frag8(fb, KF, VF, SLC ? (d1 & 0xfffff) : (d1 & NM), lane);
; __device__ __forceinline__ void dilated_unit(int unit, const bf16_t* proj, const bf16_t* kbf, bf16_t* nsaout, int lane) {
;     ...
;     for (int pt = 0; pt < 3; ++pt) {
;         const int sh = 2 * pt, head = 4 * pt + hg;
;         const bf16_t* qrow = proj + (size_t)tc * PLD + PC_QB + head * 128 + 8 * kq;
;         i64_t q8[4];
; #pragma unroll
;         for (int s = 0; s < 4; ++s) { const bf16x8 qv = *(const bf16x8*)(qrow + 32 * s); f32x4 a, b;
; #pragma unroll
;             for (int j = 0; j < 4; ++j) { a[j] = bf2f((unsigned short)qv[j]) * SL2; b[j] = bf2f((unsigned short)qv[4 + j]) * SL2; }
;             q8[s] = __builtin_bit_cast(i64_t, pack8_fp8(a, b)); }
;         const int base = (r16 & ((1 << sh) - 1)) << (14 - sh), u0 = t0 >> sh, ui = u0 + (16 >> sh) * l16;
;         const int lo = base + (ui - 128 < 0 ? 0 : ui - 128), hi = base + ui;
;         const int first = (base + (u0 - 128 < 0 ? 0 : u0 - 128)) >> 5, last = (base + u0 + 15 * (16 >> sh)) >> 5;
;         unsigned long long hoff = (unsigned long long)head * S * 128; asm volatile("" : "+s"(hoff));
;         auto desc = [&](int i) { return 32 * (first + i); };
;         attn_run_frag8<false>(q8, kb8 + hoff, vb8 + hoff, desc, last - first + 1, lo, hi, 0, st, lane);
.LBB0_694:
	s_lshl_b32 s4, s72, 2
	s_or_b32 s4, s4, s69
	s_lshl_b32 s26, s4, 8
	v_lshl_add_u64 v[2:3], v[110:111], 0, s[26:27]
	global_load_dwordx4 v[14:17], v[2:3], off
	global_load_dwordx4 v[10:13], v[2:3], off offset:64
	global_load_dwordx4 v[6:9], v[2:3], off offset:128
	s_nop 0
	global_load_dwordx4 v[2:5], v[2:3], off offset:192
	s_lshl_b32 s5, s72, 1
	s_sub_i32 s6, 14, s5
	s_lshl_b32 s6, s70, s6
	s_and_b32 s8, s6, 0x3f00
	s_ashr_i32 s10, s71, s5
	s_lshr_b32 s11, 16, s5
	s_add_i32 s9, s8, 0xffffff80
	s_max_i32 s5, s10, 0x80
	s_add_i32 s12, s9, s5
	s_mul_i32 s5, s11, 15
	s_add_i32 s5, s5, s10
	s_add_i32 s5, s5, s8
	s_lshr_b32 s73, s12, 5
	s_ashr_i32 s13, s5, 5
	s_lshl_b32 s26, s4, 21
	s_sub_i32 s74, s13, s73
	s_mov_b64 s[6:7], s[26:27]
	s_cmp_lt_i32 s74, 0
	s_cbranch_scc1 .LBB0_726
	s_add_u32 s4, s61, s6
	s_addc_u32 s5, s62, s7
	s_add_u32 s6, s59, s6
	s_addc_u32 s7, s60, s7
	s_and_b32 s75, s12, 0xffffffe0
	s_cmp_lg_u32 s13, s73
	s_cselect_b64 s[14:15], -1, 0
	s_cmp_lg_u64 s[14:15], 0
	s_addc_u32 s14, s73, 0
	s_and_b32 s15, s12, 0xbfffffe0
	s_lshr_b32 s26, s15, 4
	s_lshl_b32 s76, s14, 5
	s_lshl_b64 s[12:13], s[26:27], 11
	s_waitcnt vmcnt(3)
	v_lshlrev_b32_e32 v0, 16, v14
	v_and_b32_e32 v14, 0xffff0000, v14
	s_add_u32 s12, s6, s12
	v_mul_f32_e32 v0, 0x3e0293ee, v0
	v_mul_f32_e32 v14, 0x3e0293ee, v14
	v_lshlrev_b32_e32 v19, 16, v15
	v_and_b32_e32 v15, 0xffff0000, v15
	v_mov_b32_e32 v74, v1
	s_addc_u32 s13, s7, s13
	s_lshr_b32 s26, s15, 5
	v_mul_f32_e32 v21, 0x3e0293ee, v15
	v_cvt_pk_fp8_f32 v74, v0, v14
	v_lshl_add_u64 v[14:15], s[12:13], 0, v[98:99]
	s_lshl_b64 s[12:13], s[26:27], 12
	s_add_u32 s12, s4, s12
	s_addc_u32 s13, s5, s13
	v_lshl_add_u64 v[244:245], v[14:15], 0, v[98:99]
	global_load_dwordx4 v[132:135], v[244:245], off
	global_load_dwordx4 v[136:139], v[244:245], off offset:1024
	global_load_dwordx4 v[140:143], v[244:245], off offset:2048
	global_load_dwordx4 v[144:147], v[244:245], off offset:3072
	v_lshl_add_u64 v[14:15], s[12:13], 0, v[98:99]
	s_and_b32 s12, s76, 0x3fffffe0
	s_lshr_b32 s26, s12, 4
	s_lshl_b64 s[12:13], s[26:27], 11
	s_add_u32 s12, s6, s12
	s_addc_u32 s13, s7, s13
	s_and_b32 s26, s14, 0x1ffffff
	v_lshl_add_u64 v[246:247], v[14:15], 0, v[98:99]
	global_load_dwordx4 v[86:89], v[246:247], off
	global_load_dwordx4 v[90:93], v[246:247], off offset:1024
	global_load_dwordx4 v[94:97], v[246:247], off offset:2048
	global_load_dwordx4 v[112:115], v[246:247], off offset:3072
	v_lshl_add_u64 v[14:15], s[12:13], 0, v[98:99]
	s_lshl_b64 s[12:13], s[26:27], 12
	s_add_u32 s12, s4, s12
	s_addc_u32 s13, s5, s13
	v_lshl_add_u64 v[244:245], v[14:15], 0, v[98:99]
	global_load_dwordx4 v[148:151], v[244:245], off
	global_load_dwordx4 v[152:155], v[244:245], off offset:1024
	global_load_dwordx4 v[156:159], v[244:245], off offset:2048
	global_load_dwordx4 v[160:163], v[244:245], off offset:3072
	v_lshl_add_u64 v[14:15], s[12:13], 0, v[98:99]
	v_lshl_add_u64 v[246:247], v[14:15], 0, v[98:99]
	global_load_dwordx4 v[116:119], v[246:247], off
	global_load_dwordx4 v[120:123], v[246:247], off offset:1024
	global_load_dwordx4 v[124:127], v[246:247], off offset:2048
	global_load_dwordx4 v[128:131], v[246:247], off offset:3072
	v_lshlrev_b32_e32 v18, 16, v16
	v_and_b32_e32 v16, 0xffff0000, v16
	v_mul_f32_e32 v18, 0x3e0293ee, v18
	v_mul_f32_e32 v16, 0x3e0293ee, v16
	v_mov_b32_e32 v75, v1
	v_cvt_pk_fp8_f32 v75, v18, v16
	v_lshlrev_b32_e32 v20, 16, v17
	v_and_b32_e32 v17, 0xffff0000, v17
	s_waitcnt vmcnt(18)
	v_lshlrev_b32_e32 v14, 16, v12
	v_and_b32_e32 v12, 0xffff0000, v12
	v_mul_f32_e32 v20, 0x3e0293ee, v20
	v_mul_f32_e32 v0, 0x3e0293ee, v17
	v_mul_f32_e32 v14, 0x3e0293ee, v14
	v_mul_f32_e32 v12, 0x3e0293ee, v12
	v_mov_b32_e32 v77, v1
	v_cvt_pk_fp8_f32 v75, v20, v0 op_sel:[0,0,1]
	v_lshlrev_b32_e32 v0, 16, v10
	v_and_b32_e32 v10, 0xffff0000, v10
	v_cvt_pk_fp8_f32 v77, v14, v12
	v_mul_f32_e32 v0, 0x3e0293ee, v0
	v_mul_f32_e32 v10, 0x3e0293ee, v10
	v_mov_b32_e32 v76, v1
	v_lshlrev_b32_e32 v16, 16, v13
	v_cvt_pk_fp8_f32 v76, v0, v10
	v_and_b32_e32 v0, 0xffff0000, v13
	s_waitcnt vmcnt(17)
	v_lshlrev_b32_e32 v10, 16, v8
	v_and_b32_e32 v8, 0xffff0000, v8
	v_mul_f32_e32 v16, 0x3e0293ee, v16
	v_mul_f32_e32 v0, 0x3e0293ee, v0
	v_mul_f32_e32 v10, 0x3e0293ee, v10
	v_mul_f32_e32 v8, 0x3e0293ee, v8
	v_mov_b32_e32 v79, v1
	v_cvt_pk_fp8_f32 v77, v16, v0 op_sel:[0,0,1]
	v_lshlrev_b32_e32 v0, 16, v6
	v_and_b32_e32 v6, 0xffff0000, v6
	v_cvt_pk_fp8_f32 v79, v10, v8
	v_mul_f32_e32 v0, 0x3e0293ee, v0
	v_mul_f32_e32 v6, 0x3e0293ee, v6
	v_mov_b32_e32 v78, v1
	v_lshlrev_b32_e32 v12, 16, v9
	v_cvt_pk_fp8_f32 v78, v0, v6
	v_and_b32_e32 v0, 0xffff0000, v9
	v_mul_f32_e32 v12, 0x3e0293ee, v12
	v_mul_f32_e32 v0, 0x3e0293ee, v0
	v_lshlrev_b32_e32 v15, 16, v11
	v_and_b32_e32 v11, 0xffff0000, v11
	v_cvt_pk_fp8_f32 v79, v12, v0 op_sel:[0,0,1]
	s_waitcnt vmcnt(16)
	v_lshlrev_b32_e32 v0, 16, v2
	v_lshlrev_b32_e32 v6, 16, v4
	v_and_b32_e32 v2, 0xffff0000, v2
	v_and_b32_e32 v4, 0xffff0000, v4
	v_mul_f32_e32 v15, 0x3e0293ee, v15
	v_mul_f32_e32 v11, 0x3e0293ee, v11
	v_mul_f32_e32 v0, 0x3e0293ee, v0
	v_mul_f32_e32 v6, 0x3e0293ee, v6
	v_mul_f32_e32 v2, 0x3e0293ee, v2
	v_mul_f32_e32 v4, 0x3e0293ee, v4
	v_mov_b32_e32 v80, v1
	v_mov_b32_e32 v81, v1
	v_cvt_pk_fp8_f32 v76, v15, v11 op_sel:[0,0,1]
	v_lshlrev_b32_e32 v11, 16, v7
	v_and_b32_e32 v7, 0xffff0000, v7
	v_cvt_pk_fp8_f32 v80, v0, v2
	v_cvt_pk_fp8_f32 v81, v6, v4
	v_mul_f32_e32 v11, 0x3e0293ee, v11
	v_mul_f32_e32 v7, 0x3e0293ee, v7
	v_cvt_pk_fp8_f32 v78, v11, v7 op_sel:[0,0,1]
	v_lshlrev_b32_e32 v7, 16, v3
	v_lshlrev_b32_e32 v8, 16, v5
	v_and_b32_e32 v3, 0xffff0000, v3
	v_and_b32_e32 v0, 0xffff0000, v5
	v_mul_f32_e32 v19, 0x3e0293ee, v19
	v_mul_f32_e32 v7, 0x3e0293ee, v7
	v_mul_f32_e32 v8, 0x3e0293ee, v8
	v_mul_f32_e32 v3, 0x3e0293ee, v3
	v_mul_f32_e32 v0, 0x3e0293ee, v0
	v_cvt_pk_fp8_f32 v74, v19, v21 op_sel:[0,0,1]
	v_cvt_pk_fp8_f32 v80, v7, v3 op_sel:[0,0,1]
	v_cvt_pk_fp8_f32 v81, v8, v0 op_sel:[0,0,1]
	v_mov_b32_e32 v0, s10
	v_mad_u32_u24 v0, s11, v201, v0
	v_max_i32_e32 v2, 0x80, v0
	s_mov_b32 s66, 0
	v_add_u32_e32 v105, s9, v2
	v_add_u32_e32 v206, s8, v0
	v_lshl_add_u64 v[82:83], s[6:7], 0, v[98:99]
	v_lshl_add_u64 v[84:85], s[4:5], 0, v[98:99]
	s_branch .LBB0_698

; template <bool SLC, bool NOMASK> ...
;     const int kq = lane >> 4;
;     const int pos0 = SLC ? (dcur & 0xfffff) : dcur;
;     const int lo = SLC ? ((((dcur >> 20) == qi) | ((dcur >> 20) == 4)) ? 0 : (1 << 30)) : lo_in;
;     load_frag8(nxt, KF, VF, SLC ? (dnext & 0xfffff) : dnext, lane);
;     f32x4 sa[2] = {(f32x4){0.f, 0.f, 0.f, 0.f}, (f32x4){0.f, 0.f, 0.f, 0.f}};
; #pragma unroll
;     for (int T = 0; T < 2; ++T)
; #pragma unroll
;         for (int s2 = 0; s2 < 4; ++s2) sa[T] = __builtin_amdgcn_mfma_f32_16x16x32_fp8_fp8(cur.k[T][s2], qf[s2], sa[T], 0, 0, 0);
;     float sc[8]; bool vd[8]; float mx = -1e30f;
;     const bool act = lo == 0 || !SLC;
;     if (NOMASK) {
; #pragma unroll
;         for (int j = 0; j < 8; ++j) { sc[j] = sa[j >> 2][j & 3]; vd[j] = act; }
;         mx = fmaxf(fmaxf(fmaxf(sc[0], sc[1]), fmaxf(sc[2], sc[3])), fmaxf(fmaxf(sc[4], sc[5]), fmaxf(sc[6], sc[7])));
;         mx = act ? mx : -1e30f;
;     } else {
; #pragma unroll
;         for (int T = 0; T < 2; ++T)
; #pragma unroll
;             for (int r = 0; r < 4; ++r) { const int p = pos0 + 16 * T + 4 * kq + r; const bool v = (p >= lo) & (p <= hi); const float x = sa[T][r];
;                 sc[4 * T + r] = x; vd[4 * T + r] = v; mx = v ? fmaxf(mx, x) : mx; }
;     }
;     if (__builtin_amdgcn_ballot_w64(mx > st.m + 4.f) != 0ull) {
;         mx = fmaxf(mx, __shfl_xor(mx, 16)); mx = fmaxf(mx, __shfl_xor(mx, 32));
;         const float mn = fmaxf(st.m, mx), alpha = __builtin_amdgcn_exp2f(st.m - mn); st.m = mn; st.l *= alpha;
; #pragma unroll
;         for (int j = 0; j < 8; ++j) st.o[j] = st.o[j] * alpha;
;     }
;     f32x4 pa, pb; float ps = 0.f;
;     const float mref = st.m - 4.f;
;     if (NOMASK) {
; #pragma unroll
;         for (int j = 0; j < 4; ++j) { pa[j] = __builtin_amdgcn_exp2f(sc[j] - mref); pb[j] = __builtin_amdgcn_exp2f(sc[4 + j] - mref); }
;         if (SLC) {
; #pragma unroll
;             for (int j = 0; j < 4; ++j) { pa[j] = act ? pa[j] : 0.f; pb[j] = act ? pb[j] : 0.f; }
;         }
; #pragma unroll
;         for (int j = 0; j < 4; ++j) ps += pa[j] + pb[j];
;     } else {
; #pragma unroll
;         for (int j = 0; j < 4; ++j) { pa[j] = vd[j] ? __builtin_amdgcn_exp2f(sc[j] - mref) : 0.f; pb[j] = vd[4 + j] ? __builtin_amdgcn_exp2f(sc[4 + j] - mref) : 0.f; ps += pa[j] + pb[j]; }
;     }
;     st.l += ps;
;     const u32x2 pw = pack8_fp8(pa, pb);
.LBB0_704:
	v_lshl_add_u64 v[244:245], v[198:199], 0, v[98:99]
	global_load_dwordx4 v[180:183], v[244:245], off
	global_load_dwordx4 v[184:187], v[244:245], off offset:1024
	global_load_dwordx4 v[188:191], v[244:245], off offset:2048
	global_load_dwordx4 v[192:195], v[244:245], off offset:3072
	v_lshl_add_u64 v[246:247], v[196:197], 0, v[98:99]
	global_load_dwordx4 v[164:167], v[246:247], off
	global_load_dwordx4 v[168:171], v[246:247], off offset:1024
	global_load_dwordx4 v[172:175], v[246:247], off offset:2048
	global_load_dwordx4 v[176:179], v[246:247], off offset:3072
	s_waitcnt vmcnt(20)
	v_mfma_f32_16x16x32_fp8_fp8 v[2:5], v[132:133], v[74:75], 0
	v_mov_b64_e32 v[72:73], v[48:49]
	v_mov_b64_e32 v[68:69], v[52:53]
	v_mov_b64_e32 v[30:31], v[58:59]
	v_mfma_f32_16x16x32_fp8_fp8 v[6:9], v[140:141], v[74:75], 0
	v_mov_b64_e32 v[26:27], v[62:63]
	v_mov_b64_e32 v[22:23], v[54:55]
	v_mov_b64_e32 v[18:19], v[42:43]
	v_mfma_f32_16x16x32_fp8_fp8 v[2:5], v[134:135], v[76:77], v[2:5]
	v_mov_b64_e32 v[14:15], v[38:39]
	v_mov_b32_e32 v207, v210
	v_mov_b64_e32 v[70:71], v[46:47]
	v_mfma_f32_16x16x32_fp8_fp8 v[6:9], v[142:143], v[76:77], v[6:9]
	v_mov_b64_e32 v[66:67], v[50:51]
	v_mov_b64_e32 v[32:33], v[60:61]
	v_mov_b64_e32 v[28:29], v[64:65]
	v_mfma_f32_16x16x32_fp8_fp8 v[2:5], v[136:137], v[78:79], v[2:5]
	v_mov_b64_e32 v[24:25], v[56:57]
	v_mov_b64_e32 v[20:21], v[44:45]
	v_mov_b64_e32 v[16:17], v[40:41]
	v_mfma_f32_16x16x32_fp8_fp8 v[6:9], v[144:145], v[78:79], v[6:9]
	v_mov_b32_e32 v208, v209
	v_mfma_f32_16x16x32_fp8_fp8 v[2:5], v[138:139], v[80:81], v[2:5]
	v_mfma_f32_16x16x32_fp8_fp8 v[6:9], v[146:147], v[80:81], v[6:9]
	s_nop 5
	v_max_f32_e32 v0, v3, v3
	v_max_f32_e32 v10, v2, v2
	v_max_f32_e32 v0, v10, v0
	v_max_f32_e32 v10, v5, v5
	v_max_f32_e32 v11, v4, v4
	v_max_f32_e32 v10, v11, v10
	v_max_f32_e32 v11, v9, v9
	v_max_f32_e32 v12, v8, v8
	v_max_f32_e32 v11, v12, v11
	v_max3_f32 v11, v6, v7, v11
	v_max3_f32 v0, v0, v10, v11
	v_mov_b64_e32 v[10:11], v[34:35]
	v_cmp_gt_f32_e32 vcc, v0, v211
	v_mov_b64_e32 v[12:13], v[36:37]
	s_cbranch_vccz .LBB0_706
	v_and_b32_e32 v11, 64, v204
	v_xor_b32_e32 v10, 16, v204
	v_add_u32_e32 v11, 64, v11
	v_cmp_lt_i32_e32 vcc, v10, v11
	v_xor_b32_e32 v12, 32, v204
	s_nop 0
	v_cndmask_b32_e32 v10, v204, v10, vcc
	v_lshlrev_b32_e32 v10, 2, v10
	ds_bpermute_b32 v10, v10, v0
	v_max_f32_e32 v0, v0, v0
	v_cmp_lt_i32_e32 vcc, v12, v11
	s_waitcnt lgkmcnt(0)
	v_max_f32_e32 v10, v10, v10
	v_max_f32_e32 v0, v0, v10
	v_cndmask_b32_e32 v10, v204, v12, vcc
	v_lshlrev_b32_e32 v10, 2, v10
	ds_bpermute_b32 v10, v10, v0
	s_waitcnt lgkmcnt(0)
	v_max3_f32 v207, v210, v0, v10
	v_sub_f32_e32 v0, v210, v207
	v_exp_f32_e32 v0, v0
	s_nop 0
	v_mul_f32_e32 v208, v209, v0
	v_pk_mul_f32 v[12:13], v[36:37], v[0:1] op_sel_hi:[1,0]
	v_pk_mul_f32 v[10:11], v[34:35], v[0:1] op_sel_hi:[1,0]
	v_pk_mul_f32 v[16:17], v[40:41], v[0:1] op_sel_hi:[1,0]
	v_pk_mul_f32 v[14:15], v[38:39], v[0:1] op_sel_hi:[1,0]
	v_pk_mul_f32 v[20:21], v[44:45], v[0:1] op_sel_hi:[1,0]
	v_pk_mul_f32 v[18:19], v[42:43], v[0:1] op_sel_hi:[1,0]
	v_pk_mul_f32 v[24:25], v[56:57], v[0:1] op_sel_hi:[1,0]
	v_pk_mul_f32 v[22:23], v[54:55], v[0:1] op_sel_hi:[1,0]
	v_pk_mul_f32 v[28:29], v[64:65], v[0:1] op_sel_hi:[1,0]
	v_pk_mul_f32 v[26:27], v[62:63], v[0:1] op_sel_hi:[1,0]
	v_pk_mul_f32 v[32:33], v[60:61], v[0:1] op_sel_hi:[1,0]
	v_pk_mul_f32 v[30:31], v[58:59], v[0:1] op_sel_hi:[1,0]
	v_pk_mul_f32 v[68:69], v[52:53], v[0:1] op_sel_hi:[1,0]
	v_pk_mul_f32 v[66:67], v[50:51], v[0:1] op_sel_hi:[1,0]
	v_pk_mul_f32 v[72:73], v[48:49], v[0:1] op_sel_hi:[1,0]
	v_pk_mul_f32 v[70:71], v[46:47], v[0:1] op_sel_hi:[1,0]
.LBB0_706:
	v_add_f32_e32 v213, -4.0, v207
	v_sub_f32_e32 v0, v2, v213
	v_exp_f32_e32 v215, v0
	v_sub_f32_e32 v0, v6, v213
	v_exp_f32_e32 v217, v0
	v_sub_f32_e32 v0, v3, v213
	v_exp_f32_e32 v212, v0
	v_sub_f32_e32 v0, v7, v213
	v_exp_f32_e32 v0, v0
	v_sub_f32_e32 v2, v4, v213
	v_exp_f32_e32 v220, v2
	v_sub_f32_e32 v2, v8, v213
	v_exp_f32_e32 v221, v2
	v_sub_f32_e32 v2, v5, v213
	v_exp_f32_e32 v214, v2
	v_sub_f32_e32 v2, v9, v213
	v_mov_b32_e32 v218, v1
	v_mov_b32_e32 v219, v1
	v_exp_f32_e32 v216, v2
	v_cvt_pk_fp8_f32 v218, v215, v212
	v_cvt_pk_fp8_f32 v219, v217, v0
	v_add_f32_e32 v213, v215, v217
	v_add_f32_e32 v215, v220, v221
	v_cvt_pk_fp8_f32 v218, v220, v214 op_sel:[0,0,1]
	v_cvt_pk_fp8_f32 v219, v221, v216 op_sel:[0,0,1]
	s_nop 0
	s_waitcnt vmcnt(19)
	v_mfma_f32_16x16x32_fp8_fp8 v[2:5], v[86:87], v[218:219], v[10:13]
	v_mfma_f32_16x16x32_fp8_fp8 v[10:13], v[90:91], v[218:219], v[18:21]
	s_waitcnt vmcnt(18)
	v_mfma_f32_16x16x32_fp8_fp8 v[18:21], v[94:95], v[218:219], v[26:29]
	s_nop 2
	v_add_f32_e64 v26, v212, v0
	v_add_f32_e64 v27, v213, v1
	v_mfma_f32_16x16x32_fp8_fp8 v[6:9], v[88:89], v[218:219], v[14:17]
	v_pk_add_f32 v[26:27], v[26:27], v[26:27] op_sel_hi:[0,1]
	v_mov_b32_e32 v217, v27
	v_pk_add_f32 v[26:27], v[214:215], v[216:217]
	s_waitcnt vmcnt(17)
	v_mfma_f32_16x16x32_fp8_fp8 v[14:17], v[92:93], v[218:219], v[22:25]
	v_add_f32_e32 v0, v26, v27
	v_add_f32_e32 v208, v0, v208
	v_mfma_f32_16x16x32_fp8_fp8 v[22:25], v[96:97], v[218:219], v[30:33]
	s_waitcnt vmcnt(16)
	v_mfma_f32_16x16x32_fp8_fp8 v[30:33], v[112:113], v[218:219], v[66:69]
	v_mfma_f32_16x16x32_fp8_fp8 v[26:29], v[114:115], v[218:219], v[70:73]
	s_branch .LBB0_700
; template <bool SLC, bool NOMASK> ...
;     ...
;     load_frag8(nxt, KF, VF, SLC ? (dnext & 0xfffff) : dnext, lane);
;     f32x4 sa[2] = {(f32x4){0.f, 0.f, 0.f, 0.f}, (f32x4){0.f, 0.f, 0.f, 0.f}};
; #pragma unroll
;     for (int T = 0; T < 2; ++T)
; #pragma unroll
;         for (int s2 = 0; s2 < 4; ++s2) sa[T] = __builtin_amdgcn_mfma_f32_16x16x32_fp8_fp8(cur.k[T][s2], qf[s2], sa[T], 0, 0, 0);
;     float sc[8]; bool vd[8]; float mx = -1e30f;
;     const bool act = lo == 0 || !SLC;
;     if (NOMASK) {
; #pragma unroll
;         for (int j = 0; j < 8; ++j) { sc[j] = sa[j >> 2][j & 3]; vd[j] = act; }
;         mx = fmaxf(fmaxf(fmaxf(sc[0], sc[1]), fmaxf(sc[2], sc[3])), fmaxf(fmaxf(sc[4], sc[5]), fmaxf(sc[6], sc[7])));
;         mx = act ? mx : -1e30f;
;     } else {
; #pragma unroll
;         for (int T = 0; T < 2; ++T)
; #pragma unroll
;             for (int r = 0; r < 4; ++r) { const int p = pos0 + 16 * T + 4 * kq + r; const bool v = (p >= lo) & (p <= hi); const float x = sa[T][r];
;                 sc[4 * T + r] = x; vd[4 * T + r] = v; mx = v ? fmaxf(mx, x) : mx; }
;     }
;     if (__builtin_amdgcn_ballot_w64(mx > st.m + 4.f) != 0ull) {
;         mx = fmaxf(mx, __shfl_xor(mx, 16)); mx = fmaxf(mx, __shfl_xor(mx, 32));
;         const float mn = fmaxf(st.m, mx), alpha = __builtin_amdgcn_exp2f(st.m - mn); st.m = mn; st.l *= alpha;
; #pragma unroll
;         for (int j = 0; j < 8; ++j) st.o[j] = st.o[j] * alpha;
;     }
;     f32x4 pa, pb; float ps = 0.f;
;     const float mref = st.m - 4.f;
;     if (NOMASK) {
; #pragma unroll
;         for (int j = 0; j < 4; ++j) { pa[j] = __builtin_amdgcn_exp2f(sc[j] - mref); pb[j] = __builtin_amdgcn_exp2f(sc[4 + j] - mref); }
;         if (SLC) {
; #pragma unroll
;             for (int j = 0; j < 4; ++j) { pa[j] = act ? pa[j] : 0.f; pb[j] = act ? pb[j] : 0.f; }
;         }
; #pragma unroll
;         for (int j = 0; j < 4; ++j) ps += pa[j] + pb[j];
;     } else {
; #pragma unroll
;         for (int j = 0; j < 4; ++j) { pa[j] = vd[j] ? __builtin_amdgcn_exp2f(sc[j] - mref) : 0.f; pb[j] = vd[4 + j] ? __builtin_amdgcn_exp2f(sc[4 + j] - mref) : 0.f; ps += pa[j] + pb[j]; }
;     }
;     st.l += ps;
;     const u32x2 pw = pack8_fp8(pa, pb);
;     const i64_t pf = __builtin_bit_cast(i64_t, pw);
; #pragma unroll
;     for (int db = 0; db < 8; ++db) st.o[db] = __builtin_amdgcn_mfma_f32_16x16x32_fp8_fp8(cur.v[db], pf, st.o[db], 0, 0, 0);
.LBB0_707:
	v_lshl_add_u64 v[244:245], v[198:199], 0, v[98:99]
	global_load_dwordx4 v[180:183], v[244:245], off
	global_load_dwordx4 v[184:187], v[244:245], off offset:1024
	global_load_dwordx4 v[188:191], v[244:245], off offset:2048
	global_load_dwordx4 v[192:195], v[244:245], off offset:3072
	v_lshl_add_u64 v[246:247], v[196:197], 0, v[98:99]
	global_load_dwordx4 v[164:167], v[246:247], off
	global_load_dwordx4 v[168:171], v[246:247], off offset:1024
	global_load_dwordx4 v[172:175], v[246:247], off offset:2048
	global_load_dwordx4 v[176:179], v[246:247], off offset:3072
	s_waitcnt vmcnt(20)
	v_mfma_f32_16x16x32_fp8_fp8 v[2:5], v[132:133], v[74:75], 0
	v_or_b32_e32 v0, s75, v203
	v_cmp_ge_i32_e32 vcc, v0, v105
	v_cmp_le_i32_e64 s[4:5], v0, v206
	v_mfma_f32_16x16x32_fp8_fp8 v[2:5], v[134:135], v[76:77], v[2:5]
	s_and_b64 s[10:11], vcc, s[4:5]
	v_or_b32_e32 v11, 1, v0
	v_cmp_ge_i32_e32 vcc, v11, v105
	v_mfma_f32_16x16x32_fp8_fp8 v[2:5], v[136:137], v[78:79], v[2:5]
	v_cmp_lt_i32_e64 s[4:5], v0, v206
	s_and_b64 s[6:7], s[4:5], vcc
	v_mfma_f32_16x16x32_fp8_fp8 v[6:9], v[140:141], v[74:75], 0
	v_mfma_f32_16x16x32_fp8_fp8 v[2:5], v[138:139], v[80:81], v[2:5]
	v_mfma_f32_16x16x32_fp8_fp8 v[6:9], v[142:143], v[76:77], v[6:9]
	v_mfma_f32_16x16x32_fp8_fp8 v[6:9], v[144:145], v[78:79], v[6:9]
	s_nop 3
	v_max_f32_e32 v10, v2, v2
	v_max_f32_e32 v10, 0xf149f2ca, v10
	v_cndmask_b32_e64 v10, v205, v10, s[10:11]
	v_max_f32_e32 v11, v3, v3
	v_max_f32_e32 v11, v10, v11
	v_cndmask_b32_e64 v10, v10, v11, s[6:7]
	v_or_b32_e32 v11, 2, v0
	v_cmp_ge_i32_e32 vcc, v11, v105
	v_cmp_le_i32_e64 s[4:5], v11, v206
	v_max_f32_e32 v11, v4, v4
	v_max_f32_e32 v11, v10, v11
	s_and_b64 s[8:9], vcc, s[4:5]
	v_mfma_f32_16x16x32_fp8_fp8 v[6:9], v[146:147], v[80:81], v[6:9]
	v_cndmask_b32_e64 v10, v10, v11, s[8:9]
	v_or_b32_e32 v11, 3, v0
	v_cmp_ge_i32_e32 vcc, v11, v105
	v_cmp_le_i32_e64 s[4:5], v11, v206
	v_max_f32_e32 v11, v5, v5
	v_max_f32_e32 v11, v10, v11
	s_and_b64 s[4:5], vcc, s[4:5]
	v_cndmask_b32_e64 v10, v10, v11, s[4:5]
	v_or_b32_e32 v11, 16, v0
	v_cmp_ge_i32_e32 vcc, v11, v105
	v_cmp_le_i32_e64 s[12:13], v11, v206
	v_max_f32_e32 v11, v6, v6
	v_max_f32_e32 v11, v10, v11
	s_and_b64 s[18:19], vcc, s[12:13]
	v_cndmask_b32_e64 v10, v10, v11, s[18:19]
	v_or_b32_e32 v11, 17, v0
	v_cmp_ge_i32_e32 vcc, v11, v105
	v_cmp_le_i32_e64 s[12:13], v11, v206
	v_max_f32_e32 v11, v10, v10
	v_max_f32_e32 v12, v7, v7
	v_max_f32_e32 v11, v11, v12
	s_and_b64 s[14:15], vcc, s[12:13]
	v_cndmask_b32_e64 v10, v10, v11, s[14:15]
	v_or_b32_e32 v11, 18, v0
	v_cmp_ge_i32_e32 vcc, v11, v105
	v_cmp_le_i32_e64 s[12:13], v11, v206
	v_max_f32_e32 v11, v10, v10
	v_max_f32_e32 v12, v8, v8
	v_max_f32_e32 v11, v11, v12
	s_and_b64 s[16:17], vcc, s[12:13]
	v_cndmask_b32_e64 v10, v10, v11, s[16:17]
	v_or_b32_e32 v0, 19, v0
	v_cmp_ge_i32_e32 vcc, v0, v105
	v_cmp_le_i32_e64 s[12:13], v0, v206
	v_max_f32_e32 v0, v10, v10
	v_max_f32_e32 v11, v9, v9
	v_max_f32_e32 v0, v0, v11
	s_and_b64 s[12:13], vcc, s[12:13]
	v_cndmask_b32_e64 v0, v10, v0, s[12:13]
	v_cmp_gt_f32_e32 vcc, v0, v211
	s_cbranch_vccz .LBB0_709
	v_and_b32_e32 v11, 64, v204
	v_xor_b32_e32 v10, 16, v204
	v_add_u32_e32 v11, 64, v11
	v_cmp_lt_i32_e32 vcc, v10, v11
	v_xor_b32_e32 v12, 32, v204
	s_nop 0
	v_cndmask_b32_e32 v10, v204, v10, vcc
	v_lshlrev_b32_e32 v10, 2, v10
	ds_bpermute_b32 v10, v10, v0
	v_max_f32_e32 v0, v0, v0
	v_cmp_lt_i32_e32 vcc, v12, v11
	s_waitcnt lgkmcnt(0)
	v_max_f32_e32 v10, v10, v10
	v_max_f32_e32 v0, v0, v10
	v_cndmask_b32_e32 v10, v204, v12, vcc
	v_lshlrev_b32_e32 v10, 2, v10
	ds_bpermute_b32 v10, v10, v0
	s_waitcnt lgkmcnt(0)
	v_max3_f32 v10, v210, v0, v10
	v_sub_f32_e32 v0, v210, v10
	v_exp_f32_e32 v0, v0
	v_mov_b32_e32 v210, v10
	v_mul_f32_e32 v209, v209, v0
	v_pk_mul_f32 v[36:37], v[36:37], v[0:1] op_sel_hi:[1,0]
	v_pk_mul_f32 v[34:35], v[34:35], v[0:1] op_sel_hi:[1,0]
	v_pk_mul_f32 v[40:41], v[40:41], v[0:1] op_sel_hi:[1,0]
	v_pk_mul_f32 v[38:39], v[38:39], v[0:1] op_sel_hi:[1,0]
	v_pk_mul_f32 v[44:45], v[44:45], v[0:1] op_sel_hi:[1,0]
	v_pk_mul_f32 v[42:43], v[42:43], v[0:1] op_sel_hi:[1,0]
	v_pk_mul_f32 v[56:57], v[56:57], v[0:1] op_sel_hi:[1,0]
	v_pk_mul_f32 v[54:55], v[54:55], v[0:1] op_sel_hi:[1,0]
	v_pk_mul_f32 v[64:65], v[64:65], v[0:1] op_sel_hi:[1,0]
	v_pk_mul_f32 v[62:63], v[62:63], v[0:1] op_sel_hi:[1,0]
	v_pk_mul_f32 v[60:61], v[60:61], v[0:1] op_sel_hi:[1,0]
	v_pk_mul_f32 v[58:59], v[58:59], v[0:1] op_sel_hi:[1,0]
	v_pk_mul_f32 v[52:53], v[52:53], v[0:1] op_sel_hi:[1,0]
	v_pk_mul_f32 v[50:51], v[50:51], v[0:1] op_sel_hi:[1,0]
	v_pk_mul_f32 v[48:49], v[48:49], v[0:1] op_sel_hi:[1,0]
	v_pk_mul_f32 v[46:47], v[46:47], v[0:1] op_sel_hi:[1,0]
.LBB0_709:
	v_add_f32_e32 v0, -4.0, v210
	v_sub_f32_e32 v2, v2, v0
	v_exp_f32_e32 v2, v2
	v_sub_f32_e32 v6, v6, v0
	v_exp_f32_e32 v6, v6
	v_sub_f32_e32 v4, v4, v0
	v_cndmask_b32_e64 v22, 0, v2, s[10:11]
	v_sub_f32_e32 v2, v3, v0
	v_exp_f32_e32 v2, v2
	v_sub_f32_e32 v3, v7, v0
	v_exp_f32_e32 v3, v3
	v_cndmask_b32_e64 v23, 0, v6, s[18:19]
	v_sub_f32_e32 v6, v8, v0
	v_cndmask_b32_e64 v24, 0, v2, s[6:7]
	v_sub_f32_e32 v2, v5, v0
	v_sub_f32_e32 v0, v9, v0
	v_exp_f32_e32 v4, v4
	v_exp_f32_e32 v6, v6
	v_cndmask_b32_e64 v25, 0, v3, s[14:15]
	v_exp_f32_e32 v2, v2
	v_exp_f32_e32 v0, v0
	v_mov_b32_e32 v26, v1
	v_mov_b32_e32 v27, v1
	v_cvt_pk_fp8_f32 v26, v22, v24
	v_cvt_pk_fp8_f32 v27, v23, v25
	v_cndmask_b32_e64 v28, 0, v4, s[8:9]
	v_cndmask_b32_e64 v29, 0, v6, s[16:17]
	v_cndmask_b32_e64 v66, 0, v2, s[4:5]
	v_cndmask_b32_e64 v0, 0, v0, s[12:13]
	v_cvt_pk_fp8_f32 v26, v28, v66 op_sel:[0,0,1]
	v_cvt_pk_fp8_f32 v27, v29, v0 op_sel:[0,0,1]
	v_add_f32_e32 v22, v22, v23
	v_add_f32_e32 v30, 0, v22
	v_add_f32_e32 v31, v24, v25
	v_add_f32_e32 v30, v31, v30
	v_add_f32_e32 v28, v28, v29
	v_add_f32_e32 v28, v28, v30
	v_add_f32_e32 v0, v66, v0
	s_waitcnt vmcnt(19)
	v_mfma_f32_16x16x32_fp8_fp8 v[2:5], v[86:87], v[26:27], v[34:37]
	v_add_f32_e32 v0, v0, v28
	v_add_f32_e32 v208, v209, v0
	v_mov_b32_e32 v207, v210
	v_mfma_f32_16x16x32_fp8_fp8 v[6:9], v[88:89], v[26:27], v[38:41]
	s_waitcnt vmcnt(18)
	v_mfma_f32_16x16x32_fp8_fp8 v[10:13], v[90:91], v[26:27], v[42:45]
	v_mfma_f32_16x16x32_fp8_fp8 v[14:17], v[92:93], v[26:27], v[54:57]
	s_waitcnt vmcnt(17)
	v_mfma_f32_16x16x32_fp8_fp8 v[18:21], v[94:95], v[26:27], v[62:65]
	v_mfma_f32_16x16x32_fp8_fp8 v[22:25], v[96:97], v[26:27], v[58:61]
	s_waitcnt vmcnt(16)
	v_mfma_f32_16x16x32_fp8_fp8 v[30:33], v[112:113], v[26:27], v[50:53]
	v_mfma_f32_16x16x32_fp8_fp8 v[26:29], v[114:115], v[26:27], v[46:49]
	s_cmp_ge_i32 s66, s74
	s_mov_b64 s[4:5], -1
	s_cbranch_scc0 .LBB0_701

; template <bool SLC, bool NOMASK> ...
;     ...
;     load_frag8(nxt, KF, VF, SLC ? (dnext & 0xfffff) : dnext, lane);
;     f32x4 sa[2] = {(f32x4){0.f, 0.f, 0.f, 0.f}, (f32x4){0.f, 0.f, 0.f, 0.f}};
; #pragma unroll
;     for (int T = 0; T < 2; ++T)
; #pragma unroll
;         for (int s2 = 0; s2 < 4; ++s2) sa[T] = __builtin_amdgcn_mfma_f32_16x16x32_fp8_fp8(cur.k[T][s2], qf[s2], sa[T], 0, 0, 0);
;     float sc[8]; bool vd[8]; float mx = -1e30f;
;     const bool act = lo == 0 || !SLC;
;     if (NOMASK) {
; #pragma unroll
;         for (int j = 0; j < 8; ++j) { sc[j] = sa[j >> 2][j & 3]; vd[j] = act; }
;         mx = fmaxf(fmaxf(fmaxf(sc[0], sc[1]), fmaxf(sc[2], sc[3])), fmaxf(fmaxf(sc[4], sc[5]), fmaxf(sc[6], sc[7])));
;         mx = act ? mx : -1e30f;
;     } else {
; #pragma unroll
;         for (int T = 0; T < 2; ++T)
; #pragma unroll
;             for (int r = 0; r < 4; ++r) { const int p = pos0 + 16 * T + 4 * kq + r; const bool v = (p >= lo) & (p <= hi); const float x = sa[T][r];
;                 sc[4 * T + r] = x; vd[4 * T + r] = v; mx = v ? fmaxf(mx, x) : mx; }
;     }
;     if (__builtin_amdgcn_ballot_w64(mx > st.m + 4.f) != 0ull) {
;         mx = fmaxf(mx, __shfl_xor(mx, 16)); mx = fmaxf(mx, __shfl_xor(mx, 32));
;         const float mn = fmaxf(st.m, mx), alpha = __builtin_amdgcn_exp2f(st.m - mn); st.m = mn; st.l *= alpha;
; #pragma unroll
;         for (int j = 0; j < 8; ++j) st.o[j] = st.o[j] * alpha;
;     }
;     f32x4 pa, pb; float ps = 0.f;
;     const float mref = st.m - 4.f;
;     if (NOMASK) {
; #pragma unroll
;         for (int j = 0; j < 4; ++j) { pa[j] = __builtin_amdgcn_exp2f(sc[j] - mref); pb[j] = __builtin_amdgcn_exp2f(sc[4 + j] - mref); }
;         if (SLC) {
; #pragma unroll
;             for (int j = 0; j < 4; ++j) { pa[j] = act ? pa[j] : 0.f; pb[j] = act ? pb[j] : 0.f; }
;         }
; #pragma unroll
;         for (int j = 0; j < 4; ++j) ps += pa[j] + pb[j];
;     } else {
; #pragma unroll
;         for (int j = 0; j < 4; ++j) { pa[j] = vd[j] ? __builtin_amdgcn_exp2f(sc[j] - mref) : 0.f; pb[j] = vd[4 + j] ? __builtin_amdgcn_exp2f(sc[4 + j] - mref) : 0.f; ps += pa[j] + pb[j]; }
;     }
;     st.l += ps;
;     const u32x2 pw = pack8_fp8(pa, pb);
;     const i64_t pf = __builtin_bit_cast(i64_t, pw);
; #pragma unroll
;     for (int db = 0; db < 8; ++db) st.o[db] = __builtin_amdgcn_mfma_f32_16x16x32_fp8_fp8(cur.v[db], pf, st.o[db], 0, 0, 0);
.LBB0_711:
	v_lshl_add_u64 v[244:245], v[198:199], 0, v[98:99]
	global_load_dwordx4 v[132:135], v[244:245], off
	global_load_dwordx4 v[136:139], v[244:245], off offset:1024
	global_load_dwordx4 v[140:143], v[244:245], off offset:2048
	global_load_dwordx4 v[144:147], v[244:245], off offset:3072
	v_lshl_add_u64 v[246:247], v[196:197], 0, v[98:99]
	global_load_dwordx4 v[86:89], v[246:247], off
	global_load_dwordx4 v[90:93], v[246:247], off offset:1024
	global_load_dwordx4 v[94:97], v[246:247], off offset:2048
	global_load_dwordx4 v[112:115], v[246:247], off offset:3072
	s_waitcnt vmcnt(20)
	v_mfma_f32_16x16x32_fp8_fp8 v[34:37], v[148:149], v[74:75], 0
	v_mov_b64_e32 v[72:73], v[28:29]
	v_mov_b64_e32 v[68:69], v[32:33]
	v_mov_b64_e32 v[64:65], v[24:25]
	v_mfma_f32_16x16x32_fp8_fp8 v[38:41], v[156:157], v[74:75], 0
	v_mov_b64_e32 v[60:61], v[20:21]
	v_mov_b64_e32 v[56:57], v[16:17]
	v_mov_b64_e32 v[52:53], v[12:13]
	v_mfma_f32_16x16x32_fp8_fp8 v[34:37], v[150:151], v[76:77], v[34:37]
	v_mov_b64_e32 v[48:49], v[8:9]
	v_mov_b32_e32 v209, v207
	v_mov_b64_e32 v[70:71], v[26:27]
	v_mfma_f32_16x16x32_fp8_fp8 v[38:41], v[158:159], v[76:77], v[38:41]
	v_mov_b64_e32 v[66:67], v[30:31]
	v_mov_b64_e32 v[62:63], v[22:23]
	v_mov_b64_e32 v[58:59], v[18:19]
	v_mfma_f32_16x16x32_fp8_fp8 v[34:37], v[152:153], v[78:79], v[34:37]
	v_mov_b64_e32 v[54:55], v[14:15]
	v_mov_b64_e32 v[50:51], v[10:11]
	v_mov_b64_e32 v[46:47], v[6:7]
	v_mfma_f32_16x16x32_fp8_fp8 v[38:41], v[160:161], v[78:79], v[38:41]
	v_mov_b32_e32 v210, v208
	v_mfma_f32_16x16x32_fp8_fp8 v[34:37], v[154:155], v[80:81], v[34:37]
	v_mfma_f32_16x16x32_fp8_fp8 v[38:41], v[162:163], v[80:81], v[38:41]
	s_nop 5
	v_max_f32_e32 v0, v35, v35
	v_max_f32_e32 v42, v34, v34
	v_max_f32_e32 v0, v42, v0
	v_max_f32_e32 v42, v37, v37
	v_max_f32_e32 v43, v36, v36
	v_max_f32_e32 v42, v43, v42
	v_max_f32_e32 v43, v41, v41
	v_max_f32_e32 v44, v40, v40
	v_max_f32_e32 v43, v44, v43
	v_max3_f32 v43, v38, v39, v43
	v_max3_f32 v0, v0, v42, v43
	v_mov_b64_e32 v[44:45], v[4:5]
	v_cmp_gt_f32_e32 vcc, v0, v211
	v_mov_b64_e32 v[42:43], v[2:3]
	s_cbranch_vccz .LBB0_713
	v_and_b32_e32 v43, 64, v204
	v_xor_b32_e32 v42, 16, v204
	v_add_u32_e32 v43, 64, v43
	v_cmp_lt_i32_e32 vcc, v42, v43
	v_xor_b32_e32 v44, 32, v204
	s_nop 0
	v_cndmask_b32_e32 v42, v204, v42, vcc
	v_lshlrev_b32_e32 v42, 2, v42
	ds_bpermute_b32 v42, v42, v0
	v_max_f32_e32 v0, v0, v0
	v_cmp_lt_i32_e32 vcc, v44, v43
	s_waitcnt lgkmcnt(0)
	v_max_f32_e32 v42, v42, v42
	v_max_f32_e32 v0, v0, v42
	v_cndmask_b32_e32 v42, v204, v44, vcc
	v_lshlrev_b32_e32 v42, 2, v42
	ds_bpermute_b32 v42, v42, v0
	s_waitcnt lgkmcnt(0)
	v_max3_f32 v209, v207, v0, v42
	v_sub_f32_e32 v0, v207, v209
	v_exp_f32_e32 v0, v0
	s_nop 0
	v_mul_f32_e32 v210, v208, v0
	v_pk_mul_f32 v[44:45], v[4:5], v[0:1] op_sel_hi:[1,0]
	v_pk_mul_f32 v[42:43], v[2:3], v[0:1] op_sel_hi:[1,0]
	v_pk_mul_f32 v[48:49], v[8:9], v[0:1] op_sel_hi:[1,0]
	v_pk_mul_f32 v[46:47], v[6:7], v[0:1] op_sel_hi:[1,0]
	v_pk_mul_f32 v[52:53], v[12:13], v[0:1] op_sel_hi:[1,0]
	v_pk_mul_f32 v[50:51], v[10:11], v[0:1] op_sel_hi:[1,0]
	v_pk_mul_f32 v[56:57], v[16:17], v[0:1] op_sel_hi:[1,0]
	v_pk_mul_f32 v[54:55], v[14:15], v[0:1] op_sel_hi:[1,0]
	v_pk_mul_f32 v[60:61], v[20:21], v[0:1] op_sel_hi:[1,0]
	v_pk_mul_f32 v[58:59], v[18:19], v[0:1] op_sel_hi:[1,0]
	v_pk_mul_f32 v[64:65], v[24:25], v[0:1] op_sel_hi:[1,0]
	v_pk_mul_f32 v[62:63], v[22:23], v[0:1] op_sel_hi:[1,0]
	v_pk_mul_f32 v[68:69], v[32:33], v[0:1] op_sel_hi:[1,0]
	v_pk_mul_f32 v[66:67], v[30:31], v[0:1] op_sel_hi:[1,0]
	v_pk_mul_f32 v[72:73], v[28:29], v[0:1] op_sel_hi:[1,0]
	v_pk_mul_f32 v[70:71], v[26:27], v[0:1] op_sel_hi:[1,0]
.LBB0_713:
	v_add_f32_e32 v213, -4.0, v209
	v_sub_f32_e32 v0, v34, v213
	v_exp_f32_e32 v215, v0
	v_sub_f32_e32 v0, v38, v213
	v_exp_f32_e32 v217, v0
	v_sub_f32_e32 v0, v35, v213
	v_exp_f32_e32 v212, v0
	v_sub_f32_e32 v0, v39, v213
	v_exp_f32_e32 v0, v0
	v_sub_f32_e32 v34, v36, v213
	v_exp_f32_e32 v220, v34
	v_sub_f32_e32 v34, v40, v213
	v_exp_f32_e32 v221, v34
	v_sub_f32_e32 v34, v37, v213
	v_exp_f32_e32 v214, v34
	v_sub_f32_e32 v34, v41, v213
	v_mov_b32_e32 v218, v1
	v_mov_b32_e32 v219, v1
	v_exp_f32_e32 v216, v34
	v_cvt_pk_fp8_f32 v218, v215, v212
	v_cvt_pk_fp8_f32 v219, v217, v0
	v_add_f32_e32 v213, v215, v217
	v_add_f32_e32 v215, v220, v221
	v_cvt_pk_fp8_f32 v218, v220, v214 op_sel:[0,0,1]
	v_cvt_pk_fp8_f32 v219, v221, v216 op_sel:[0,0,1]
	s_nop 0
	s_waitcnt vmcnt(19)
	v_mfma_f32_16x16x32_fp8_fp8 v[34:37], v[116:117], v[218:219], v[42:45]
	v_mfma_f32_16x16x32_fp8_fp8 v[42:45], v[120:121], v[218:219], v[50:53]
	s_waitcnt vmcnt(18)
	v_mfma_f32_16x16x32_fp8_fp8 v[50:53], v[124:125], v[218:219], v[58:61]
	s_nop 2
	v_add_f32_e64 v58, v212, v0
	v_add_f32_e64 v59, v213, v1
	v_mfma_f32_16x16x32_fp8_fp8 v[38:41], v[118:119], v[218:219], v[46:49]
	v_pk_add_f32 v[58:59], v[58:59], v[58:59] op_sel_hi:[0,1]
	v_mov_b32_e32 v217, v59
	s_waitcnt vmcnt(17)
	v_mfma_f32_16x16x32_fp8_fp8 v[46:49], v[122:123], v[218:219], v[54:57]
	v_mfma_f32_16x16x32_fp8_fp8 v[54:57], v[126:127], v[218:219], v[62:65]
	s_nop 2
	v_add_f32_e64 v62, v214, v216
	v_add_f32_e64 v63, v215, v217
	s_waitcnt vmcnt(16)
	v_mfma_f32_16x16x32_fp8_fp8 v[58:61], v[128:129], v[218:219], v[66:69]
	v_add_f32_e32 v0, v62, v63
	v_add_f32_e32 v210, v0, v210
	v_mfma_f32_16x16x32_fp8_fp8 v[62:65], v[130:131], v[218:219], v[70:73]
	s_branch .LBB0_703
; template <bool SLC, bool NOMASK> ...
;     ...
;     load_frag8(nxt, KF, VF, SLC ? (dnext & 0xfffff) : dnext, lane);
;     f32x4 sa[2] = {(f32x4){0.f, 0.f, 0.f, 0.f}, (f32x4){0.f, 0.f, 0.f, 0.f}};
; #pragma unroll
;     for (int T = 0; T < 2; ++T)
; #pragma unroll
;         for (int s2 = 0; s2 < 4; ++s2) sa[T] = __builtin_amdgcn_mfma_f32_16x16x32_fp8_fp8(cur.k[T][s2], qf[s2], sa[T], 0, 0, 0);
;     float sc[8]; bool vd[8]; float mx = -1e30f;
;     const bool act = lo == 0 || !SLC;
;     if (NOMASK) {
; #pragma unroll
;         for (int j = 0; j < 8; ++j) { sc[j] = sa[j >> 2][j & 3]; vd[j] = act; }
;         mx = fmaxf(fmaxf(fmaxf(sc[0], sc[1]), fmaxf(sc[2], sc[3])), fmaxf(fmaxf(sc[4], sc[5]), fmaxf(sc[6], sc[7])));
;         mx = act ? mx : -1e30f;
;     } else {
; #pragma unroll
;         for (int T = 0; T < 2; ++T)
; #pragma unroll
;             for (int r = 0; r < 4; ++r) { const int p = pos0 + 16 * T + 4 * kq + r; const bool v = (p >= lo) & (p <= hi); const float x = sa[T][r];
;                 sc[4 * T + r] = x; vd[4 * T + r] = v; mx = v ? fmaxf(mx, x) : mx; }
;     }
;     if (__builtin_amdgcn_ballot_w64(mx > st.m + 4.f) != 0ull) {
;         mx = fmaxf(mx, __shfl_xor(mx, 16)); mx = fmaxf(mx, __shfl_xor(mx, 32));
;         const float mn = fmaxf(st.m, mx), alpha = __builtin_amdgcn_exp2f(st.m - mn); st.m = mn; st.l *= alpha;
; #pragma unroll
;         for (int j = 0; j < 8; ++j) st.o[j] = st.o[j] * alpha;
;     }
.LBB0_714:
	v_lshl_add_u64 v[244:245], v[198:199], 0, v[98:99]
	global_load_dwordx4 v[132:135], v[244:245], off
	global_load_dwordx4 v[136:139], v[244:245], off offset:1024
	global_load_dwordx4 v[140:143], v[244:245], off offset:2048
	global_load_dwordx4 v[144:147], v[244:245], off offset:3072
	v_lshl_add_u64 v[246:247], v[196:197], 0, v[98:99]
	global_load_dwordx4 v[86:89], v[246:247], off
	global_load_dwordx4 v[90:93], v[246:247], off offset:1024
	global_load_dwordx4 v[94:97], v[246:247], off offset:2048
	global_load_dwordx4 v[112:115], v[246:247], off offset:3072
	s_waitcnt vmcnt(20)
	v_mfma_f32_16x16x32_fp8_fp8 v[34:37], v[148:149], v[74:75], 0
	v_or_b32_e32 v0, s76, v203
	v_cmp_ge_i32_e32 vcc, v0, v105
	v_cmp_le_i32_e64 s[4:5], v0, v206
	v_mfma_f32_16x16x32_fp8_fp8 v[34:37], v[150:151], v[76:77], v[34:37]
	s_and_b64 s[10:11], vcc, s[4:5]
	v_or_b32_e32 v43, 1, v0
	v_cmp_ge_i32_e32 vcc, v43, v105
	v_mfma_f32_16x16x32_fp8_fp8 v[34:37], v[152:153], v[78:79], v[34:37]
	v_cmp_lt_i32_e64 s[4:5], v0, v206
	s_and_b64 s[6:7], s[4:5], vcc
	v_mfma_f32_16x16x32_fp8_fp8 v[38:41], v[156:157], v[74:75], 0
	v_mfma_f32_16x16x32_fp8_fp8 v[34:37], v[154:155], v[80:81], v[34:37]
	v_mfma_f32_16x16x32_fp8_fp8 v[38:41], v[158:159], v[76:77], v[38:41]
	v_mfma_f32_16x16x32_fp8_fp8 v[38:41], v[160:161], v[78:79], v[38:41]
	s_nop 3
	v_max_f32_e32 v42, v34, v34
	v_max_f32_e32 v42, 0xf149f2ca, v42
	v_cndmask_b32_e64 v42, v205, v42, s[10:11]
	v_max_f32_e32 v43, v35, v35
	v_max_f32_e32 v43, v42, v43
	v_cndmask_b32_e64 v42, v42, v43, s[6:7]
	v_or_b32_e32 v43, 2, v0
	v_cmp_ge_i32_e32 vcc, v43, v105
	v_cmp_le_i32_e64 s[4:5], v43, v206
	v_max_f32_e32 v43, v36, v36
	v_max_f32_e32 v43, v42, v43
	s_and_b64 s[8:9], vcc, s[4:5]
	v_mfma_f32_16x16x32_fp8_fp8 v[38:41], v[162:163], v[80:81], v[38:41]
	v_cndmask_b32_e64 v42, v42, v43, s[8:9]
	v_or_b32_e32 v43, 3, v0
	v_cmp_ge_i32_e32 vcc, v43, v105
	v_cmp_le_i32_e64 s[4:5], v43, v206
	v_max_f32_e32 v43, v37, v37
	v_max_f32_e32 v43, v42, v43
	s_and_b64 s[4:5], vcc, s[4:5]
	v_cndmask_b32_e64 v42, v42, v43, s[4:5]
	v_or_b32_e32 v43, 16, v0
	v_cmp_ge_i32_e32 vcc, v43, v105
	v_cmp_le_i32_e64 s[12:13], v43, v206
	v_max_f32_e32 v43, v38, v38
	v_max_f32_e32 v43, v42, v43
	s_and_b64 s[18:19], vcc, s[12:13]
	v_cndmask_b32_e64 v42, v42, v43, s[18:19]
	v_or_b32_e32 v43, 17, v0
	v_cmp_ge_i32_e32 vcc, v43, v105
	v_cmp_le_i32_e64 s[12:13], v43, v206
	v_max_f32_e32 v43, v42, v42
	v_max_f32_e32 v44, v39, v39
	v_max_f32_e32 v43, v43, v44
	s_and_b64 s[14:15], vcc, s[12:13]
	v_cndmask_b32_e64 v42, v42, v43, s[14:15]
	v_or_b32_e32 v43, 18, v0
	v_cmp_ge_i32_e32 vcc, v43, v105
	v_cmp_le_i32_e64 s[12:13], v43, v206
	v_max_f32_e32 v43, v42, v42
	v_max_f32_e32 v44, v40, v40
	v_max_f32_e32 v43, v43, v44
	s_and_b64 s[16:17], vcc, s[12:13]
	v_cndmask_b32_e64 v42, v42, v43, s[16:17]
	v_or_b32_e32 v0, 19, v0
	v_cmp_ge_i32_e32 vcc, v0, v105
	v_cmp_le_i32_e64 s[12:13], v0, v206
	v_max_f32_e32 v0, v42, v42
	v_max_f32_e32 v43, v41, v41
	v_max_f32_e32 v0, v0, v43
	s_and_b64 s[12:13], vcc, s[12:13]
	v_cndmask_b32_e64 v0, v42, v0, s[12:13]
	v_cmp_gt_f32_e32 vcc, v0, v211
	s_cbranch_vccz .LBB0_716
	v_and_b32_e32 v43, 64, v204
	v_xor_b32_e32 v42, 16, v204
	v_add_u32_e32 v43, 64, v43
	v_cmp_lt_i32_e32 vcc, v42, v43
	v_xor_b32_e32 v44, 32, v204
	s_nop 0
	v_cndmask_b32_e32 v42, v204, v42, vcc
	v_lshlrev_b32_e32 v42, 2, v42
	ds_bpermute_b32 v42, v42, v0
	v_max_f32_e32 v0, v0, v0
	v_cmp_lt_i32_e32 vcc, v44, v43
	s_waitcnt lgkmcnt(0)
	v_max_f32_e32 v42, v42, v42
	v_max_f32_e32 v0, v0, v42
	v_cndmask_b32_e32 v42, v204, v44, vcc
	v_lshlrev_b32_e32 v42, 2, v42
	ds_bpermute_b32 v42, v42, v0
	s_waitcnt lgkmcnt(0)
	v_max3_f32 v42, v207, v0, v42
	v_sub_f32_e32 v0, v207, v42
	v_exp_f32_e32 v0, v0
	v_mov_b32_e32 v207, v42
	v_mul_f32_e32 v208, v208, v0
	v_pk_mul_f32 v[4:5], v[4:5], v[0:1] op_sel_hi:[1,0]
	v_pk_mul_f32 v[2:3], v[2:3], v[0:1] op_sel_hi:[1,0]
	v_pk_mul_f32 v[8:9], v[8:9], v[0:1] op_sel_hi:[1,0]
	v_pk_mul_f32 v[6:7], v[6:7], v[0:1] op_sel_hi:[1,0]
	v_pk_mul_f32 v[12:13], v[12:13], v[0:1] op_sel_hi:[1,0]
	v_pk_mul_f32 v[10:11], v[10:11], v[0:1] op_sel_hi:[1,0]
	v_pk_mul_f32 v[16:17], v[16:17], v[0:1] op_sel_hi:[1,0]
	v_pk_mul_f32 v[14:15], v[14:15], v[0:1] op_sel_hi:[1,0]
	v_pk_mul_f32 v[20:21], v[20:21], v[0:1] op_sel_hi:[1,0]
	v_pk_mul_f32 v[18:19], v[18:19], v[0:1] op_sel_hi:[1,0]
	v_pk_mul_f32 v[24:25], v[24:25], v[0:1] op_sel_hi:[1,0]
	v_pk_mul_f32 v[22:23], v[22:23], v[0:1] op_sel_hi:[1,0]
	v_pk_mul_f32 v[32:33], v[32:33], v[0:1] op_sel_hi:[1,0]
	v_pk_mul_f32 v[30:31], v[30:31], v[0:1] op_sel_hi:[1,0]
	v_pk_mul_f32 v[28:29], v[28:29], v[0:1] op_sel_hi:[1,0]
	v_pk_mul_f32 v[26:27], v[26:27], v[0:1] op_sel_hi:[1,0]
; template <bool SLC, bool NOMASK> ...
;     ...
;     load_frag8(nxt, KF, VF, SLC ? (dnext & 0xfffff) : dnext, lane);
;     f32x4 sa[2] = {(f32x4){0.f, 0.f, 0.f, 0.f}, (f32x4){0.f, 0.f, 0.f, 0.f}};
; #pragma unroll
;     for (int T = 0; T < 2; ++T)
; #pragma unroll
;         for (int s2 = 0; s2 < 4; ++s2) sa[T] = __builtin_amdgcn_mfma_f32_16x16x32_fp8_fp8(cur.k[T][s2], qf[s2], sa[T], 0, 0, 0);
;     float sc[8]; bool vd[8]; float mx = -1e30f;
;     const bool act = lo == 0 || !SLC;
;     if (NOMASK) {
; #pragma unroll
;         for (int j = 0; j < 8; ++j) { sc[j] = sa[j >> 2][j & 3]; vd[j] = act; }
;         mx = fmaxf(fmaxf(fmaxf(sc[0], sc[1]), fmaxf(sc[2], sc[3])), fmaxf(fmaxf(sc[4], sc[5]), fmaxf(sc[6], sc[7])));
;         mx = act ? mx : -1e30f;
;     } else {
; #pragma unroll
;         for (int T = 0; T < 2; ++T)
; #pragma unroll
;             for (int r = 0; r < 4; ++r) { const int p = pos0 + 16 * T + 4 * kq + r; const bool v = (p >= lo) & (p <= hi); const float x = sa[T][r];
;                 sc[4 * T + r] = x; vd[4 * T + r] = v; mx = v ? fmaxf(mx, x) : mx; }
;     }
;     if (__builtin_amdgcn_ballot_w64(mx > st.m + 4.f) != 0ull) {
;         mx = fmaxf(mx, __shfl_xor(mx, 16)); mx = fmaxf(mx, __shfl_xor(mx, 32));
;         const float mn = fmaxf(st.m, mx), alpha = __builtin_amdgcn_exp2f(st.m - mn); st.m = mn; st.l *= alpha;
; #pragma unroll
;         for (int j = 0; j < 8; ++j) st.o[j] = st.o[j] * alpha;
;     }
;     f32x4 pa, pb; float ps = 0.f;
;     const float mref = st.m - 4.f;
;     if (NOMASK) {
; #pragma unroll
;         for (int j = 0; j < 4; ++j) { pa[j] = __builtin_amdgcn_exp2f(sc[j] - mref); pb[j] = __builtin_amdgcn_exp2f(sc[4 + j] - mref); }
;         if (SLC) {
; #pragma unroll
;             for (int j = 0; j < 4; ++j) { pa[j] = act ? pa[j] : 0.f; pb[j] = act ? pb[j] : 0.f; }
;         }
; #pragma unroll
;         for (int j = 0; j < 4; ++j) ps += pa[j] + pb[j];
;     } else {
; #pragma unroll
;         for (int j = 0; j < 4; ++j) { pa[j] = vd[j] ? __builtin_amdgcn_exp2f(sc[j] - mref) : 0.f; pb[j] = vd[4 + j] ? __builtin_amdgcn_exp2f(sc[4 + j] - mref) : 0.f; ps += pa[j] + pb[j]; }
;     }
;     st.l += ps;
;     const u32x2 pw = pack8_fp8(pa, pb);
;     const i64_t pf = __builtin_bit_cast(i64_t, pw);
; #pragma unroll
;     for (int db = 0; db < 8; ++db) st.o[db] = __builtin_amdgcn_mfma_f32_16x16x32_fp8_fp8(cur.v[db], pf, st.o[db], 0, 0, 0);
.LBB0_716:
	v_add_f32_e32 v0, -4.0, v207
	v_sub_f32_e32 v34, v34, v0
	v_exp_f32_e32 v34, v34
	v_sub_f32_e32 v38, v38, v0
	v_exp_f32_e32 v38, v38
	v_sub_f32_e32 v36, v36, v0
	v_cndmask_b32_e64 v54, 0, v34, s[10:11]
	v_sub_f32_e32 v34, v35, v0
	v_exp_f32_e32 v34, v34
	v_sub_f32_e32 v35, v39, v0
	v_exp_f32_e32 v35, v35
	v_cndmask_b32_e64 v55, 0, v38, s[18:19]
	v_sub_f32_e32 v38, v40, v0
	v_cndmask_b32_e64 v56, 0, v34, s[6:7]
	v_sub_f32_e32 v34, v37, v0
	v_sub_f32_e32 v0, v41, v0
	v_exp_f32_e32 v36, v36
	v_exp_f32_e32 v38, v38
	v_cndmask_b32_e64 v57, 0, v35, s[14:15]
	v_exp_f32_e32 v34, v34
	v_exp_f32_e32 v0, v0
	v_mov_b32_e32 v62, v1
	v_mov_b32_e32 v63, v1
	v_cvt_pk_fp8_f32 v62, v54, v56
	v_cvt_pk_fp8_f32 v63, v55, v57
	v_cndmask_b32_e64 v58, 0, v36, s[8:9]
	v_cndmask_b32_e64 v59, 0, v38, s[16:17]
	v_cndmask_b32_e64 v64, 0, v34, s[4:5]
	v_cndmask_b32_e64 v0, 0, v0, s[12:13]
	v_cvt_pk_fp8_f32 v62, v58, v64 op_sel:[0,0,1]
	v_cvt_pk_fp8_f32 v63, v59, v0 op_sel:[0,0,1]
	v_add_f32_e32 v0, v64, v0
	v_mov_b32_e32 v209, v207
	s_waitcnt vmcnt(19)
	v_mfma_f32_16x16x32_fp8_fp8 v[34:37], v[116:117], v[62:63], v[2:5]
	s_nop 2
	v_add_f32_e32 v2, v54, v55
	v_add_f32_e32 v2, 0, v2
	v_add_f32_e32 v3, v56, v57
	v_mfma_f32_16x16x32_fp8_fp8 v[38:41], v[118:119], v[62:63], v[6:9]
	v_add_f32_e32 v2, v3, v2
	v_add_f32_e32 v3, v58, v59
	v_add_f32_e32 v2, v3, v2
	s_waitcnt vmcnt(18)
	v_mfma_f32_16x16x32_fp8_fp8 v[42:45], v[120:121], v[62:63], v[10:13]
	v_add_f32_e32 v0, v0, v2
	v_add_f32_e32 v210, v208, v0
	v_mfma_f32_16x16x32_fp8_fp8 v[46:49], v[122:123], v[62:63], v[14:17]
	s_waitcnt vmcnt(17)
	v_mfma_f32_16x16x32_fp8_fp8 v[50:53], v[124:125], v[62:63], v[18:21]
	v_mfma_f32_16x16x32_fp8_fp8 v[54:57], v[126:127], v[62:63], v[22:25]
	s_waitcnt vmcnt(16)
	v_mfma_f32_16x16x32_fp8_fp8 v[58:61], v[128:129], v[62:63], v[30:33]
	v_mfma_f32_16x16x32_fp8_fp8 v[62:65], v[130:131], v[62:63], v[26:29]
	s_cmp_gt_i32 s77, s74
	s_mov_b64 s[4:5], -1
	s_cbranch_scc1 .LBB0_696
.LBB0_717:
	s_add_i32 s66, s66, 4
	s_min_i32 s4, s66, s74
	s_add_i32 s6, s4, s73
	s_lshl_b32 s76, s6, 5
	s_and_b32 s4, s76, 0x3fffffe0
	s_lshr_b32 s26, s4, 4
	s_lshl_b64 s[4:5], s[26:27], 11
	s_and_b32 s26, s6, 0x1ffffff
	s_and_b32 s8, s42, 0x2000000
	s_lshl_b64 s[6:7], s[26:27], 12
	s_cmp_eq_u32 s8, 0
	v_lshl_add_u64 v[198:199], v[82:83], 0, s[4:5]
	v_lshl_add_u64 v[196:197], v[84:85], 0, s[6:7]
	s_mov_b64 s[4:5], -1
	v_add_f32_e32 v211, 4.0, v209
	s_cbranch_scc1 .LBB0_721
	v_lshl_add_u64 v[244:245], v[198:199], 0, v[98:99]
	global_load_dwordx4 v[148:151], v[244:245], off
	global_load_dwordx4 v[152:155], v[244:245], off offset:1024
	global_load_dwordx4 v[156:159], v[244:245], off offset:2048
	global_load_dwordx4 v[160:163], v[244:245], off offset:3072
	v_lshl_add_u64 v[246:247], v[196:197], 0, v[98:99]
	global_load_dwordx4 v[116:119], v[246:247], off
	global_load_dwordx4 v[120:123], v[246:247], off offset:1024
	global_load_dwordx4 v[124:127], v[246:247], off offset:2048
	global_load_dwordx4 v[128:131], v[246:247], off offset:3072
	s_waitcnt vmcnt(20)
	v_mfma_f32_16x16x32_fp8_fp8 v[2:5], v[180:181], v[74:75], 0
	v_mov_b64_e32 v[72:73], v[64:65]
	v_mov_b64_e32 v[68:69], v[60:61]
	v_mov_b64_e32 v[30:31], v[54:55]
	v_mfma_f32_16x16x32_fp8_fp8 v[6:9], v[188:189], v[74:75], 0
	v_mov_b64_e32 v[26:27], v[50:51]
	v_mov_b64_e32 v[22:23], v[46:47]
	v_mov_b64_e32 v[18:19], v[42:43]
	v_mfma_f32_16x16x32_fp8_fp8 v[2:5], v[182:183], v[76:77], v[2:5]
	v_mov_b64_e32 v[14:15], v[38:39]
	v_mov_b32_e32 v207, v209
	v_mov_b64_e32 v[70:71], v[62:63]
	v_mfma_f32_16x16x32_fp8_fp8 v[6:9], v[190:191], v[76:77], v[6:9]
	v_mov_b64_e32 v[66:67], v[58:59]
	v_mov_b64_e32 v[32:33], v[56:57]
	v_mov_b64_e32 v[28:29], v[52:53]
	v_mfma_f32_16x16x32_fp8_fp8 v[2:5], v[184:185], v[78:79], v[2:5]
	v_mov_b64_e32 v[24:25], v[48:49]
	v_mov_b64_e32 v[20:21], v[44:45]
	v_mov_b64_e32 v[16:17], v[40:41]
	v_mfma_f32_16x16x32_fp8_fp8 v[6:9], v[192:193], v[78:79], v[6:9]
	v_mov_b32_e32 v208, v210
	v_mfma_f32_16x16x32_fp8_fp8 v[2:5], v[186:187], v[80:81], v[2:5]
	v_mfma_f32_16x16x32_fp8_fp8 v[6:9], v[194:195], v[80:81], v[6:9]
	s_nop 5
	v_max_f32_e32 v0, v3, v3
	v_max_f32_e32 v10, v2, v2
	v_max_f32_e32 v0, v10, v0
	v_max_f32_e32 v10, v5, v5
	v_max_f32_e32 v11, v4, v4
	v_max_f32_e32 v10, v11, v10
	v_max_f32_e32 v11, v9, v9
	v_max_f32_e32 v12, v8, v8
	v_max_f32_e32 v11, v12, v11
	v_max3_f32 v11, v6, v7, v11
	v_max3_f32 v0, v0, v10, v11
	v_mov_b64_e32 v[10:11], v[34:35]
	v_cmp_gt_f32_e32 vcc, v0, v211
	v_mov_b64_e32 v[12:13], v[36:37]
	s_cbranch_vccz .LBB0_720
	v_and_b32_e32 v11, 64, v204
	v_xor_b32_e32 v10, 16, v204
	v_add_u32_e32 v11, 64, v11
	v_cmp_lt_i32_e32 vcc, v10, v11
	v_xor_b32_e32 v12, 32, v204
	s_nop 0
	v_cndmask_b32_e32 v10, v204, v10, vcc
	v_lshlrev_b32_e32 v10, 2, v10
	ds_bpermute_b32 v10, v10, v0
	v_max_f32_e32 v0, v0, v0
	v_cmp_lt_i32_e32 vcc, v12, v11
	s_waitcnt lgkmcnt(0)
	v_max_f32_e32 v10, v10, v10
	v_max_f32_e32 v0, v0, v10
	v_cndmask_b32_e32 v10, v204, v12, vcc
	v_lshlrev_b32_e32 v10, 2, v10
	ds_bpermute_b32 v10, v10, v0
	s_waitcnt lgkmcnt(0)
	v_max3_f32 v207, v209, v0, v10
	v_sub_f32_e32 v0, v209, v207
	v_exp_f32_e32 v0, v0
	s_nop 0
	v_mul_f32_e32 v208, v210, v0
	v_pk_mul_f32 v[12:13], v[36:37], v[0:1] op_sel_hi:[1,0]
	v_pk_mul_f32 v[10:11], v[34:35], v[0:1] op_sel_hi:[1,0]
	v_pk_mul_f32 v[16:17], v[40:41], v[0:1] op_sel_hi:[1,0]
	v_pk_mul_f32 v[14:15], v[38:39], v[0:1] op_sel_hi:[1,0]
	v_pk_mul_f32 v[20:21], v[44:45], v[0:1] op_sel_hi:[1,0]
	v_pk_mul_f32 v[18:19], v[42:43], v[0:1] op_sel_hi:[1,0]
	v_pk_mul_f32 v[24:25], v[48:49], v[0:1] op_sel_hi:[1,0]
	v_pk_mul_f32 v[22:23], v[46:47], v[0:1] op_sel_hi:[1,0]
	v_pk_mul_f32 v[28:29], v[52:53], v[0:1] op_sel_hi:[1,0]
	v_pk_mul_f32 v[26:27], v[50:51], v[0:1] op_sel_hi:[1,0]
	v_pk_mul_f32 v[32:33], v[56:57], v[0:1] op_sel_hi:[1,0]
	v_pk_mul_f32 v[30:31], v[54:55], v[0:1] op_sel_hi:[1,0]
	v_pk_mul_f32 v[68:69], v[60:61], v[0:1] op_sel_hi:[1,0]
	v_pk_mul_f32 v[66:67], v[58:59], v[0:1] op_sel_hi:[1,0]
	v_pk_mul_f32 v[72:73], v[64:65], v[0:1] op_sel_hi:[1,0]
	v_pk_mul_f32 v[70:71], v[62:63], v[0:1] op_sel_hi:[1,0]
; template <bool SLC, bool NOMASK> ...
;     ...
;     load_frag8(nxt, KF, VF, SLC ? (dnext & 0xfffff) : dnext, lane);
;     f32x4 sa[2] = {(f32x4){0.f, 0.f, 0.f, 0.f}, (f32x4){0.f, 0.f, 0.f, 0.f}};
; #pragma unroll
;     for (int T = 0; T < 2; ++T)
; #pragma unroll
;         for (int s2 = 0; s2 < 4; ++s2) sa[T] = __builtin_amdgcn_mfma_f32_16x16x32_fp8_fp8(cur.k[T][s2], qf[s2], sa[T], 0, 0, 0);
;     float sc[8]; bool vd[8]; float mx = -1e30f;
;     const bool act = lo == 0 || !SLC;
;     if (NOMASK) {
; #pragma unroll
;         for (int j = 0; j < 8; ++j) { sc[j] = sa[j >> 2][j & 3]; vd[j] = act; }
;         mx = fmaxf(fmaxf(fmaxf(sc[0], sc[1]), fmaxf(sc[2], sc[3])), fmaxf(fmaxf(sc[4], sc[5]), fmaxf(sc[6], sc[7])));
;         mx = act ? mx : -1e30f;
;     } else {
; #pragma unroll
;         for (int T = 0; T < 2; ++T)
; #pragma unroll
;             for (int r = 0; r < 4; ++r) { const int p = pos0 + 16 * T + 4 * kq + r; const bool v = (p >= lo) & (p <= hi); const float x = sa[T][r];
;                 sc[4 * T + r] = x; vd[4 * T + r] = v; mx = v ? fmaxf(mx, x) : mx; }
;     }
;     if (__builtin_amdgcn_ballot_w64(mx > st.m + 4.f) != 0ull) {
;         mx = fmaxf(mx, __shfl_xor(mx, 16)); mx = fmaxf(mx, __shfl_xor(mx, 32));
;         const float mn = fmaxf(st.m, mx), alpha = __builtin_amdgcn_exp2f(st.m - mn); st.m = mn; st.l *= alpha;
; #pragma unroll
;         for (int j = 0; j < 8; ++j) st.o[j] = st.o[j] * alpha;
;     }
;     f32x4 pa, pb; float ps = 0.f;
;     const float mref = st.m - 4.f;
;     if (NOMASK) {
; #pragma unroll
;         for (int j = 0; j < 4; ++j) { pa[j] = __builtin_amdgcn_exp2f(sc[j] - mref); pb[j] = __builtin_amdgcn_exp2f(sc[4 + j] - mref); }
;         if (SLC) {
; #pragma unroll
;             for (int j = 0; j < 4; ++j) { pa[j] = act ? pa[j] : 0.f; pb[j] = act ? pb[j] : 0.f; }
;         }
; #pragma unroll
;         for (int j = 0; j < 4; ++j) ps += pa[j] + pb[j];
;     } else {
; #pragma unroll
;         for (int j = 0; j < 4; ++j) { pa[j] = vd[j] ? __builtin_amdgcn_exp2f(sc[j] - mref) : 0.f; pb[j] = vd[4 + j] ? __builtin_amdgcn_exp2f(sc[4 + j] - mref) : 0.f; ps += pa[j] + pb[j]; }
;     }
;     st.l += ps;
;     const u32x2 pw = pack8_fp8(pa, pb);
;     const i64_t pf = __builtin_bit_cast(i64_t, pw);
; #pragma unroll
;     for (int db = 0; db < 8; ++db) st.o[db] = __builtin_amdgcn_mfma_f32_16x16x32_fp8_fp8(cur.v[db], pf, st.o[db], 0, 0, 0);
.LBB0_720:
	v_add_f32_e32 v213, -4.0, v207
	v_sub_f32_e32 v0, v2, v213
	v_exp_f32_e32 v215, v0
	v_sub_f32_e32 v0, v6, v213
	v_exp_f32_e32 v217, v0
	v_sub_f32_e32 v0, v3, v213
	v_exp_f32_e32 v212, v0
	v_sub_f32_e32 v0, v7, v213
	v_exp_f32_e32 v0, v0
	v_sub_f32_e32 v2, v4, v213
	v_exp_f32_e32 v220, v2
	v_sub_f32_e32 v2, v8, v213
	v_exp_f32_e32 v221, v2
	v_sub_f32_e32 v2, v5, v213
	v_exp_f32_e32 v214, v2
	v_sub_f32_e32 v2, v9, v213
	v_mov_b32_e32 v218, v1
	v_mov_b32_e32 v219, v1
	v_exp_f32_e32 v216, v2
	v_cvt_pk_fp8_f32 v218, v215, v212
	v_cvt_pk_fp8_f32 v219, v217, v0
	v_add_f32_e32 v213, v215, v217
	v_add_f32_e32 v215, v220, v221
	v_cvt_pk_fp8_f32 v218, v220, v214 op_sel:[0,0,1]
	v_cvt_pk_fp8_f32 v219, v221, v216 op_sel:[0,0,1]
	s_mov_b64 s[4:5], 0
	s_waitcnt vmcnt(19)
	v_mfma_f32_16x16x32_fp8_fp8 v[2:5], v[164:165], v[218:219], v[10:13]
	v_mfma_f32_16x16x32_fp8_fp8 v[10:13], v[168:169], v[218:219], v[18:21]
	s_waitcnt vmcnt(18)
	v_mfma_f32_16x16x32_fp8_fp8 v[18:21], v[172:173], v[218:219], v[26:29]
	s_nop 2
	v_add_f32_e64 v26, v212, v0
	v_add_f32_e64 v27, v213, v1
	v_mfma_f32_16x16x32_fp8_fp8 v[6:9], v[166:167], v[218:219], v[14:17]
	v_pk_add_f32 v[26:27], v[26:27], v[26:27] op_sel_hi:[0,1]
	v_mov_b32_e32 v217, v27
	v_pk_add_f32 v[26:27], v[214:215], v[216:217]
	s_waitcnt vmcnt(17)
	v_mfma_f32_16x16x32_fp8_fp8 v[14:17], v[170:171], v[218:219], v[22:25]
	v_add_f32_e32 v0, v26, v27
	v_add_f32_e32 v208, v0, v208
	v_mfma_f32_16x16x32_fp8_fp8 v[22:25], v[174:175], v[218:219], v[30:33]
	s_waitcnt vmcnt(16)
	v_mfma_f32_16x16x32_fp8_fp8 v[30:33], v[176:177], v[218:219], v[66:69]
	v_mfma_f32_16x16x32_fp8_fp8 v[26:29], v[178:179], v[218:219], v[70:73]
.LBB0_721:
	s_and_b64 vcc, exec, s[4:5]
	s_cbranch_vccz .LBB0_725
	v_lshl_add_u64 v[244:245], v[198:199], 0, v[98:99]
	global_load_dwordx4 v[148:151], v[244:245], off
	global_load_dwordx4 v[152:155], v[244:245], off offset:1024
	global_load_dwordx4 v[156:159], v[244:245], off offset:2048
	global_load_dwordx4 v[160:163], v[244:245], off offset:3072
	v_lshl_add_u64 v[246:247], v[196:197], 0, v[98:99]
	global_load_dwordx4 v[116:119], v[246:247], off
	global_load_dwordx4 v[120:123], v[246:247], off offset:1024
	global_load_dwordx4 v[124:127], v[246:247], off offset:2048
	global_load_dwordx4 v[128:131], v[246:247], off offset:3072
	s_waitcnt vmcnt(20)
	v_mfma_f32_16x16x32_fp8_fp8 v[2:5], v[180:181], v[74:75], 0
	v_or_b32_e32 v0, s78, v203
	v_cmp_ge_i32_e32 vcc, v0, v105
	v_cmp_le_i32_e64 s[4:5], v0, v206
	v_mfma_f32_16x16x32_fp8_fp8 v[2:5], v[182:183], v[76:77], v[2:5]
	s_and_b64 s[10:11], vcc, s[4:5]
	v_or_b32_e32 v11, 1, v0
	v_cmp_ge_i32_e32 vcc, v11, v105
	v_mfma_f32_16x16x32_fp8_fp8 v[2:5], v[184:185], v[78:79], v[2:5]
	v_cmp_lt_i32_e64 s[4:5], v0, v206
	s_and_b64 s[6:7], s[4:5], vcc
	v_mfma_f32_16x16x32_fp8_fp8 v[6:9], v[188:189], v[74:75], 0
	v_mfma_f32_16x16x32_fp8_fp8 v[2:5], v[186:187], v[80:81], v[2:5]
	v_mfma_f32_16x16x32_fp8_fp8 v[6:9], v[190:191], v[76:77], v[6:9]
	v_mfma_f32_16x16x32_fp8_fp8 v[6:9], v[192:193], v[78:79], v[6:9]
	s_nop 3
	v_max_f32_e32 v10, v2, v2
	v_max_f32_e32 v10, 0xf149f2ca, v10
	v_cndmask_b32_e64 v10, v205, v10, s[10:11]
	v_max_f32_e32 v11, v3, v3
	v_max_f32_e32 v11, v10, v11
	v_cndmask_b32_e64 v10, v10, v11, s[6:7]
	v_or_b32_e32 v11, 2, v0
	v_cmp_ge_i32_e32 vcc, v11, v105
	v_cmp_le_i32_e64 s[4:5], v11, v206
	v_max_f32_e32 v11, v4, v4
	v_max_f32_e32 v11, v10, v11
	s_and_b64 s[8:9], vcc, s[4:5]
	v_mfma_f32_16x16x32_fp8_fp8 v[6:9], v[194:195], v[80:81], v[6:9]
	v_cndmask_b32_e64 v10, v10, v11, s[8:9]
	v_or_b32_e32 v11, 3, v0
	v_cmp_ge_i32_e32 vcc, v11, v105
	v_cmp_le_i32_e64 s[4:5], v11, v206
	v_max_f32_e32 v11, v5, v5
	v_max_f32_e32 v11, v10, v11
	s_and_b64 s[4:5], vcc, s[4:5]
	v_cndmask_b32_e64 v10, v10, v11, s[4:5]
	v_or_b32_e32 v11, 16, v0
	v_cmp_ge_i32_e32 vcc, v11, v105
	v_cmp_le_i32_e64 s[12:13], v11, v206
	v_max_f32_e32 v11, v6, v6
	v_max_f32_e32 v11, v10, v11
	s_and_b64 s[18:19], vcc, s[12:13]
	v_cndmask_b32_e64 v10, v10, v11, s[18:19]
	v_or_b32_e32 v11, 17, v0
	v_cmp_ge_i32_e32 vcc, v11, v105
	v_cmp_le_i32_e64 s[12:13], v11, v206
	v_max_f32_e32 v11, v10, v10
	v_max_f32_e32 v12, v7, v7
	v_max_f32_e32 v11, v11, v12
	s_and_b64 s[14:15], vcc, s[12:13]
	v_cndmask_b32_e64 v10, v10, v11, s[14:15]
	v_or_b32_e32 v11, 18, v0
	v_cmp_ge_i32_e32 vcc, v11, v105
	v_cmp_le_i32_e64 s[12:13], v11, v206
	v_max_f32_e32 v11, v10, v10
	v_max_f32_e32 v12, v8, v8
	v_max_f32_e32 v11, v11, v12
	s_and_b64 s[16:17], vcc, s[12:13]
	v_cndmask_b32_e64 v10, v10, v11, s[16:17]
	v_or_b32_e32 v0, 19, v0
	v_cmp_ge_i32_e32 vcc, v0, v105
	v_cmp_le_i32_e64 s[12:13], v0, v206
	v_max_f32_e32 v0, v10, v10
	v_max_f32_e32 v11, v9, v9
	v_max_f32_e32 v0, v0, v11
	s_and_b64 s[12:13], vcc, s[12:13]
	v_cndmask_b32_e64 v0, v10, v0, s[12:13]
	v_cmp_gt_f32_e32 vcc, v0, v211
	s_cbranch_vccz .LBB0_724
	v_and_b32_e32 v11, 64, v204
	v_xor_b32_e32 v10, 16, v204
	v_add_u32_e32 v11, 64, v11
	v_cmp_lt_i32_e32 vcc, v10, v11
	v_xor_b32_e32 v12, 32, v204
	s_nop 0
	v_cndmask_b32_e32 v10, v204, v10, vcc
	v_lshlrev_b32_e32 v10, 2, v10
	ds_bpermute_b32 v10, v10, v0
	v_max_f32_e32 v0, v0, v0
	v_cmp_lt_i32_e32 vcc, v12, v11
	s_waitcnt lgkmcnt(0)
	v_max_f32_e32 v10, v10, v10
	v_max_f32_e32 v0, v0, v10
	v_cndmask_b32_e32 v10, v204, v12, vcc
	v_lshlrev_b32_e32 v10, 2, v10
	ds_bpermute_b32 v10, v10, v0
	s_waitcnt lgkmcnt(0)
	v_max3_f32 v10, v209, v0, v10
	v_sub_f32_e32 v0, v209, v10
	v_exp_f32_e32 v0, v0
	v_mov_b32_e32 v209, v10
	v_mul_f32_e32 v210, v210, v0
	v_pk_mul_f32 v[36:37], v[36:37], v[0:1] op_sel_hi:[1,0]
	v_pk_mul_f32 v[34:35], v[34:35], v[0:1] op_sel_hi:[1,0]
	v_pk_mul_f32 v[40:41], v[40:41], v[0:1] op_sel_hi:[1,0]
	v_pk_mul_f32 v[38:39], v[38:39], v[0:1] op_sel_hi:[1,0]
	v_pk_mul_f32 v[44:45], v[44:45], v[0:1] op_sel_hi:[1,0]
	v_pk_mul_f32 v[42:43], v[42:43], v[0:1] op_sel_hi:[1,0]
	v_pk_mul_f32 v[48:49], v[48:49], v[0:1] op_sel_hi:[1,0]
	v_pk_mul_f32 v[46:47], v[46:47], v[0:1] op_sel_hi:[1,0]
	v_pk_mul_f32 v[52:53], v[52:53], v[0:1] op_sel_hi:[1,0]
	v_pk_mul_f32 v[50:51], v[50:51], v[0:1] op_sel_hi:[1,0]
	v_pk_mul_f32 v[56:57], v[56:57], v[0:1] op_sel_hi:[1,0]
	v_pk_mul_f32 v[54:55], v[54:55], v[0:1] op_sel_hi:[1,0]
	v_pk_mul_f32 v[60:61], v[60:61], v[0:1] op_sel_hi:[1,0]
	v_pk_mul_f32 v[58:59], v[58:59], v[0:1] op_sel_hi:[1,0]
	v_pk_mul_f32 v[64:65], v[64:65], v[0:1] op_sel_hi:[1,0]
	v_pk_mul_f32 v[62:63], v[62:63], v[0:1] op_sel_hi:[1,0]
; template <bool SLC, bool NOMASK> ...
;     ...
;     f32x4 pa, pb; float ps = 0.f;
;     const float mref = st.m - 4.f;
;     if (NOMASK) {
; #pragma unroll
;         for (int j = 0; j < 4; ++j) { pa[j] = __builtin_amdgcn_exp2f(sc[j] - mref); pb[j] = __builtin_amdgcn_exp2f(sc[4 + j] - mref); }
;         if (SLC) {
; #pragma unroll
;             for (int j = 0; j < 4; ++j) { pa[j] = act ? pa[j] : 0.f; pb[j] = act ? pb[j] : 0.f; }
;         }
; #pragma unroll
;         for (int j = 0; j < 4; ++j) ps += pa[j] + pb[j];
;     } else {
; #pragma unroll
;         for (int j = 0; j < 4; ++j) { pa[j] = vd[j] ? __builtin_amdgcn_exp2f(sc[j] - mref) : 0.f; pb[j] = vd[4 + j] ? __builtin_amdgcn_exp2f(sc[4 + j] - mref) : 0.f; ps += pa[j] + pb[j]; }
;     }
;     st.l += ps;
;     const u32x2 pw = pack8_fp8(pa, pb);
;     const i64_t pf = __builtin_bit_cast(i64_t, pw);
; #pragma unroll
;     for (int db = 0; db < 8; ++db) st.o[db] = __builtin_amdgcn_mfma_f32_16x16x32_fp8_fp8(cur.v[db], pf, st.o[db], 0, 0, 0);
.LBB0_724:
	v_add_f32_e32 v0, -4.0, v209
	v_sub_f32_e32 v2, v2, v0
	v_exp_f32_e32 v2, v2
	v_sub_f32_e32 v6, v6, v0
	v_exp_f32_e32 v6, v6
	v_sub_f32_e32 v4, v4, v0
	v_cndmask_b32_e64 v22, 0, v2, s[10:11]
	v_sub_f32_e32 v2, v3, v0
	v_exp_f32_e32 v2, v2
	v_sub_f32_e32 v3, v7, v0
	v_exp_f32_e32 v3, v3
	v_cndmask_b32_e64 v23, 0, v6, s[18:19]
	v_sub_f32_e32 v6, v8, v0
	v_cndmask_b32_e64 v24, 0, v2, s[6:7]
	v_sub_f32_e32 v2, v5, v0
	v_sub_f32_e32 v0, v9, v0
	v_exp_f32_e32 v4, v4
	v_exp_f32_e32 v6, v6
	v_cndmask_b32_e64 v25, 0, v3, s[14:15]
	v_exp_f32_e32 v2, v2
	v_exp_f32_e32 v0, v0
	v_mov_b32_e32 v26, v1
	v_mov_b32_e32 v27, v1
	v_cvt_pk_fp8_f32 v26, v22, v24
	v_cvt_pk_fp8_f32 v27, v23, v25
	v_cndmask_b32_e64 v28, 0, v4, s[8:9]
	v_cndmask_b32_e64 v29, 0, v6, s[16:17]
	v_cndmask_b32_e64 v66, 0, v2, s[4:5]
	v_cndmask_b32_e64 v0, 0, v0, s[12:13]
	v_cvt_pk_fp8_f32 v26, v28, v66 op_sel:[0,0,1]
	v_cvt_pk_fp8_f32 v27, v29, v0 op_sel:[0,0,1]
	v_add_f32_e32 v22, v22, v23
	v_add_f32_e32 v30, 0, v22
	v_add_f32_e32 v31, v24, v25
	v_add_f32_e32 v30, v31, v30
	v_add_f32_e32 v28, v28, v29
	v_add_f32_e32 v28, v28, v30
	v_add_f32_e32 v0, v66, v0
	s_waitcnt vmcnt(19)
	v_mfma_f32_16x16x32_fp8_fp8 v[2:5], v[164:165], v[26:27], v[34:37]
	v_add_f32_e32 v0, v0, v28
	v_add_f32_e32 v208, v210, v0
	v_mov_b32_e32 v207, v209
	v_mfma_f32_16x16x32_fp8_fp8 v[6:9], v[166:167], v[26:27], v[38:41]
	s_waitcnt vmcnt(18)
	v_mfma_f32_16x16x32_fp8_fp8 v[10:13], v[168:169], v[26:27], v[42:45]
	v_mfma_f32_16x16x32_fp8_fp8 v[14:17], v[170:171], v[26:27], v[46:49]
	s_waitcnt vmcnt(17)
	v_mfma_f32_16x16x32_fp8_fp8 v[18:21], v[172:173], v[26:27], v[50:53]
	v_mfma_f32_16x16x32_fp8_fp8 v[22:25], v[174:175], v[26:27], v[54:57]
	s_waitcnt vmcnt(16)
	v_mfma_f32_16x16x32_fp8_fp8 v[30:33], v[176:177], v[26:27], v[58:61]
	v_mfma_f32_16x16x32_fp8_fp8 v[26:29], v[178:179], v[26:27], v[62:65]

; __device__ __forceinline__ float bf2f(unsigned short b) { return __uint_as_float(((unsigned)b) << 16); }
; __device__ __forceinline__ void dilated_unit(int unit, const bf16_t* proj, const bf16_t* kbf, bf16_t* nsaout, int lane) {
;     ...
;     for (int pt = 0; pt < 3; ++pt) {
;         const int sh = 2 * pt, head = 4 * pt + hg;
;         const bf16_t* qrow = proj + (size_t)tc * PLD + PC_QB + head * 128 + 8 * kq;
;         i64_t q8[4];
; #pragma unroll
;         for (int s = 0; s < 4; ++s) { const bf16x8 qv = *(const bf16x8*)(qrow + 32 * s); f32x4 a, b;
; #pragma unroll
;             for (int j = 0; j < 4; ++j) { a[j] = bf2f((unsigned short)qv[j]) * SL2; b[j] = bf2f((unsigned short)qv[4 + j]) * SL2; }
;             q8[s] = __builtin_bit_cast(i64_t, pack8_fp8(a, b)); }
;         const int base = (r16 & ((1 << sh) - 1)) << (14 - sh), u0 = t0 >> sh, ui = u0 + (16 >> sh) * l16;
;         const int lo = base + (ui - 128 < 0 ? 0 : ui - 128), hi = base + ui;
;         const int first = (base + (u0 - 128 < 0 ? 0 : u0 - 128)) >> 5, last = (base + u0 + 15 * (16 >> sh)) >> 5;
;         unsigned long long hoff = (unsigned long long)head * S * 128; asm volatile("" : "+s"(hoff));
;         auto desc = [&](int i) { return 32 * (first + i); };
;         attn_run_frag8<false>(q8, kb8 + hoff, vb8 + hoff, desc, last - first + 1, lo, hi, 0, st, lane);
;     }
.LBB0_727:
	s_waitcnt vmcnt(8)
	s_nop 1
	v_mov_b64_e32 v[68:69], v[28:29]
	s_waitcnt vmcnt(0)
	v_mov_b64_e32 v[96:97], v[4:5]
	v_mov_b64_e32 v[92:93], v[8:9]
	v_mov_b64_e32 v[88:89], v[12:13]
	v_mov_b64_e32 v[84:85], v[16:17]
	v_mov_b64_e32 v[80:81], v[20:21]
	v_mov_b64_e32 v[76:77], v[24:25]
	v_mov_b64_e32 v[72:73], v[32:33]
	v_mov_b64_e32 v[66:67], v[26:27]
	v_mov_b64_e32 v[94:95], v[2:3]
	v_mov_b64_e32 v[90:91], v[6:7]
	v_mov_b64_e32 v[86:87], v[10:11]
	v_mov_b64_e32 v[82:83], v[14:15]
	v_mov_b64_e32 v[78:79], v[18:19]
	v_mov_b64_e32 v[74:75], v[22:23]
	v_mov_b64_e32 v[70:71], v[30:31]
	s_add_i32 s72, s72, 1
	s_cmp_lg_u32 s72, 3
	s_cbranch_scc0 .LBB0_692

; __device__ __forceinline__ float bf2f(unsigned short b) { return __uint_as_float(((unsigned)b) << 16); }
; template <bool SLC, class Desc>
; __device__ __forceinline__ void attn_run_frag8(const i64_t (&qf)[4], const unsigned char* __restrict__ KF, const unsigned char* __restrict__ VF, const Desc& desc, int n,
;                                                int lo_in, int hi, int qi, AState& st, int lane) {
;     if (n <= 0) return;
;     Frag8 fa, fb, fc;
;     constexpr int NM = ~(1 << 30);
;     int d0 = desc(0), d1 = desc(n > 1 ? 1 : 0);
;     load_frag8(fa, KF, VF, SLC ? (d0 & 0xfffff) : (d0 & NM), lane);
;     load_frag8(fb, KF, VF, SLC ? (d1 & 0xfffff) : (d1 & NM), lane);
; __device__ __forceinline__ void dilated_unit(int unit, const bf16_t* proj, const bf16_t* kbf, bf16_t* nsaout, int lane) {
;     ...
;         const int sh = 2 * pt, head = 4 * pt + hg;
;         const bf16_t* qrow = proj + (size_t)tc * PLD + PC_QB + head * 128 + 8 * kq;
;         i64_t q8[4];
; #pragma unroll
;         for (int s = 0; s < 4; ++s) { const bf16x8 qv = *(const bf16x8*)(qrow + 32 * s); f32x4 a, b;
; #pragma unroll
;             for (int j = 0; j < 4; ++j) { a[j] = bf2f((unsigned short)qv[j]) * SL2; b[j] = bf2f((unsigned short)qv[4 + j]) * SL2; }
;             q8[s] = __builtin_bit_cast(i64_t, pack8_fp8(a, b)); }
;         const int base = (r16 & ((1 << sh) - 1)) << (14 - sh), u0 = t0 >> sh, ui = u0 + (16 >> sh) * l16;
;         const int lo = base + (ui - 128 < 0 ? 0 : ui - 128), hi = base + ui;
;         const int first = (base + (u0 - 128 < 0 ? 0 : u0 - 128)) >> 5, last = (base + u0 + 15 * (16 >> sh)) >> 5;
;         unsigned long long hoff = (unsigned long long)head * S * 128; asm volatile("" : "+s"(hoff));
;         auto desc = [&](int i) { return 32 * (first + i); };
;         attn_run_frag8<false>(q8, kb8 + hoff, vb8 + hoff, desc, last - first + 1, lo, hi, 0, st, lane);
.LBB0_735:
	s_lshl_b32 s4, s59, 2
	s_or_b32 s4, s4, s56
	s_lshl_b32 s24, s4, 8
	v_lshl_add_u64 v[18:19], v[110:111], 0, s[24:25]
	global_load_dwordx4 v[14:17], v[18:19], off
	global_load_dwordx4 v[10:13], v[18:19], off offset:64
	global_load_dwordx4 v[6:9], v[18:19], off offset:128
	global_load_dwordx4 v[2:5], v[18:19], off offset:192
	s_lshl_b32 s5, s59, 1
	s_sub_i32 s6, 14, s5
	s_lshl_b32 s6, s57, s6
	s_and_b32 s8, s6, 0x3f00
	s_ashr_i32 s10, s58, s5
	s_lshr_b32 s11, 16, s5
	s_add_i32 s9, s8, 0xffffff80
	s_max_i32 s5, s10, 0x80
	s_add_i32 s12, s9, s5
	s_mul_i32 s5, s11, 15
	s_add_i32 s5, s5, s10
	s_add_i32 s5, s5, s8
	s_lshr_b32 s60, s12, 5
	s_ashr_i32 s13, s5, 5
	s_lshl_b32 s24, s4, 21
	s_sub_i32 s61, s13, s60
	s_mov_b64 s[6:7], s[24:25]
	s_cmp_lt_i32 s61, 0
	s_cbranch_scc1 .LBB0_767
	s_add_u32 s4, s51, s6
	s_addc_u32 s5, s52, s7
	s_add_u32 s6, s49, s6
	s_addc_u32 s7, s50, s7
	s_and_b32 s62, s12, 0xffffffe0
	s_cmp_lg_u32 s13, s60
	s_cselect_b64 s[14:15], -1, 0
	s_cmp_lg_u64 s[14:15], 0
	s_addc_u32 s14, s60, 0
	s_and_b32 s15, s12, 0xbfffffe0
	s_lshr_b32 s24, s15, 4
	s_lshl_b32 s63, s14, 5
	s_lshl_b64 s[12:13], s[24:25], 11
	s_waitcnt vmcnt(3)
	v_lshlrev_b32_e32 v0, 16, v14
	v_and_b32_e32 v14, 0xffff0000, v14
	s_add_u32 s12, s6, s12
	v_mul_f32_e32 v0, 0x3e0293ee, v0
	v_mul_f32_e32 v14, 0x3e0293ee, v14
	v_lshlrev_b32_e32 v19, 16, v15
	v_and_b32_e32 v15, 0xffff0000, v15
	v_mov_b32_e32 v74, v1
	s_addc_u32 s13, s7, s13
	s_lshr_b32 s24, s15, 5
	v_mul_f32_e32 v21, 0x3e0293ee, v15
	v_cvt_pk_fp8_f32 v74, v0, v14
	v_lshl_add_u64 v[14:15], s[12:13], 0, v[98:99]
	s_lshl_b64 s[12:13], s[24:25], 12
	s_add_u32 s12, s4, s12
	s_addc_u32 s13, s5, s13
	v_lshl_add_u64 v[244:245], v[14:15], 0, v[98:99]
	global_load_dwordx4 v[132:135], v[244:245], off
	global_load_dwordx4 v[136:139], v[244:245], off offset:1024
	global_load_dwordx4 v[140:143], v[244:245], off offset:2048
	global_load_dwordx4 v[144:147], v[244:245], off offset:3072
	v_lshl_add_u64 v[14:15], s[12:13], 0, v[98:99]
	s_and_b32 s12, s63, 0x3fffffe0
	s_lshr_b32 s24, s12, 4
	s_lshl_b64 s[12:13], s[24:25], 11
	s_add_u32 s12, s6, s12
	s_addc_u32 s13, s7, s13
	s_and_b32 s24, s14, 0x1ffffff
	v_lshl_add_u64 v[246:247], v[14:15], 0, v[98:99]
	global_load_dwordx4 v[86:89], v[246:247], off
	global_load_dwordx4 v[90:93], v[246:247], off offset:1024
	global_load_dwordx4 v[94:97], v[246:247], off offset:2048
	global_load_dwordx4 v[112:115], v[246:247], off offset:3072
	v_lshl_add_u64 v[14:15], s[12:13], 0, v[98:99]
	s_lshl_b64 s[12:13], s[24:25], 12
	s_add_u32 s12, s4, s12
	s_addc_u32 s13, s5, s13
	v_lshl_add_u64 v[244:245], v[14:15], 0, v[98:99]
	global_load_dwordx4 v[148:151], v[244:245], off
	global_load_dwordx4 v[152:155], v[244:245], off offset:1024
	global_load_dwordx4 v[156:159], v[244:245], off offset:2048
	global_load_dwordx4 v[160:163], v[244:245], off offset:3072
	v_lshl_add_u64 v[14:15], s[12:13], 0, v[98:99]
	v_lshl_add_u64 v[246:247], v[14:15], 0, v[98:99]
	global_load_dwordx4 v[116:119], v[246:247], off
	global_load_dwordx4 v[120:123], v[246:247], off offset:1024
	global_load_dwordx4 v[124:127], v[246:247], off offset:2048
	global_load_dwordx4 v[128:131], v[246:247], off offset:3072
	v_lshlrev_b32_e32 v18, 16, v16
	v_and_b32_e32 v16, 0xffff0000, v16
	v_mul_f32_e32 v18, 0x3e0293ee, v18
	v_mul_f32_e32 v16, 0x3e0293ee, v16
	v_mov_b32_e32 v75, v1
	v_cvt_pk_fp8_f32 v75, v18, v16
	v_lshlrev_b32_e32 v20, 16, v17
	v_and_b32_e32 v17, 0xffff0000, v17
	s_waitcnt vmcnt(18)
	v_lshlrev_b32_e32 v14, 16, v12
	v_and_b32_e32 v12, 0xffff0000, v12
	v_mul_f32_e32 v20, 0x3e0293ee, v20
	v_mul_f32_e32 v0, 0x3e0293ee, v17
	v_mul_f32_e32 v14, 0x3e0293ee, v14
	v_mul_f32_e32 v12, 0x3e0293ee, v12
	v_mov_b32_e32 v77, v1
	v_cvt_pk_fp8_f32 v75, v20, v0 op_sel:[0,0,1]
	v_lshlrev_b32_e32 v0, 16, v10
	v_and_b32_e32 v10, 0xffff0000, v10
	v_cvt_pk_fp8_f32 v77, v14, v12
	v_mul_f32_e32 v0, 0x3e0293ee, v0
	v_mul_f32_e32 v10, 0x3e0293ee, v10
	v_mov_b32_e32 v76, v1
	v_lshlrev_b32_e32 v16, 16, v13
	v_cvt_pk_fp8_f32 v76, v0, v10
	v_and_b32_e32 v0, 0xffff0000, v13
	s_waitcnt vmcnt(17)
	v_lshlrev_b32_e32 v10, 16, v8
	v_and_b32_e32 v8, 0xffff0000, v8
	v_mul_f32_e32 v16, 0x3e0293ee, v16
	v_mul_f32_e32 v0, 0x3e0293ee, v0
	v_mul_f32_e32 v10, 0x3e0293ee, v10
	v_mul_f32_e32 v8, 0x3e0293ee, v8
	v_mov_b32_e32 v79, v1
	v_cvt_pk_fp8_f32 v77, v16, v0 op_sel:[0,0,1]
	v_lshlrev_b32_e32 v0, 16, v6
	v_and_b32_e32 v6, 0xffff0000, v6
	v_cvt_pk_fp8_f32 v79, v10, v8
	v_mul_f32_e32 v0, 0x3e0293ee, v0
	v_mul_f32_e32 v6, 0x3e0293ee, v6
	v_mov_b32_e32 v78, v1
	v_lshlrev_b32_e32 v12, 16, v9
	v_cvt_pk_fp8_f32 v78, v0, v6
	v_and_b32_e32 v0, 0xffff0000, v9
	v_mul_f32_e32 v12, 0x3e0293ee, v12
	v_mul_f32_e32 v0, 0x3e0293ee, v0
	v_lshlrev_b32_e32 v15, 16, v11
	v_and_b32_e32 v11, 0xffff0000, v11
	v_cvt_pk_fp8_f32 v79, v12, v0 op_sel:[0,0,1]
	s_waitcnt vmcnt(16)
	v_lshlrev_b32_e32 v0, 16, v2
	v_lshlrev_b32_e32 v6, 16, v4
	v_and_b32_e32 v2, 0xffff0000, v2
	v_and_b32_e32 v4, 0xffff0000, v4
	v_mul_f32_e32 v15, 0x3e0293ee, v15
	v_mul_f32_e32 v11, 0x3e0293ee, v11
	v_mul_f32_e32 v0, 0x3e0293ee, v0
	v_mul_f32_e32 v6, 0x3e0293ee, v6
	v_mul_f32_e32 v2, 0x3e0293ee, v2
	v_mul_f32_e32 v4, 0x3e0293ee, v4
	v_mov_b32_e32 v80, v1
	v_mov_b32_e32 v81, v1
	v_cvt_pk_fp8_f32 v76, v15, v11 op_sel:[0,0,1]
	v_lshlrev_b32_e32 v11, 16, v7
	v_and_b32_e32 v7, 0xffff0000, v7
	v_cvt_pk_fp8_f32 v80, v0, v2
	v_cvt_pk_fp8_f32 v81, v6, v4
	v_mul_f32_e32 v11, 0x3e0293ee, v11
	v_mul_f32_e32 v7, 0x3e0293ee, v7
	v_cvt_pk_fp8_f32 v78, v11, v7 op_sel:[0,0,1]
	v_lshlrev_b32_e32 v7, 16, v3
	v_lshlrev_b32_e32 v8, 16, v5
	v_and_b32_e32 v3, 0xffff0000, v3
	v_and_b32_e32 v0, 0xffff0000, v5
	v_mul_f32_e32 v19, 0x3e0293ee, v19
	v_mul_f32_e32 v7, 0x3e0293ee, v7
	v_mul_f32_e32 v8, 0x3e0293ee, v8
	v_mul_f32_e32 v3, 0x3e0293ee, v3
	v_mul_f32_e32 v0, 0x3e0293ee, v0
	v_cvt_pk_fp8_f32 v74, v19, v21 op_sel:[0,0,1]
	v_cvt_pk_fp8_f32 v80, v7, v3 op_sel:[0,0,1]
	v_cvt_pk_fp8_f32 v81, v8, v0 op_sel:[0,0,1]
	v_mov_b32_e32 v0, s10
	v_mad_u32_u24 v0, s11, v201, v0
	v_max_i32_e32 v2, 0x80, v0
	s_mov_b32 s66, 0
	v_add_u32_e32 v105, s9, v2
	v_add_u32_e32 v204, s8, v0
	v_lshl_add_u64 v[82:83], s[6:7], 0, v[98:99]
	v_lshl_add_u64 v[84:85], s[4:5], 0, v[98:99]
	s_branch .LBB0_739

; template <bool SLC, bool NOMASK> ...
;     ...
;     load_frag8(nxt, KF, VF, SLC ? (dnext & 0xfffff) : dnext, lane);
;     f32x4 sa[2] = {(f32x4){0.f, 0.f, 0.f, 0.f}, (f32x4){0.f, 0.f, 0.f, 0.f}};
; #pragma unroll
;     for (int T = 0; T < 2; ++T)
; #pragma unroll
;         for (int s2 = 0; s2 < 4; ++s2) sa[T] = __builtin_amdgcn_mfma_f32_16x16x32_fp8_fp8(cur.k[T][s2], qf[s2], sa[T], 0, 0, 0);
;     float sc[8]; bool vd[8]; float mx = -1e30f;
;     const bool act = lo == 0 || !SLC;
;     if (NOMASK) {
; #pragma unroll
;         for (int j = 0; j < 8; ++j) { sc[j] = sa[j >> 2][j & 3]; vd[j] = act; }
;         mx = fmaxf(fmaxf(fmaxf(sc[0], sc[1]), fmaxf(sc[2], sc[3])), fmaxf(fmaxf(sc[4], sc[5]), fmaxf(sc[6], sc[7])));
;         mx = act ? mx : -1e30f;
;     } else {
; #pragma unroll
;         for (int T = 0; T < 2; ++T)
; #pragma unroll
;             for (int r = 0; r < 4; ++r) { const int p = pos0 + 16 * T + 4 * kq + r; const bool v = (p >= lo) & (p <= hi); const float x = sa[T][r];
;                 sc[4 * T + r] = x; vd[4 * T + r] = v; mx = v ? fmaxf(mx, x) : mx; }
;     }
;     if (__builtin_amdgcn_ballot_w64(mx > st.m + 4.f) != 0ull) {
;         mx = fmaxf(mx, __shfl_xor(mx, 16)); mx = fmaxf(mx, __shfl_xor(mx, 32));
;         const float mn = fmaxf(st.m, mx), alpha = __builtin_amdgcn_exp2f(st.m - mn); st.m = mn; st.l *= alpha;
; #pragma unroll
;         for (int j = 0; j < 8; ++j) st.o[j] = st.o[j] * alpha;
;     }
;     f32x4 pa, pb; float ps = 0.f;
;     const float mref = st.m - 4.f;
;     if (NOMASK) {
; #pragma unroll
;         for (int j = 0; j < 4; ++j) { pa[j] = __builtin_amdgcn_exp2f(sc[j] - mref); pb[j] = __builtin_amdgcn_exp2f(sc[4 + j] - mref); }
;         if (SLC) {
; #pragma unroll
;             for (int j = 0; j < 4; ++j) { pa[j] = act ? pa[j] : 0.f; pb[j] = act ? pb[j] : 0.f; }
;         }
; #pragma unroll
;         for (int j = 0; j < 4; ++j) ps += pa[j] + pb[j];
;     } else {
; #pragma unroll
;         for (int j = 0; j < 4; ++j) { pa[j] = vd[j] ? __builtin_amdgcn_exp2f(sc[j] - mref) : 0.f; pb[j] = vd[4 + j] ? __builtin_amdgcn_exp2f(sc[4 + j] - mref) : 0.f; ps += pa[j] + pb[j]; }
;     }
;     st.l += ps;
;     const u32x2 pw = pack8_fp8(pa, pb);
;     const i64_t pf = __builtin_bit_cast(i64_t, pw);
; #pragma unroll
;     for (int db = 0; db < 8; ++db) st.o[db] = __builtin_amdgcn_mfma_f32_16x16x32_fp8_fp8(cur.v[db], pf, st.o[db], 0, 0, 0);
.LBB0_745:
	v_lshl_add_u64 v[244:245], v[198:199], 0, v[98:99]
	global_load_dwordx4 v[180:183], v[244:245], off
	global_load_dwordx4 v[184:187], v[244:245], off offset:1024
	global_load_dwordx4 v[188:191], v[244:245], off offset:2048
	global_load_dwordx4 v[192:195], v[244:245], off offset:3072
	v_lshl_add_u64 v[246:247], v[196:197], 0, v[98:99]
	global_load_dwordx4 v[164:167], v[246:247], off
	global_load_dwordx4 v[168:171], v[246:247], off offset:1024
	global_load_dwordx4 v[172:175], v[246:247], off offset:2048
	global_load_dwordx4 v[176:179], v[246:247], off offset:3072
	s_waitcnt vmcnt(20)
	v_mfma_f32_16x16x32_fp8_fp8 v[2:5], v[132:133], v[74:75], 0
	v_mov_b64_e32 v[72:73], v[48:49]
	v_mov_b64_e32 v[68:69], v[52:53]
	v_mov_b64_e32 v[30:31], v[58:59]
	v_mfma_f32_16x16x32_fp8_fp8 v[6:9], v[140:141], v[74:75], 0
	v_mov_b64_e32 v[26:27], v[62:63]
	v_mov_b64_e32 v[22:23], v[54:55]
	v_mov_b64_e32 v[18:19], v[42:43]
	v_mfma_f32_16x16x32_fp8_fp8 v[2:5], v[134:135], v[76:77], v[2:5]
	v_mov_b64_e32 v[14:15], v[38:39]
	v_mov_b32_e32 v205, v208
	v_mov_b64_e32 v[70:71], v[46:47]
	v_mfma_f32_16x16x32_fp8_fp8 v[6:9], v[142:143], v[76:77], v[6:9]
	v_mov_b64_e32 v[66:67], v[50:51]
	v_mov_b64_e32 v[32:33], v[60:61]
	v_mov_b64_e32 v[28:29], v[64:65]
	v_mfma_f32_16x16x32_fp8_fp8 v[2:5], v[136:137], v[78:79], v[2:5]
	v_mov_b64_e32 v[24:25], v[56:57]
	v_mov_b64_e32 v[20:21], v[44:45]
	v_mov_b64_e32 v[16:17], v[40:41]
	v_mfma_f32_16x16x32_fp8_fp8 v[6:9], v[144:145], v[78:79], v[6:9]
	v_mov_b32_e32 v206, v207
	v_mfma_f32_16x16x32_fp8_fp8 v[2:5], v[138:139], v[80:81], v[2:5]
	v_mfma_f32_16x16x32_fp8_fp8 v[6:9], v[146:147], v[80:81], v[6:9]
	s_nop 5
	v_max_f32_e32 v0, v3, v3
	v_max_f32_e32 v10, v2, v2
	v_max_f32_e32 v0, v10, v0
	v_max_f32_e32 v10, v5, v5
	v_max_f32_e32 v11, v4, v4
	v_max_f32_e32 v10, v11, v10
	v_max_f32_e32 v11, v9, v9
	v_max_f32_e32 v12, v8, v8
	v_max_f32_e32 v11, v12, v11
	v_max3_f32 v11, v6, v7, v11
	v_max3_f32 v0, v0, v10, v11
	v_add_f32_e32 v10, 4.0, v208
	v_cmp_gt_f32_e32 vcc, v0, v10
	v_mov_b64_e32 v[10:11], v[34:35]
	v_mov_b64_e32 v[12:13], v[36:37]
	s_cbranch_vccz .LBB0_747
	v_and_b32_e32 v11, 64, v200
	v_xor_b32_e32 v10, 16, v200
	v_add_u32_e32 v11, 64, v11
	v_cmp_lt_i32_e32 vcc, v10, v11
	v_xor_b32_e32 v12, 32, v200
	s_nop 0
	v_cndmask_b32_e32 v10, v200, v10, vcc
	v_lshlrev_b32_e32 v10, 2, v10
	ds_bpermute_b32 v10, v10, v0
	v_max_f32_e32 v0, v0, v0
	v_cmp_lt_i32_e32 vcc, v12, v11
	s_waitcnt lgkmcnt(0)
	v_max_f32_e32 v10, v10, v10
	v_max_f32_e32 v0, v0, v10
	v_cndmask_b32_e32 v10, v200, v12, vcc
	v_lshlrev_b32_e32 v10, 2, v10
	ds_bpermute_b32 v10, v10, v0
	s_waitcnt lgkmcnt(0)
	v_max3_f32 v205, v208, v0, v10
	v_sub_f32_e32 v0, v208, v205
	v_exp_f32_e32 v0, v0
	s_nop 0
	v_mul_f32_e32 v206, v207, v0
	v_pk_mul_f32 v[12:13], v[36:37], v[0:1] op_sel_hi:[1,0]
	v_pk_mul_f32 v[10:11], v[34:35], v[0:1] op_sel_hi:[1,0]
	v_pk_mul_f32 v[16:17], v[40:41], v[0:1] op_sel_hi:[1,0]
	v_pk_mul_f32 v[14:15], v[38:39], v[0:1] op_sel_hi:[1,0]
	v_pk_mul_f32 v[20:21], v[44:45], v[0:1] op_sel_hi:[1,0]
	v_pk_mul_f32 v[18:19], v[42:43], v[0:1] op_sel_hi:[1,0]
	v_pk_mul_f32 v[24:25], v[56:57], v[0:1] op_sel_hi:[1,0]
	v_pk_mul_f32 v[22:23], v[54:55], v[0:1] op_sel_hi:[1,0]
	v_pk_mul_f32 v[28:29], v[64:65], v[0:1] op_sel_hi:[1,0]
	v_pk_mul_f32 v[26:27], v[62:63], v[0:1] op_sel_hi:[1,0]
	v_pk_mul_f32 v[32:33], v[60:61], v[0:1] op_sel_hi:[1,0]
	v_pk_mul_f32 v[30:31], v[58:59], v[0:1] op_sel_hi:[1,0]
	v_pk_mul_f32 v[68:69], v[52:53], v[0:1] op_sel_hi:[1,0]
	v_pk_mul_f32 v[66:67], v[50:51], v[0:1] op_sel_hi:[1,0]
	v_pk_mul_f32 v[72:73], v[48:49], v[0:1] op_sel_hi:[1,0]
	v_pk_mul_f32 v[70:71], v[46:47], v[0:1] op_sel_hi:[1,0]
.LBB0_747:
	v_add_f32_e32 v209, -4.0, v205
	v_sub_f32_e32 v0, v2, v209
	v_exp_f32_e32 v211, v0
	v_sub_f32_e32 v0, v6, v209
	v_exp_f32_e32 v213, v0
	v_sub_f32_e32 v0, v3, v209
	v_exp_f32_e32 v210, v0
	v_sub_f32_e32 v0, v7, v209
	v_exp_f32_e32 v0, v0
	v_sub_f32_e32 v2, v4, v209
	v_exp_f32_e32 v215, v2
	v_sub_f32_e32 v2, v8, v209
	v_exp_f32_e32 v218, v2
	v_sub_f32_e32 v2, v5, v209
	v_exp_f32_e32 v212, v2
	v_sub_f32_e32 v2, v9, v209
	v_mov_b32_e32 v216, v1
	v_mov_b32_e32 v217, v1
	v_exp_f32_e32 v214, v2
	v_cvt_pk_fp8_f32 v216, v211, v210
	v_cvt_pk_fp8_f32 v217, v213, v0
	v_add_f32_e32 v211, v211, v213
	v_add_f32_e32 v213, v215, v218
	v_cvt_pk_fp8_f32 v216, v215, v212 op_sel:[0,0,1]
	v_cvt_pk_fp8_f32 v217, v218, v214 op_sel:[0,0,1]
	s_nop 0
	s_waitcnt vmcnt(19)
	v_mfma_f32_16x16x32_fp8_fp8 v[2:5], v[86:87], v[216:217], v[10:13]
	v_mfma_f32_16x16x32_fp8_fp8 v[10:13], v[90:91], v[216:217], v[18:21]
	s_waitcnt vmcnt(18)
	v_mfma_f32_16x16x32_fp8_fp8 v[18:21], v[94:95], v[216:217], v[26:29]
	s_nop 2
	v_add_f32_e64 v26, v210, v0
	v_add_f32_e64 v27, v211, v1
	v_mfma_f32_16x16x32_fp8_fp8 v[6:9], v[88:89], v[216:217], v[14:17]
	v_pk_add_f32 v[26:27], v[26:27], v[26:27] op_sel_hi:[0,1]
	v_mov_b32_e32 v215, v27
	v_pk_add_f32 v[26:27], v[212:213], v[214:215]
	s_waitcnt vmcnt(17)
	v_mfma_f32_16x16x32_fp8_fp8 v[14:17], v[92:93], v[216:217], v[22:25]
	v_add_f32_e32 v0, v26, v27
	v_add_f32_e32 v206, v0, v206
	v_mfma_f32_16x16x32_fp8_fp8 v[22:25], v[96:97], v[216:217], v[30:33]
	s_waitcnt vmcnt(16)
	v_mfma_f32_16x16x32_fp8_fp8 v[30:33], v[112:113], v[216:217], v[66:69]
	v_mfma_f32_16x16x32_fp8_fp8 v[26:29], v[114:115], v[216:217], v[70:73]
	s_branch .LBB0_741
; template <bool SLC, bool NOMASK> ...
;     ...
;     load_frag8(nxt, KF, VF, SLC ? (dnext & 0xfffff) : dnext, lane);
;     f32x4 sa[2] = {(f32x4){0.f, 0.f, 0.f, 0.f}, (f32x4){0.f, 0.f, 0.f, 0.f}};
; #pragma unroll
;     for (int T = 0; T < 2; ++T)
; #pragma unroll
;         for (int s2 = 0; s2 < 4; ++s2) sa[T] = __builtin_amdgcn_mfma_f32_16x16x32_fp8_fp8(cur.k[T][s2], qf[s2], sa[T], 0, 0, 0);
;     float sc[8]; bool vd[8]; float mx = -1e30f;
;     const bool act = lo == 0 || !SLC;
;     if (NOMASK) {
; #pragma unroll
;         for (int j = 0; j < 8; ++j) { sc[j] = sa[j >> 2][j & 3]; vd[j] = act; }
;         mx = fmaxf(fmaxf(fmaxf(sc[0], sc[1]), fmaxf(sc[2], sc[3])), fmaxf(fmaxf(sc[4], sc[5]), fmaxf(sc[6], sc[7])));
;         mx = act ? mx : -1e30f;
;     } else {
; #pragma unroll
;         for (int T = 0; T < 2; ++T)
; #pragma unroll
;             for (int r = 0; r < 4; ++r) { const int p = pos0 + 16 * T + 4 * kq + r; const bool v = (p >= lo) & (p <= hi); const float x = sa[T][r];
;                 sc[4 * T + r] = x; vd[4 * T + r] = v; mx = v ? fmaxf(mx, x) : mx; }
;     }
;     if (__builtin_amdgcn_ballot_w64(mx > st.m + 4.f) != 0ull) {
;         mx = fmaxf(mx, __shfl_xor(mx, 16)); mx = fmaxf(mx, __shfl_xor(mx, 32));
;         const float mn = fmaxf(st.m, mx), alpha = __builtin_amdgcn_exp2f(st.m - mn); st.m = mn; st.l *= alpha;
; #pragma unroll
;         for (int j = 0; j < 8; ++j) st.o[j] = st.o[j] * alpha;
;     }
;     f32x4 pa, pb; float ps = 0.f;
;     const float mref = st.m - 4.f;
;     if (NOMASK) {
; #pragma unroll
;         for (int j = 0; j < 4; ++j) { pa[j] = __builtin_amdgcn_exp2f(sc[j] - mref); pb[j] = __builtin_amdgcn_exp2f(sc[4 + j] - mref); }
;         if (SLC) {
; #pragma unroll
;             for (int j = 0; j < 4; ++j) { pa[j] = act ? pa[j] : 0.f; pb[j] = act ? pb[j] : 0.f; }
;         }
; #pragma unroll
;         for (int j = 0; j < 4; ++j) ps += pa[j] + pb[j];
;     } else {
; #pragma unroll
;         for (int j = 0; j < 4; ++j) { pa[j] = vd[j] ? __builtin_amdgcn_exp2f(sc[j] - mref) : 0.f; pb[j] = vd[4 + j] ? __builtin_amdgcn_exp2f(sc[4 + j] - mref) : 0.f; ps += pa[j] + pb[j]; }
;     }
;     st.l += ps;
;     const u32x2 pw = pack8_fp8(pa, pb);
;     const i64_t pf = __builtin_bit_cast(i64_t, pw);
; #pragma unroll
;     for (int db = 0; db < 8; ++db) st.o[db] = __builtin_amdgcn_mfma_f32_16x16x32_fp8_fp8(cur.v[db], pf, st.o[db], 0, 0, 0);
.LBB0_748:
	v_lshl_add_u64 v[244:245], v[198:199], 0, v[98:99]
	global_load_dwordx4 v[180:183], v[244:245], off
	global_load_dwordx4 v[184:187], v[244:245], off offset:1024
	global_load_dwordx4 v[188:191], v[244:245], off offset:2048
	global_load_dwordx4 v[192:195], v[244:245], off offset:3072
	v_lshl_add_u64 v[246:247], v[196:197], 0, v[98:99]
	global_load_dwordx4 v[164:167], v[246:247], off
	global_load_dwordx4 v[168:171], v[246:247], off offset:1024
	global_load_dwordx4 v[172:175], v[246:247], off offset:2048
	global_load_dwordx4 v[176:179], v[246:247], off offset:3072
	s_waitcnt vmcnt(20)
	v_mfma_f32_16x16x32_fp8_fp8 v[2:5], v[132:133], v[74:75], 0
	v_or_b32_e32 v0, s62, v107
	v_cmp_ge_i32_e32 vcc, v0, v105
	v_cmp_le_i32_e64 s[4:5], v0, v204
	v_mfma_f32_16x16x32_fp8_fp8 v[2:5], v[134:135], v[76:77], v[2:5]
	s_and_b64 s[10:11], vcc, s[4:5]
	v_or_b32_e32 v11, 1, v0
	v_cmp_ge_i32_e32 vcc, v11, v105
	v_mfma_f32_16x16x32_fp8_fp8 v[2:5], v[136:137], v[78:79], v[2:5]
	v_cmp_lt_i32_e64 s[4:5], v0, v204
	s_and_b64 s[6:7], s[4:5], vcc
	v_mfma_f32_16x16x32_fp8_fp8 v[6:9], v[140:141], v[74:75], 0
	v_mfma_f32_16x16x32_fp8_fp8 v[2:5], v[138:139], v[80:81], v[2:5]
	v_mfma_f32_16x16x32_fp8_fp8 v[6:9], v[142:143], v[76:77], v[6:9]
	v_mfma_f32_16x16x32_fp8_fp8 v[6:9], v[144:145], v[78:79], v[6:9]
	s_nop 3
	v_max_f32_e32 v10, v2, v2
	v_max_f32_e32 v10, 0xf149f2ca, v10
	v_cndmask_b32_e64 v10, v203, v10, s[10:11]
	v_max_f32_e32 v11, v3, v3
	v_max_f32_e32 v11, v10, v11
	v_cndmask_b32_e64 v10, v10, v11, s[6:7]
	v_or_b32_e32 v11, 2, v0
	v_cmp_ge_i32_e32 vcc, v11, v105
	v_cmp_le_i32_e64 s[4:5], v11, v204
	v_max_f32_e32 v11, v4, v4
	v_max_f32_e32 v11, v10, v11
	s_and_b64 s[8:9], vcc, s[4:5]
	v_mfma_f32_16x16x32_fp8_fp8 v[6:9], v[146:147], v[80:81], v[6:9]
	v_cndmask_b32_e64 v10, v10, v11, s[8:9]
	v_or_b32_e32 v11, 3, v0
	v_cmp_ge_i32_e32 vcc, v11, v105
	v_cmp_le_i32_e64 s[4:5], v11, v204
	v_max_f32_e32 v11, v5, v5
	v_max_f32_e32 v11, v10, v11
	s_and_b64 s[4:5], vcc, s[4:5]
	v_cndmask_b32_e64 v10, v10, v11, s[4:5]
	v_or_b32_e32 v11, 16, v0
	v_cmp_ge_i32_e32 vcc, v11, v105
	v_cmp_le_i32_e64 s[12:13], v11, v204
	v_max_f32_e32 v11, v6, v6
	v_max_f32_e32 v11, v10, v11
	s_and_b64 s[18:19], vcc, s[12:13]
	v_cndmask_b32_e64 v10, v10, v11, s[18:19]
	v_or_b32_e32 v11, 17, v0
	v_cmp_ge_i32_e32 vcc, v11, v105
	v_cmp_le_i32_e64 s[12:13], v11, v204
	v_max_f32_e32 v11, v10, v10
	v_max_f32_e32 v12, v7, v7
	v_max_f32_e32 v11, v11, v12
	s_and_b64 s[14:15], vcc, s[12:13]
	v_cndmask_b32_e64 v10, v10, v11, s[14:15]
	v_or_b32_e32 v11, 18, v0
	v_cmp_ge_i32_e32 vcc, v11, v105
	v_cmp_le_i32_e64 s[12:13], v11, v204
	v_max_f32_e32 v11, v10, v10
	v_max_f32_e32 v12, v8, v8
	v_max_f32_e32 v11, v11, v12
	s_and_b64 s[16:17], vcc, s[12:13]
	v_cndmask_b32_e64 v10, v10, v11, s[16:17]
	v_or_b32_e32 v0, 19, v0
	v_cmp_ge_i32_e32 vcc, v0, v105
	v_cmp_le_i32_e64 s[12:13], v0, v204
	v_max_f32_e32 v0, v10, v10
	v_max_f32_e32 v11, v9, v9
	v_max_f32_e32 v0, v0, v11
	s_and_b64 s[12:13], vcc, s[12:13]
	v_cndmask_b32_e64 v0, v10, v0, s[12:13]
	v_add_f32_e32 v10, 4.0, v208
	v_cmp_gt_f32_e32 vcc, v0, v10
	s_cbranch_vccz .LBB0_750
	v_and_b32_e32 v11, 64, v200
	v_xor_b32_e32 v10, 16, v200
	v_add_u32_e32 v11, 64, v11
	v_cmp_lt_i32_e32 vcc, v10, v11
	v_xor_b32_e32 v12, 32, v200
	s_nop 0
	v_cndmask_b32_e32 v10, v200, v10, vcc
	v_lshlrev_b32_e32 v10, 2, v10
	ds_bpermute_b32 v10, v10, v0
	v_max_f32_e32 v0, v0, v0
	v_cmp_lt_i32_e32 vcc, v12, v11
	s_waitcnt lgkmcnt(0)
	v_max_f32_e32 v10, v10, v10
	v_max_f32_e32 v0, v0, v10
	v_cndmask_b32_e32 v10, v200, v12, vcc
	v_lshlrev_b32_e32 v10, 2, v10
	ds_bpermute_b32 v10, v10, v0
	s_waitcnt lgkmcnt(0)
	v_max3_f32 v10, v208, v0, v10
	v_sub_f32_e32 v0, v208, v10
	v_exp_f32_e32 v0, v0
	v_mov_b32_e32 v208, v10
	v_mul_f32_e32 v207, v207, v0
	v_pk_mul_f32 v[36:37], v[36:37], v[0:1] op_sel_hi:[1,0]
	v_pk_mul_f32 v[34:35], v[34:35], v[0:1] op_sel_hi:[1,0]
	v_pk_mul_f32 v[40:41], v[40:41], v[0:1] op_sel_hi:[1,0]
	v_pk_mul_f32 v[38:39], v[38:39], v[0:1] op_sel_hi:[1,0]
	v_pk_mul_f32 v[44:45], v[44:45], v[0:1] op_sel_hi:[1,0]
	v_pk_mul_f32 v[42:43], v[42:43], v[0:1] op_sel_hi:[1,0]
	v_pk_mul_f32 v[56:57], v[56:57], v[0:1] op_sel_hi:[1,0]
	v_pk_mul_f32 v[54:55], v[54:55], v[0:1] op_sel_hi:[1,0]
	v_pk_mul_f32 v[64:65], v[64:65], v[0:1] op_sel_hi:[1,0]
	v_pk_mul_f32 v[62:63], v[62:63], v[0:1] op_sel_hi:[1,0]
	v_pk_mul_f32 v[60:61], v[60:61], v[0:1] op_sel_hi:[1,0]
	v_pk_mul_f32 v[58:59], v[58:59], v[0:1] op_sel_hi:[1,0]
	v_pk_mul_f32 v[52:53], v[52:53], v[0:1] op_sel_hi:[1,0]
	v_pk_mul_f32 v[50:51], v[50:51], v[0:1] op_sel_hi:[1,0]
	v_pk_mul_f32 v[48:49], v[48:49], v[0:1] op_sel_hi:[1,0]
	v_pk_mul_f32 v[46:47], v[46:47], v[0:1] op_sel_hi:[1,0]
.LBB0_750:
	v_add_f32_e32 v0, -4.0, v208
	v_sub_f32_e32 v2, v2, v0
	v_exp_f32_e32 v2, v2
	v_sub_f32_e32 v6, v6, v0
	v_exp_f32_e32 v6, v6
	v_sub_f32_e32 v4, v4, v0
	v_cndmask_b32_e64 v22, 0, v2, s[10:11]
	v_sub_f32_e32 v2, v3, v0
	v_exp_f32_e32 v2, v2
	v_sub_f32_e32 v3, v7, v0
	v_exp_f32_e32 v3, v3
	v_cndmask_b32_e64 v23, 0, v6, s[18:19]
	v_sub_f32_e32 v6, v8, v0
	v_cndmask_b32_e64 v24, 0, v2, s[6:7]
	v_sub_f32_e32 v2, v5, v0
	v_sub_f32_e32 v0, v9, v0
	v_exp_f32_e32 v4, v4
	v_exp_f32_e32 v6, v6
	v_cndmask_b32_e64 v25, 0, v3, s[14:15]
	v_exp_f32_e32 v2, v2
	v_exp_f32_e32 v0, v0
	v_mov_b32_e32 v26, v1
	v_mov_b32_e32 v27, v1
	v_cvt_pk_fp8_f32 v26, v22, v24
	v_cvt_pk_fp8_f32 v27, v23, v25
	v_cndmask_b32_e64 v28, 0, v4, s[8:9]
	v_cndmask_b32_e64 v29, 0, v6, s[16:17]
	v_cndmask_b32_e64 v66, 0, v2, s[4:5]
	v_cndmask_b32_e64 v0, 0, v0, s[12:13]
	v_cvt_pk_fp8_f32 v26, v28, v66 op_sel:[0,0,1]
	v_cvt_pk_fp8_f32 v27, v29, v0 op_sel:[0,0,1]
	v_add_f32_e32 v22, v22, v23
	v_add_f32_e32 v30, 0, v22
	v_add_f32_e32 v31, v24, v25
	v_add_f32_e32 v30, v31, v30
	v_add_f32_e32 v28, v28, v29
	v_add_f32_e32 v28, v28, v30
	v_add_f32_e32 v0, v66, v0
	s_waitcnt vmcnt(19)
	v_mfma_f32_16x16x32_fp8_fp8 v[2:5], v[86:87], v[26:27], v[34:37]
	v_add_f32_e32 v0, v0, v28
	v_add_f32_e32 v206, v207, v0
	v_mov_b32_e32 v205, v208
	v_mfma_f32_16x16x32_fp8_fp8 v[6:9], v[88:89], v[26:27], v[38:41]
	s_waitcnt vmcnt(18)
	v_mfma_f32_16x16x32_fp8_fp8 v[10:13], v[90:91], v[26:27], v[42:45]
	v_mfma_f32_16x16x32_fp8_fp8 v[14:17], v[92:93], v[26:27], v[54:57]
	s_waitcnt vmcnt(17)
	v_mfma_f32_16x16x32_fp8_fp8 v[18:21], v[94:95], v[26:27], v[62:65]
	v_mfma_f32_16x16x32_fp8_fp8 v[22:25], v[96:97], v[26:27], v[58:61]
	s_waitcnt vmcnt(16)
	v_mfma_f32_16x16x32_fp8_fp8 v[30:33], v[112:113], v[26:27], v[50:53]
	v_mfma_f32_16x16x32_fp8_fp8 v[26:29], v[114:115], v[26:27], v[46:49]
	s_cmp_ge_i32 s66, s61
	s_mov_b64 s[4:5], -1
	s_cbranch_scc0 .LBB0_742

; template <bool SLC, bool NOMASK> ...
;     ...
;     load_frag8(nxt, KF, VF, SLC ? (dnext & 0xfffff) : dnext, lane);
;     f32x4 sa[2] = {(f32x4){0.f, 0.f, 0.f, 0.f}, (f32x4){0.f, 0.f, 0.f, 0.f}};
; #pragma unroll
;     for (int T = 0; T < 2; ++T)
; #pragma unroll
;         for (int s2 = 0; s2 < 4; ++s2) sa[T] = __builtin_amdgcn_mfma_f32_16x16x32_fp8_fp8(cur.k[T][s2], qf[s2], sa[T], 0, 0, 0);
;     float sc[8]; bool vd[8]; float mx = -1e30f;
;     const bool act = lo == 0 || !SLC;
;     if (NOMASK) {
; #pragma unroll
;         for (int j = 0; j < 8; ++j) { sc[j] = sa[j >> 2][j & 3]; vd[j] = act; }
;         mx = fmaxf(fmaxf(fmaxf(sc[0], sc[1]), fmaxf(sc[2], sc[3])), fmaxf(fmaxf(sc[4], sc[5]), fmaxf(sc[6], sc[7])));
;         mx = act ? mx : -1e30f;
;     } else {
; #pragma unroll
;         for (int T = 0; T < 2; ++T)
; #pragma unroll
;             for (int r = 0; r < 4; ++r) { const int p = pos0 + 16 * T + 4 * kq + r; const bool v = (p >= lo) & (p <= hi); const float x = sa[T][r];
;                 sc[4 * T + r] = x; vd[4 * T + r] = v; mx = v ? fmaxf(mx, x) : mx; }
;     }
;     if (__builtin_amdgcn_ballot_w64(mx > st.m + 4.f) != 0ull) {
;         mx = fmaxf(mx, __shfl_xor(mx, 16)); mx = fmaxf(mx, __shfl_xor(mx, 32));
;         const float mn = fmaxf(st.m, mx), alpha = __builtin_amdgcn_exp2f(st.m - mn); st.m = mn; st.l *= alpha;
; #pragma unroll
;         for (int j = 0; j < 8; ++j) st.o[j] = st.o[j] * alpha;
;     }
;     f32x4 pa, pb; float ps = 0.f;
;     const float mref = st.m - 4.f;
;     if (NOMASK) {
; #pragma unroll
;         for (int j = 0; j < 4; ++j) { pa[j] = __builtin_amdgcn_exp2f(sc[j] - mref); pb[j] = __builtin_amdgcn_exp2f(sc[4 + j] - mref); }
;         if (SLC) {
; #pragma unroll
;             for (int j = 0; j < 4; ++j) { pa[j] = act ? pa[j] : 0.f; pb[j] = act ? pb[j] : 0.f; }
;         }
; #pragma unroll
;         for (int j = 0; j < 4; ++j) ps += pa[j] + pb[j];
;     } else {
; #pragma unroll
;         for (int j = 0; j < 4; ++j) { pa[j] = vd[j] ? __builtin_amdgcn_exp2f(sc[j] - mref) : 0.f; pb[j] = vd[4 + j] ? __builtin_amdgcn_exp2f(sc[4 + j] - mref) : 0.f; ps += pa[j] + pb[j]; }
;     }
;     st.l += ps;
;     const u32x2 pw = pack8_fp8(pa, pb);
;     const i64_t pf = __builtin_bit_cast(i64_t, pw);
; #pragma unroll
;     for (int db = 0; db < 8; ++db) st.o[db] = __builtin_amdgcn_mfma_f32_16x16x32_fp8_fp8(cur.v[db], pf, st.o[db], 0, 0, 0);
.LBB0_752:
	v_lshl_add_u64 v[244:245], v[198:199], 0, v[98:99]
	global_load_dwordx4 v[132:135], v[244:245], off
	global_load_dwordx4 v[136:139], v[244:245], off offset:1024
	global_load_dwordx4 v[140:143], v[244:245], off offset:2048
	global_load_dwordx4 v[144:147], v[244:245], off offset:3072
	v_lshl_add_u64 v[246:247], v[196:197], 0, v[98:99]
	global_load_dwordx4 v[86:89], v[246:247], off
	global_load_dwordx4 v[90:93], v[246:247], off offset:1024
	global_load_dwordx4 v[94:97], v[246:247], off offset:2048
	global_load_dwordx4 v[112:115], v[246:247], off offset:3072
	s_waitcnt vmcnt(20)
	v_mfma_f32_16x16x32_fp8_fp8 v[34:37], v[148:149], v[74:75], 0
	v_mov_b64_e32 v[72:73], v[28:29]
	v_mov_b64_e32 v[68:69], v[32:33]
	v_mov_b64_e32 v[64:65], v[24:25]
	v_mfma_f32_16x16x32_fp8_fp8 v[38:41], v[156:157], v[74:75], 0
	v_mov_b64_e32 v[60:61], v[20:21]
	v_mov_b64_e32 v[56:57], v[16:17]
	v_mov_b64_e32 v[52:53], v[12:13]
	v_mfma_f32_16x16x32_fp8_fp8 v[34:37], v[150:151], v[76:77], v[34:37]
	v_mov_b64_e32 v[48:49], v[8:9]
	v_mov_b32_e32 v207, v205
	v_mov_b64_e32 v[70:71], v[26:27]
	v_mfma_f32_16x16x32_fp8_fp8 v[38:41], v[158:159], v[76:77], v[38:41]
	v_mov_b64_e32 v[66:67], v[30:31]
	v_mov_b64_e32 v[62:63], v[22:23]
	v_mov_b64_e32 v[58:59], v[18:19]
	v_mfma_f32_16x16x32_fp8_fp8 v[34:37], v[152:153], v[78:79], v[34:37]
	v_mov_b64_e32 v[54:55], v[14:15]
	v_mov_b64_e32 v[50:51], v[10:11]
	v_mov_b64_e32 v[46:47], v[6:7]
	v_mfma_f32_16x16x32_fp8_fp8 v[38:41], v[160:161], v[78:79], v[38:41]
	v_mov_b32_e32 v208, v206
	v_mfma_f32_16x16x32_fp8_fp8 v[34:37], v[154:155], v[80:81], v[34:37]
	v_mfma_f32_16x16x32_fp8_fp8 v[38:41], v[162:163], v[80:81], v[38:41]
	s_nop 5
	v_max_f32_e32 v0, v35, v35
	v_max_f32_e32 v42, v34, v34
	v_max_f32_e32 v0, v42, v0
	v_max_f32_e32 v42, v37, v37
	v_max_f32_e32 v43, v36, v36
	v_max_f32_e32 v42, v43, v42
	v_max_f32_e32 v43, v41, v41
	v_max_f32_e32 v44, v40, v40
	v_max_f32_e32 v43, v44, v43
	v_max3_f32 v43, v38, v39, v43
	v_max3_f32 v0, v0, v42, v43
	v_add_f32_e32 v42, 4.0, v205
	v_cmp_gt_f32_e32 vcc, v0, v42
	v_mov_b64_e32 v[44:45], v[4:5]
	v_mov_b64_e32 v[42:43], v[2:3]
	s_cbranch_vccz .LBB0_754
	v_and_b32_e32 v43, 64, v200
	v_xor_b32_e32 v42, 16, v200
	v_add_u32_e32 v43, 64, v43
	v_cmp_lt_i32_e32 vcc, v42, v43
	v_xor_b32_e32 v44, 32, v200
	s_nop 0
	v_cndmask_b32_e32 v42, v200, v42, vcc
	v_lshlrev_b32_e32 v42, 2, v42
	ds_bpermute_b32 v42, v42, v0
	v_max_f32_e32 v0, v0, v0
	v_cmp_lt_i32_e32 vcc, v44, v43
	s_waitcnt lgkmcnt(0)
	v_max_f32_e32 v42, v42, v42
	v_max_f32_e32 v0, v0, v42
	v_cndmask_b32_e32 v42, v200, v44, vcc
	v_lshlrev_b32_e32 v42, 2, v42
	ds_bpermute_b32 v42, v42, v0
	s_waitcnt lgkmcnt(0)
	v_max3_f32 v207, v205, v0, v42
	v_sub_f32_e32 v0, v205, v207
	v_exp_f32_e32 v0, v0
	s_nop 0
	v_mul_f32_e32 v208, v206, v0
	v_pk_mul_f32 v[44:45], v[4:5], v[0:1] op_sel_hi:[1,0]
	v_pk_mul_f32 v[42:43], v[2:3], v[0:1] op_sel_hi:[1,0]
	v_pk_mul_f32 v[48:49], v[8:9], v[0:1] op_sel_hi:[1,0]
	v_pk_mul_f32 v[46:47], v[6:7], v[0:1] op_sel_hi:[1,0]
	v_pk_mul_f32 v[52:53], v[12:13], v[0:1] op_sel_hi:[1,0]
	v_pk_mul_f32 v[50:51], v[10:11], v[0:1] op_sel_hi:[1,0]
	v_pk_mul_f32 v[56:57], v[16:17], v[0:1] op_sel_hi:[1,0]
	v_pk_mul_f32 v[54:55], v[14:15], v[0:1] op_sel_hi:[1,0]
	v_pk_mul_f32 v[60:61], v[20:21], v[0:1] op_sel_hi:[1,0]
	v_pk_mul_f32 v[58:59], v[18:19], v[0:1] op_sel_hi:[1,0]
	v_pk_mul_f32 v[64:65], v[24:25], v[0:1] op_sel_hi:[1,0]
	v_pk_mul_f32 v[62:63], v[22:23], v[0:1] op_sel_hi:[1,0]
	v_pk_mul_f32 v[68:69], v[32:33], v[0:1] op_sel_hi:[1,0]
	v_pk_mul_f32 v[66:67], v[30:31], v[0:1] op_sel_hi:[1,0]
	v_pk_mul_f32 v[72:73], v[28:29], v[0:1] op_sel_hi:[1,0]
	v_pk_mul_f32 v[70:71], v[26:27], v[0:1] op_sel_hi:[1,0]
.LBB0_754:
	v_add_f32_e32 v209, -4.0, v207
	v_sub_f32_e32 v0, v34, v209
	v_exp_f32_e32 v211, v0
	v_sub_f32_e32 v0, v38, v209
	v_exp_f32_e32 v213, v0
	v_sub_f32_e32 v0, v35, v209
	v_exp_f32_e32 v210, v0
	v_sub_f32_e32 v0, v39, v209
	v_exp_f32_e32 v0, v0
	v_sub_f32_e32 v34, v36, v209
	v_exp_f32_e32 v215, v34
	v_sub_f32_e32 v34, v40, v209
	v_exp_f32_e32 v218, v34
	v_sub_f32_e32 v34, v37, v209
	v_exp_f32_e32 v212, v34
	v_sub_f32_e32 v34, v41, v209
	v_mov_b32_e32 v216, v1
	v_mov_b32_e32 v217, v1
	v_exp_f32_e32 v214, v34
	v_cvt_pk_fp8_f32 v216, v211, v210
	v_cvt_pk_fp8_f32 v217, v213, v0
	v_add_f32_e32 v211, v211, v213
	v_add_f32_e32 v213, v215, v218
	v_cvt_pk_fp8_f32 v216, v215, v212 op_sel:[0,0,1]
	v_cvt_pk_fp8_f32 v217, v218, v214 op_sel:[0,0,1]
	s_nop 0
	s_waitcnt vmcnt(19)
	v_mfma_f32_16x16x32_fp8_fp8 v[34:37], v[116:117], v[216:217], v[42:45]
	v_mfma_f32_16x16x32_fp8_fp8 v[42:45], v[120:121], v[216:217], v[50:53]
	s_waitcnt vmcnt(18)
	v_mfma_f32_16x16x32_fp8_fp8 v[50:53], v[124:125], v[216:217], v[58:61]
	s_nop 2
	v_add_f32_e64 v58, v210, v0
	v_add_f32_e64 v59, v211, v1
	v_mfma_f32_16x16x32_fp8_fp8 v[38:41], v[118:119], v[216:217], v[46:49]
	v_pk_add_f32 v[58:59], v[58:59], v[58:59] op_sel_hi:[0,1]
	v_mov_b32_e32 v215, v59
	s_waitcnt vmcnt(17)
	v_mfma_f32_16x16x32_fp8_fp8 v[46:49], v[122:123], v[216:217], v[54:57]
	v_mfma_f32_16x16x32_fp8_fp8 v[54:57], v[126:127], v[216:217], v[62:65]
	s_nop 2
	v_add_f32_e64 v62, v212, v214
	v_add_f32_e64 v63, v213, v215
	s_waitcnt vmcnt(16)
	v_mfma_f32_16x16x32_fp8_fp8 v[58:61], v[128:129], v[216:217], v[66:69]
	v_add_f32_e32 v0, v62, v63
	v_add_f32_e32 v208, v0, v208
	v_mfma_f32_16x16x32_fp8_fp8 v[62:65], v[130:131], v[216:217], v[70:73]
	s_branch .LBB0_744
; template <bool SLC, bool NOMASK> ...
;     ...
;     load_frag8(nxt, KF, VF, SLC ? (dnext & 0xfffff) : dnext, lane);
;     f32x4 sa[2] = {(f32x4){0.f, 0.f, 0.f, 0.f}, (f32x4){0.f, 0.f, 0.f, 0.f}};
; #pragma unroll
;     for (int T = 0; T < 2; ++T)
; #pragma unroll
;         for (int s2 = 0; s2 < 4; ++s2) sa[T] = __builtin_amdgcn_mfma_f32_16x16x32_fp8_fp8(cur.k[T][s2], qf[s2], sa[T], 0, 0, 0);
;     float sc[8]; bool vd[8]; float mx = -1e30f;
;     const bool act = lo == 0 || !SLC;
;     if (NOMASK) {
; #pragma unroll
;         for (int j = 0; j < 8; ++j) { sc[j] = sa[j >> 2][j & 3]; vd[j] = act; }
;         mx = fmaxf(fmaxf(fmaxf(sc[0], sc[1]), fmaxf(sc[2], sc[3])), fmaxf(fmaxf(sc[4], sc[5]), fmaxf(sc[6], sc[7])));
;         mx = act ? mx : -1e30f;
;     } else {
; #pragma unroll
;         for (int T = 0; T < 2; ++T)
; #pragma unroll
;             for (int r = 0; r < 4; ++r) { const int p = pos0 + 16 * T + 4 * kq + r; const bool v = (p >= lo) & (p <= hi); const float x = sa[T][r];
;                 sc[4 * T + r] = x; vd[4 * T + r] = v; mx = v ? fmaxf(mx, x) : mx; }
;     }
;     if (__builtin_amdgcn_ballot_w64(mx > st.m + 4.f) != 0ull) {
;         mx = fmaxf(mx, __shfl_xor(mx, 16)); mx = fmaxf(mx, __shfl_xor(mx, 32));
;         const float mn = fmaxf(st.m, mx), alpha = __builtin_amdgcn_exp2f(st.m - mn); st.m = mn; st.l *= alpha;
; #pragma unroll
;         for (int j = 0; j < 8; ++j) st.o[j] = st.o[j] * alpha;
;     }
.LBB0_755:
	v_lshl_add_u64 v[244:245], v[198:199], 0, v[98:99]
	global_load_dwordx4 v[132:135], v[244:245], off
	global_load_dwordx4 v[136:139], v[244:245], off offset:1024
	global_load_dwordx4 v[140:143], v[244:245], off offset:2048
	global_load_dwordx4 v[144:147], v[244:245], off offset:3072
	v_lshl_add_u64 v[246:247], v[196:197], 0, v[98:99]
	global_load_dwordx4 v[86:89], v[246:247], off
	global_load_dwordx4 v[90:93], v[246:247], off offset:1024
	global_load_dwordx4 v[94:97], v[246:247], off offset:2048
	global_load_dwordx4 v[112:115], v[246:247], off offset:3072
	s_waitcnt vmcnt(20)
	v_mfma_f32_16x16x32_fp8_fp8 v[34:37], v[148:149], v[74:75], 0
	v_or_b32_e32 v0, s63, v107
	v_cmp_ge_i32_e32 vcc, v0, v105
	v_cmp_le_i32_e64 s[4:5], v0, v204
	v_mfma_f32_16x16x32_fp8_fp8 v[34:37], v[150:151], v[76:77], v[34:37]
	s_and_b64 s[10:11], vcc, s[4:5]
	v_or_b32_e32 v43, 1, v0
	v_cmp_ge_i32_e32 vcc, v43, v105
	v_mfma_f32_16x16x32_fp8_fp8 v[34:37], v[152:153], v[78:79], v[34:37]
	v_cmp_lt_i32_e64 s[4:5], v0, v204
	s_and_b64 s[6:7], s[4:5], vcc
	v_mfma_f32_16x16x32_fp8_fp8 v[38:41], v[156:157], v[74:75], 0
	v_mfma_f32_16x16x32_fp8_fp8 v[34:37], v[154:155], v[80:81], v[34:37]
	v_mfma_f32_16x16x32_fp8_fp8 v[38:41], v[158:159], v[76:77], v[38:41]
	v_mfma_f32_16x16x32_fp8_fp8 v[38:41], v[160:161], v[78:79], v[38:41]
	s_nop 3
	v_max_f32_e32 v42, v34, v34
	v_max_f32_e32 v42, 0xf149f2ca, v42
	v_cndmask_b32_e64 v42, v203, v42, s[10:11]
	v_max_f32_e32 v43, v35, v35
	v_max_f32_e32 v43, v42, v43
	v_cndmask_b32_e64 v42, v42, v43, s[6:7]
	v_or_b32_e32 v43, 2, v0
	v_cmp_ge_i32_e32 vcc, v43, v105
	v_cmp_le_i32_e64 s[4:5], v43, v204
	v_max_f32_e32 v43, v36, v36
	v_max_f32_e32 v43, v42, v43
	s_and_b64 s[8:9], vcc, s[4:5]
	v_mfma_f32_16x16x32_fp8_fp8 v[38:41], v[162:163], v[80:81], v[38:41]
	v_cndmask_b32_e64 v42, v42, v43, s[8:9]
	v_or_b32_e32 v43, 3, v0
	v_cmp_ge_i32_e32 vcc, v43, v105
	v_cmp_le_i32_e64 s[4:5], v43, v204
	v_max_f32_e32 v43, v37, v37
	v_max_f32_e32 v43, v42, v43
	s_and_b64 s[4:5], vcc, s[4:5]
	v_cndmask_b32_e64 v42, v42, v43, s[4:5]
	v_or_b32_e32 v43, 16, v0
	v_cmp_ge_i32_e32 vcc, v43, v105
	v_cmp_le_i32_e64 s[12:13], v43, v204
	v_max_f32_e32 v43, v38, v38
	v_max_f32_e32 v43, v42, v43
	s_and_b64 s[18:19], vcc, s[12:13]
	v_cndmask_b32_e64 v42, v42, v43, s[18:19]
	v_or_b32_e32 v43, 17, v0
	v_cmp_ge_i32_e32 vcc, v43, v105
	v_cmp_le_i32_e64 s[12:13], v43, v204
	v_max_f32_e32 v43, v42, v42
	v_max_f32_e32 v44, v39, v39
	v_max_f32_e32 v43, v43, v44
	s_and_b64 s[14:15], vcc, s[12:13]
	v_cndmask_b32_e64 v42, v42, v43, s[14:15]
	v_or_b32_e32 v43, 18, v0
	v_cmp_ge_i32_e32 vcc, v43, v105
	v_cmp_le_i32_e64 s[12:13], v43, v204
	v_max_f32_e32 v43, v42, v42
	v_max_f32_e32 v44, v40, v40
	v_max_f32_e32 v43, v43, v44
	s_and_b64 s[16:17], vcc, s[12:13]
	v_cndmask_b32_e64 v42, v42, v43, s[16:17]
	v_or_b32_e32 v0, 19, v0
	v_cmp_ge_i32_e32 vcc, v0, v105
	v_cmp_le_i32_e64 s[12:13], v0, v204
	v_max_f32_e32 v0, v42, v42
	v_max_f32_e32 v43, v41, v41
	v_max_f32_e32 v0, v0, v43
	s_and_b64 s[12:13], vcc, s[12:13]
	v_cndmask_b32_e64 v0, v42, v0, s[12:13]
	v_add_f32_e32 v42, 4.0, v205
	v_cmp_gt_f32_e32 vcc, v0, v42
	s_cbranch_vccz .LBB0_757
	v_and_b32_e32 v43, 64, v200
	v_xor_b32_e32 v42, 16, v200
	v_add_u32_e32 v43, 64, v43
	v_cmp_lt_i32_e32 vcc, v42, v43
	v_xor_b32_e32 v44, 32, v200
	s_nop 0
	v_cndmask_b32_e32 v42, v200, v42, vcc
	v_lshlrev_b32_e32 v42, 2, v42
	ds_bpermute_b32 v42, v42, v0
	v_max_f32_e32 v0, v0, v0
	v_cmp_lt_i32_e32 vcc, v44, v43
	s_waitcnt lgkmcnt(0)
	v_max_f32_e32 v42, v42, v42
	v_max_f32_e32 v0, v0, v42
	v_cndmask_b32_e32 v42, v200, v44, vcc
	v_lshlrev_b32_e32 v42, 2, v42
	ds_bpermute_b32 v42, v42, v0
	s_waitcnt lgkmcnt(0)
	v_max3_f32 v42, v205, v0, v42
	v_sub_f32_e32 v0, v205, v42
	v_exp_f32_e32 v0, v0
	v_mov_b32_e32 v205, v42
	v_mul_f32_e32 v206, v206, v0
	v_pk_mul_f32 v[4:5], v[4:5], v[0:1] op_sel_hi:[1,0]
	v_pk_mul_f32 v[2:3], v[2:3], v[0:1] op_sel_hi:[1,0]
	v_pk_mul_f32 v[8:9], v[8:9], v[0:1] op_sel_hi:[1,0]
	v_pk_mul_f32 v[6:7], v[6:7], v[0:1] op_sel_hi:[1,0]
	v_pk_mul_f32 v[12:13], v[12:13], v[0:1] op_sel_hi:[1,0]
	v_pk_mul_f32 v[10:11], v[10:11], v[0:1] op_sel_hi:[1,0]
	v_pk_mul_f32 v[16:17], v[16:17], v[0:1] op_sel_hi:[1,0]
	v_pk_mul_f32 v[14:15], v[14:15], v[0:1] op_sel_hi:[1,0]
	v_pk_mul_f32 v[20:21], v[20:21], v[0:1] op_sel_hi:[1,0]
	v_pk_mul_f32 v[18:19], v[18:19], v[0:1] op_sel_hi:[1,0]
	v_pk_mul_f32 v[24:25], v[24:25], v[0:1] op_sel_hi:[1,0]
	v_pk_mul_f32 v[22:23], v[22:23], v[0:1] op_sel_hi:[1,0]
	v_pk_mul_f32 v[32:33], v[32:33], v[0:1] op_sel_hi:[1,0]
	v_pk_mul_f32 v[30:31], v[30:31], v[0:1] op_sel_hi:[1,0]
	v_pk_mul_f32 v[28:29], v[28:29], v[0:1] op_sel_hi:[1,0]
	v_pk_mul_f32 v[26:27], v[26:27], v[0:1] op_sel_hi:[1,0]
; template <bool SLC, bool NOMASK> ...
;     ...
;     load_frag8(nxt, KF, VF, SLC ? (dnext & 0xfffff) : dnext, lane);
;     f32x4 sa[2] = {(f32x4){0.f, 0.f, 0.f, 0.f}, (f32x4){0.f, 0.f, 0.f, 0.f}};
; #pragma unroll
;     for (int T = 0; T < 2; ++T)
; #pragma unroll
;         for (int s2 = 0; s2 < 4; ++s2) sa[T] = __builtin_amdgcn_mfma_f32_16x16x32_fp8_fp8(cur.k[T][s2], qf[s2], sa[T], 0, 0, 0);
;     float sc[8]; bool vd[8]; float mx = -1e30f;
;     const bool act = lo == 0 || !SLC;
;     if (NOMASK) {
; #pragma unroll
;         for (int j = 0; j < 8; ++j) { sc[j] = sa[j >> 2][j & 3]; vd[j] = act; }
;         mx = fmaxf(fmaxf(fmaxf(sc[0], sc[1]), fmaxf(sc[2], sc[3])), fmaxf(fmaxf(sc[4], sc[5]), fmaxf(sc[6], sc[7])));
;         mx = act ? mx : -1e30f;
;     } else {
; #pragma unroll
;         for (int T = 0; T < 2; ++T)
; #pragma unroll
;             for (int r = 0; r < 4; ++r) { const int p = pos0 + 16 * T + 4 * kq + r; const bool v = (p >= lo) & (p <= hi); const float x = sa[T][r];
;                 sc[4 * T + r] = x; vd[4 * T + r] = v; mx = v ? fmaxf(mx, x) : mx; }
;     }
;     if (__builtin_amdgcn_ballot_w64(mx > st.m + 4.f) != 0ull) {
;         mx = fmaxf(mx, __shfl_xor(mx, 16)); mx = fmaxf(mx, __shfl_xor(mx, 32));
;         const float mn = fmaxf(st.m, mx), alpha = __builtin_amdgcn_exp2f(st.m - mn); st.m = mn; st.l *= alpha;
; #pragma unroll
;         for (int j = 0; j < 8; ++j) st.o[j] = st.o[j] * alpha;
;     }
;     f32x4 pa, pb; float ps = 0.f;
;     const float mref = st.m - 4.f;
;     if (NOMASK) {
; #pragma unroll
;         for (int j = 0; j < 4; ++j) { pa[j] = __builtin_amdgcn_exp2f(sc[j] - mref); pb[j] = __builtin_amdgcn_exp2f(sc[4 + j] - mref); }
;         if (SLC) {
; #pragma unroll
;             for (int j = 0; j < 4; ++j) { pa[j] = act ? pa[j] : 0.f; pb[j] = act ? pb[j] : 0.f; }
;         }
; #pragma unroll
;         for (int j = 0; j < 4; ++j) ps += pa[j] + pb[j];
;     } else {
; #pragma unroll
;         for (int j = 0; j < 4; ++j) { pa[j] = vd[j] ? __builtin_amdgcn_exp2f(sc[j] - mref) : 0.f; pb[j] = vd[4 + j] ? __builtin_amdgcn_exp2f(sc[4 + j] - mref) : 0.f; ps += pa[j] + pb[j]; }
;     }
;     st.l += ps;
;     const u32x2 pw = pack8_fp8(pa, pb);
;     const i64_t pf = __builtin_bit_cast(i64_t, pw);
; #pragma unroll
;     for (int db = 0; db < 8; ++db) st.o[db] = __builtin_amdgcn_mfma_f32_16x16x32_fp8_fp8(cur.v[db], pf, st.o[db], 0, 0, 0);
.LBB0_757:
	v_add_f32_e32 v0, -4.0, v205
	v_sub_f32_e32 v34, v34, v0
	v_exp_f32_e32 v34, v34
	v_sub_f32_e32 v38, v38, v0
	v_exp_f32_e32 v38, v38
	v_sub_f32_e32 v36, v36, v0
	v_cndmask_b32_e64 v54, 0, v34, s[10:11]
	v_sub_f32_e32 v34, v35, v0
	v_exp_f32_e32 v34, v34
	v_sub_f32_e32 v35, v39, v0
	v_exp_f32_e32 v35, v35
	v_cndmask_b32_e64 v55, 0, v38, s[18:19]
	v_sub_f32_e32 v38, v40, v0
	v_cndmask_b32_e64 v56, 0, v34, s[6:7]
	v_sub_f32_e32 v34, v37, v0
	v_sub_f32_e32 v0, v41, v0
	v_exp_f32_e32 v36, v36
	v_exp_f32_e32 v38, v38
	v_cndmask_b32_e64 v57, 0, v35, s[14:15]
	v_exp_f32_e32 v34, v34
	v_exp_f32_e32 v0, v0
	v_mov_b32_e32 v62, v1
	v_mov_b32_e32 v63, v1
	v_cvt_pk_fp8_f32 v62, v54, v56
	v_cvt_pk_fp8_f32 v63, v55, v57
	v_cndmask_b32_e64 v58, 0, v36, s[8:9]
	v_cndmask_b32_e64 v59, 0, v38, s[16:17]
	v_cndmask_b32_e64 v64, 0, v34, s[4:5]
	v_cndmask_b32_e64 v0, 0, v0, s[12:13]
	v_cvt_pk_fp8_f32 v62, v58, v64 op_sel:[0,0,1]
	v_cvt_pk_fp8_f32 v63, v59, v0 op_sel:[0,0,1]
	v_add_f32_e32 v0, v64, v0
	v_mov_b32_e32 v207, v205
	s_waitcnt vmcnt(19)
	v_mfma_f32_16x16x32_fp8_fp8 v[34:37], v[116:117], v[62:63], v[2:5]
	s_nop 2
	v_add_f32_e32 v2, v54, v55
	v_add_f32_e32 v2, 0, v2
	v_add_f32_e32 v3, v56, v57
	v_mfma_f32_16x16x32_fp8_fp8 v[38:41], v[118:119], v[62:63], v[6:9]
	v_add_f32_e32 v2, v3, v2
	v_add_f32_e32 v3, v58, v59
	v_add_f32_e32 v2, v3, v2
	s_waitcnt vmcnt(18)
	v_mfma_f32_16x16x32_fp8_fp8 v[42:45], v[120:121], v[62:63], v[10:13]
	v_add_f32_e32 v0, v0, v2
	v_add_f32_e32 v208, v206, v0
	v_mfma_f32_16x16x32_fp8_fp8 v[46:49], v[122:123], v[62:63], v[14:17]
	s_waitcnt vmcnt(17)
	v_mfma_f32_16x16x32_fp8_fp8 v[50:53], v[124:125], v[62:63], v[18:21]
	v_mfma_f32_16x16x32_fp8_fp8 v[54:57], v[126:127], v[62:63], v[22:25]
	s_waitcnt vmcnt(16)
	v_mfma_f32_16x16x32_fp8_fp8 v[58:61], v[128:129], v[62:63], v[30:33]
	v_mfma_f32_16x16x32_fp8_fp8 v[62:65], v[130:131], v[62:63], v[26:29]
	s_cmp_gt_i32 s67, s61
	s_mov_b64 s[4:5], -1
	s_cbranch_scc1 .LBB0_737
.LBB0_758:
	s_add_i32 s66, s66, 4
	s_min_i32 s4, s66, s61
	s_add_i32 s6, s4, s60
	s_lshl_b32 s63, s6, 5
	s_and_b32 s4, s63, 0x3fffffe0
	s_lshr_b32 s24, s4, 4
	s_lshl_b64 s[4:5], s[24:25], 11
	s_and_b32 s24, s6, 0x1ffffff
	s_and_b32 s8, s42, 0x2000000
	s_lshl_b64 s[6:7], s[24:25], 12
	s_cmp_eq_u32 s8, 0
	v_lshl_add_u64 v[198:199], v[82:83], 0, s[4:5]
	v_lshl_add_u64 v[196:197], v[84:85], 0, s[6:7]
	s_mov_b64 s[4:5], -1
	v_add_f32_e32 v209, 4.0, v207
	s_cbranch_scc1 .LBB0_762
	v_lshl_add_u64 v[244:245], v[198:199], 0, v[98:99]
	global_load_dwordx4 v[148:151], v[244:245], off
	global_load_dwordx4 v[152:155], v[244:245], off offset:1024
	global_load_dwordx4 v[156:159], v[244:245], off offset:2048
	global_load_dwordx4 v[160:163], v[244:245], off offset:3072
	v_lshl_add_u64 v[246:247], v[196:197], 0, v[98:99]
	global_load_dwordx4 v[116:119], v[246:247], off
	global_load_dwordx4 v[120:123], v[246:247], off offset:1024
	global_load_dwordx4 v[124:127], v[246:247], off offset:2048
	global_load_dwordx4 v[128:131], v[246:247], off offset:3072
	s_waitcnt vmcnt(20)
	v_mfma_f32_16x16x32_fp8_fp8 v[2:5], v[180:181], v[74:75], 0
	v_mov_b64_e32 v[72:73], v[64:65]
	v_mov_b64_e32 v[68:69], v[60:61]
	v_mov_b64_e32 v[30:31], v[54:55]
	v_mfma_f32_16x16x32_fp8_fp8 v[6:9], v[188:189], v[74:75], 0
	v_mov_b64_e32 v[26:27], v[50:51]
	v_mov_b64_e32 v[22:23], v[46:47]
	v_mov_b64_e32 v[18:19], v[42:43]
	v_mfma_f32_16x16x32_fp8_fp8 v[2:5], v[182:183], v[76:77], v[2:5]
	v_mov_b64_e32 v[14:15], v[38:39]
	v_mov_b32_e32 v205, v207
	v_mov_b64_e32 v[70:71], v[62:63]
	v_mfma_f32_16x16x32_fp8_fp8 v[6:9], v[190:191], v[76:77], v[6:9]
	v_mov_b64_e32 v[66:67], v[58:59]
	v_mov_b64_e32 v[32:33], v[56:57]
	v_mov_b64_e32 v[28:29], v[52:53]
	v_mfma_f32_16x16x32_fp8_fp8 v[2:5], v[184:185], v[78:79], v[2:5]
	v_mov_b64_e32 v[24:25], v[48:49]
	v_mov_b64_e32 v[20:21], v[44:45]
	v_mov_b64_e32 v[16:17], v[40:41]
	v_mfma_f32_16x16x32_fp8_fp8 v[6:9], v[192:193], v[78:79], v[6:9]
	v_mov_b32_e32 v206, v208
	v_mfma_f32_16x16x32_fp8_fp8 v[2:5], v[186:187], v[80:81], v[2:5]
	v_mfma_f32_16x16x32_fp8_fp8 v[6:9], v[194:195], v[80:81], v[6:9]
	s_nop 5
	v_max_f32_e32 v0, v3, v3
	v_max_f32_e32 v10, v2, v2
	v_max_f32_e32 v0, v10, v0
	v_max_f32_e32 v10, v5, v5
	v_max_f32_e32 v11, v4, v4
	v_max_f32_e32 v10, v11, v10
	v_max_f32_e32 v11, v9, v9
	v_max_f32_e32 v12, v8, v8
	v_max_f32_e32 v11, v12, v11
	v_max3_f32 v11, v6, v7, v11
	v_max3_f32 v0, v0, v10, v11
	v_mov_b64_e32 v[10:11], v[34:35]
	v_cmp_gt_f32_e32 vcc, v0, v209
	v_mov_b64_e32 v[12:13], v[36:37]
	s_cbranch_vccz .LBB0_761
	v_and_b32_e32 v11, 64, v200
	v_xor_b32_e32 v10, 16, v200
	v_add_u32_e32 v11, 64, v11
	v_cmp_lt_i32_e32 vcc, v10, v11
	v_xor_b32_e32 v12, 32, v200
	s_nop 0
	v_cndmask_b32_e32 v10, v200, v10, vcc
	v_lshlrev_b32_e32 v10, 2, v10
	ds_bpermute_b32 v10, v10, v0
	v_max_f32_e32 v0, v0, v0
	v_cmp_lt_i32_e32 vcc, v12, v11
	s_waitcnt lgkmcnt(0)
	v_max_f32_e32 v10, v10, v10
	v_max_f32_e32 v0, v0, v10
	v_cndmask_b32_e32 v10, v200, v12, vcc
	v_lshlrev_b32_e32 v10, 2, v10
	ds_bpermute_b32 v10, v10, v0
	s_waitcnt lgkmcnt(0)
	v_max3_f32 v205, v207, v0, v10
	v_sub_f32_e32 v0, v207, v205
	v_exp_f32_e32 v0, v0
	s_nop 0
	v_mul_f32_e32 v206, v208, v0
	v_pk_mul_f32 v[12:13], v[36:37], v[0:1] op_sel_hi:[1,0]
	v_pk_mul_f32 v[10:11], v[34:35], v[0:1] op_sel_hi:[1,0]
	v_pk_mul_f32 v[16:17], v[40:41], v[0:1] op_sel_hi:[1,0]
	v_pk_mul_f32 v[14:15], v[38:39], v[0:1] op_sel_hi:[1,0]
	v_pk_mul_f32 v[20:21], v[44:45], v[0:1] op_sel_hi:[1,0]
	v_pk_mul_f32 v[18:19], v[42:43], v[0:1] op_sel_hi:[1,0]
	v_pk_mul_f32 v[24:25], v[48:49], v[0:1] op_sel_hi:[1,0]
	v_pk_mul_f32 v[22:23], v[46:47], v[0:1] op_sel_hi:[1,0]
	v_pk_mul_f32 v[28:29], v[52:53], v[0:1] op_sel_hi:[1,0]
	v_pk_mul_f32 v[26:27], v[50:51], v[0:1] op_sel_hi:[1,0]
	v_pk_mul_f32 v[32:33], v[56:57], v[0:1] op_sel_hi:[1,0]
	v_pk_mul_f32 v[30:31], v[54:55], v[0:1] op_sel_hi:[1,0]
	v_pk_mul_f32 v[68:69], v[60:61], v[0:1] op_sel_hi:[1,0]
	v_pk_mul_f32 v[66:67], v[58:59], v[0:1] op_sel_hi:[1,0]
	v_pk_mul_f32 v[72:73], v[64:65], v[0:1] op_sel_hi:[1,0]
	v_pk_mul_f32 v[70:71], v[62:63], v[0:1] op_sel_hi:[1,0]
; template <bool SLC, bool NOMASK> ...
;     ...
;     load_frag8(nxt, KF, VF, SLC ? (dnext & 0xfffff) : dnext, lane);
;     f32x4 sa[2] = {(f32x4){0.f, 0.f, 0.f, 0.f}, (f32x4){0.f, 0.f, 0.f, 0.f}};
; #pragma unroll
;     for (int T = 0; T < 2; ++T)
; #pragma unroll
;         for (int s2 = 0; s2 < 4; ++s2) sa[T] = __builtin_amdgcn_mfma_f32_16x16x32_fp8_fp8(cur.k[T][s2], qf[s2], sa[T], 0, 0, 0);
;     float sc[8]; bool vd[8]; float mx = -1e30f;
;     const bool act = lo == 0 || !SLC;
;     if (NOMASK) {
; #pragma unroll
;         for (int j = 0; j < 8; ++j) { sc[j] = sa[j >> 2][j & 3]; vd[j] = act; }
;         mx = fmaxf(fmaxf(fmaxf(sc[0], sc[1]), fmaxf(sc[2], sc[3])), fmaxf(fmaxf(sc[4], sc[5]), fmaxf(sc[6], sc[7])));
;         mx = act ? mx : -1e30f;
;     } else {
; #pragma unroll
;         for (int T = 0; T < 2; ++T)
; #pragma unroll
;             for (int r = 0; r < 4; ++r) { const int p = pos0 + 16 * T + 4 * kq + r; const bool v = (p >= lo) & (p <= hi); const float x = sa[T][r];
;                 sc[4 * T + r] = x; vd[4 * T + r] = v; mx = v ? fmaxf(mx, x) : mx; }
;     }
;     if (__builtin_amdgcn_ballot_w64(mx > st.m + 4.f) != 0ull) {
;         mx = fmaxf(mx, __shfl_xor(mx, 16)); mx = fmaxf(mx, __shfl_xor(mx, 32));
;         const float mn = fmaxf(st.m, mx), alpha = __builtin_amdgcn_exp2f(st.m - mn); st.m = mn; st.l *= alpha;
; #pragma unroll
;         for (int j = 0; j < 8; ++j) st.o[j] = st.o[j] * alpha;
;     }
;     f32x4 pa, pb; float ps = 0.f;
;     const float mref = st.m - 4.f;
;     if (NOMASK) {
; #pragma unroll
;         for (int j = 0; j < 4; ++j) { pa[j] = __builtin_amdgcn_exp2f(sc[j] - mref); pb[j] = __builtin_amdgcn_exp2f(sc[4 + j] - mref); }
;         if (SLC) {
; #pragma unroll
;             for (int j = 0; j < 4; ++j) { pa[j] = act ? pa[j] : 0.f; pb[j] = act ? pb[j] : 0.f; }
;         }
; #pragma unroll
;         for (int j = 0; j < 4; ++j) ps += pa[j] + pb[j];
;     } else {
; #pragma unroll
;         for (int j = 0; j < 4; ++j) { pa[j] = vd[j] ? __builtin_amdgcn_exp2f(sc[j] - mref) : 0.f; pb[j] = vd[4 + j] ? __builtin_amdgcn_exp2f(sc[4 + j] - mref) : 0.f; ps += pa[j] + pb[j]; }
;     }
;     st.l += ps;
;     const u32x2 pw = pack8_fp8(pa, pb);
;     const i64_t pf = __builtin_bit_cast(i64_t, pw);
; #pragma unroll
;     for (int db = 0; db < 8; ++db) st.o[db] = __builtin_amdgcn_mfma_f32_16x16x32_fp8_fp8(cur.v[db], pf, st.o[db], 0, 0, 0);
.LBB0_761:
	v_add_f32_e32 v211, -4.0, v205
	v_sub_f32_e32 v0, v2, v211
	v_exp_f32_e32 v213, v0
	v_sub_f32_e32 v0, v6, v211
	v_exp_f32_e32 v215, v0
	v_sub_f32_e32 v0, v3, v211
	v_exp_f32_e32 v210, v0
	v_sub_f32_e32 v0, v7, v211
	v_exp_f32_e32 v0, v0
	v_sub_f32_e32 v2, v4, v211
	v_exp_f32_e32 v218, v2
	v_sub_f32_e32 v2, v8, v211
	v_exp_f32_e32 v219, v2
	v_sub_f32_e32 v2, v5, v211
	v_exp_f32_e32 v212, v2
	v_sub_f32_e32 v2, v9, v211
	v_mov_b32_e32 v216, v1
	v_mov_b32_e32 v217, v1
	v_exp_f32_e32 v214, v2
	v_cvt_pk_fp8_f32 v216, v213, v210
	v_cvt_pk_fp8_f32 v217, v215, v0
	v_add_f32_e32 v211, v213, v215
	v_add_f32_e32 v213, v218, v219
	v_cvt_pk_fp8_f32 v216, v218, v212 op_sel:[0,0,1]
	v_cvt_pk_fp8_f32 v217, v219, v214 op_sel:[0,0,1]
	s_mov_b64 s[4:5], 0
	s_waitcnt vmcnt(19)
	v_mfma_f32_16x16x32_fp8_fp8 v[2:5], v[164:165], v[216:217], v[10:13]
	v_mfma_f32_16x16x32_fp8_fp8 v[10:13], v[168:169], v[216:217], v[18:21]
	s_waitcnt vmcnt(18)
	v_mfma_f32_16x16x32_fp8_fp8 v[18:21], v[172:173], v[216:217], v[26:29]
	s_nop 2
	v_add_f32_e64 v26, v210, v0
	v_add_f32_e64 v27, v211, v1
	v_mfma_f32_16x16x32_fp8_fp8 v[6:9], v[166:167], v[216:217], v[14:17]
	v_pk_add_f32 v[26:27], v[26:27], v[26:27] op_sel_hi:[0,1]
	v_mov_b32_e32 v215, v27
	v_pk_add_f32 v[26:27], v[212:213], v[214:215]
	s_waitcnt vmcnt(17)
	v_mfma_f32_16x16x32_fp8_fp8 v[14:17], v[170:171], v[216:217], v[22:25]
	v_add_f32_e32 v0, v26, v27
	v_add_f32_e32 v206, v0, v206
	v_mfma_f32_16x16x32_fp8_fp8 v[22:25], v[174:175], v[216:217], v[30:33]
	s_waitcnt vmcnt(16)
	v_mfma_f32_16x16x32_fp8_fp8 v[30:33], v[176:177], v[216:217], v[66:69]
	v_mfma_f32_16x16x32_fp8_fp8 v[26:29], v[178:179], v[216:217], v[70:73]
.LBB0_762:
	s_and_b64 vcc, exec, s[4:5]
	s_cbranch_vccz .LBB0_766
	v_lshl_add_u64 v[244:245], v[198:199], 0, v[98:99]
	global_load_dwordx4 v[148:151], v[244:245], off
	global_load_dwordx4 v[152:155], v[244:245], off offset:1024
	global_load_dwordx4 v[156:159], v[244:245], off offset:2048
	global_load_dwordx4 v[160:163], v[244:245], off offset:3072
	v_lshl_add_u64 v[246:247], v[196:197], 0, v[98:99]
	global_load_dwordx4 v[116:119], v[246:247], off
	global_load_dwordx4 v[120:123], v[246:247], off offset:1024
	global_load_dwordx4 v[124:127], v[246:247], off offset:2048
	global_load_dwordx4 v[128:131], v[246:247], off offset:3072
	s_waitcnt vmcnt(20)
	v_mfma_f32_16x16x32_fp8_fp8 v[2:5], v[180:181], v[74:75], 0
	v_or_b32_e32 v0, s68, v107
	v_cmp_ge_i32_e32 vcc, v0, v105
	v_cmp_le_i32_e64 s[4:5], v0, v204
	v_mfma_f32_16x16x32_fp8_fp8 v[2:5], v[182:183], v[76:77], v[2:5]
	s_and_b64 s[10:11], vcc, s[4:5]
	v_or_b32_e32 v11, 1, v0
	v_cmp_ge_i32_e32 vcc, v11, v105
	v_mfma_f32_16x16x32_fp8_fp8 v[2:5], v[184:185], v[78:79], v[2:5]
	v_cmp_lt_i32_e64 s[4:5], v0, v204
	s_and_b64 s[6:7], s[4:5], vcc
	v_mfma_f32_16x16x32_fp8_fp8 v[6:9], v[188:189], v[74:75], 0
	v_mfma_f32_16x16x32_fp8_fp8 v[2:5], v[186:187], v[80:81], v[2:5]
	v_mfma_f32_16x16x32_fp8_fp8 v[6:9], v[190:191], v[76:77], v[6:9]
	v_mfma_f32_16x16x32_fp8_fp8 v[6:9], v[192:193], v[78:79], v[6:9]
	s_nop 3
	v_max_f32_e32 v10, v2, v2
	v_max_f32_e32 v10, 0xf149f2ca, v10
	v_cndmask_b32_e64 v10, v203, v10, s[10:11]
	v_max_f32_e32 v11, v3, v3
	v_max_f32_e32 v11, v10, v11
	v_cndmask_b32_e64 v10, v10, v11, s[6:7]
	v_or_b32_e32 v11, 2, v0
	v_cmp_ge_i32_e32 vcc, v11, v105
	v_cmp_le_i32_e64 s[4:5], v11, v204
	v_max_f32_e32 v11, v4, v4
	v_max_f32_e32 v11, v10, v11
	s_and_b64 s[8:9], vcc, s[4:5]
	v_mfma_f32_16x16x32_fp8_fp8 v[6:9], v[194:195], v[80:81], v[6:9]
	v_cndmask_b32_e64 v10, v10, v11, s[8:9]
	v_or_b32_e32 v11, 3, v0
	v_cmp_ge_i32_e32 vcc, v11, v105
	v_cmp_le_i32_e64 s[4:5], v11, v204
	v_max_f32_e32 v11, v5, v5
	v_max_f32_e32 v11, v10, v11
	s_and_b64 s[4:5], vcc, s[4:5]
	v_cndmask_b32_e64 v10, v10, v11, s[4:5]
	v_or_b32_e32 v11, 16, v0
	v_cmp_ge_i32_e32 vcc, v11, v105
	v_cmp_le_i32_e64 s[12:13], v11, v204
	v_max_f32_e32 v11, v6, v6
	v_max_f32_e32 v11, v10, v11
	s_and_b64 s[18:19], vcc, s[12:13]
	v_cndmask_b32_e64 v10, v10, v11, s[18:19]
	v_or_b32_e32 v11, 17, v0
	v_cmp_ge_i32_e32 vcc, v11, v105
	v_cmp_le_i32_e64 s[12:13], v11, v204
	v_max_f32_e32 v11, v10, v10
	v_max_f32_e32 v12, v7, v7
	v_max_f32_e32 v11, v11, v12
	s_and_b64 s[14:15], vcc, s[12:13]
	v_cndmask_b32_e64 v10, v10, v11, s[14:15]
	v_or_b32_e32 v11, 18, v0
	v_cmp_ge_i32_e32 vcc, v11, v105
	v_cmp_le_i32_e64 s[12:13], v11, v204
	v_max_f32_e32 v11, v10, v10
	v_max_f32_e32 v12, v8, v8
	v_max_f32_e32 v11, v11, v12
	s_and_b64 s[16:17], vcc, s[12:13]
	v_cndmask_b32_e64 v10, v10, v11, s[16:17]
	v_or_b32_e32 v0, 19, v0
	v_cmp_ge_i32_e32 vcc, v0, v105
	v_cmp_le_i32_e64 s[12:13], v0, v204
	v_max_f32_e32 v0, v10, v10
	v_max_f32_e32 v11, v9, v9
	v_max_f32_e32 v0, v0, v11
	s_and_b64 s[12:13], vcc, s[12:13]
	v_cndmask_b32_e64 v0, v10, v0, s[12:13]
	v_cmp_gt_f32_e32 vcc, v0, v209
	s_cbranch_vccz .LBB0_765
	v_and_b32_e32 v11, 64, v200
	v_xor_b32_e32 v10, 16, v200
	v_add_u32_e32 v11, 64, v11
	v_cmp_lt_i32_e32 vcc, v10, v11
	v_xor_b32_e32 v12, 32, v200
	s_nop 0
	v_cndmask_b32_e32 v10, v200, v10, vcc
	v_lshlrev_b32_e32 v10, 2, v10
	ds_bpermute_b32 v10, v10, v0
	v_max_f32_e32 v0, v0, v0
	v_cmp_lt_i32_e32 vcc, v12, v11
	s_waitcnt lgkmcnt(0)
	v_max_f32_e32 v10, v10, v10
	v_max_f32_e32 v0, v0, v10
	v_cndmask_b32_e32 v10, v200, v12, vcc
	v_lshlrev_b32_e32 v10, 2, v10
	ds_bpermute_b32 v10, v10, v0
	s_waitcnt lgkmcnt(0)
	v_max3_f32 v10, v207, v0, v10
	v_sub_f32_e32 v0, v207, v10
	v_exp_f32_e32 v0, v0
	v_mov_b32_e32 v207, v10
	v_mul_f32_e32 v208, v208, v0
	v_pk_mul_f32 v[36:37], v[36:37], v[0:1] op_sel_hi:[1,0]
	v_pk_mul_f32 v[34:35], v[34:35], v[0:1] op_sel_hi:[1,0]
	v_pk_mul_f32 v[40:41], v[40:41], v[0:1] op_sel_hi:[1,0]
	v_pk_mul_f32 v[38:39], v[38:39], v[0:1] op_sel_hi:[1,0]
	v_pk_mul_f32 v[44:45], v[44:45], v[0:1] op_sel_hi:[1,0]
	v_pk_mul_f32 v[42:43], v[42:43], v[0:1] op_sel_hi:[1,0]
	v_pk_mul_f32 v[48:49], v[48:49], v[0:1] op_sel_hi:[1,0]
	v_pk_mul_f32 v[46:47], v[46:47], v[0:1] op_sel_hi:[1,0]
	v_pk_mul_f32 v[52:53], v[52:53], v[0:1] op_sel_hi:[1,0]
	v_pk_mul_f32 v[50:51], v[50:51], v[0:1] op_sel_hi:[1,0]
	v_pk_mul_f32 v[56:57], v[56:57], v[0:1] op_sel_hi:[1,0]
	v_pk_mul_f32 v[54:55], v[54:55], v[0:1] op_sel_hi:[1,0]
	v_pk_mul_f32 v[60:61], v[60:61], v[0:1] op_sel_hi:[1,0]
	v_pk_mul_f32 v[58:59], v[58:59], v[0:1] op_sel_hi:[1,0]
	v_pk_mul_f32 v[64:65], v[64:65], v[0:1] op_sel_hi:[1,0]
	v_pk_mul_f32 v[62:63], v[62:63], v[0:1] op_sel_hi:[1,0]
; template <bool SLC, bool NOMASK> ...
;     ...
;     f32x4 pa, pb; float ps = 0.f;
;     const float mref = st.m - 4.f;
;     if (NOMASK) {
; #pragma unroll
;         for (int j = 0; j < 4; ++j) { pa[j] = __builtin_amdgcn_exp2f(sc[j] - mref); pb[j] = __builtin_amdgcn_exp2f(sc[4 + j] - mref); }
;         if (SLC) {
; #pragma unroll
;             for (int j = 0; j < 4; ++j) { pa[j] = act ? pa[j] : 0.f; pb[j] = act ? pb[j] : 0.f; }
;         }
; #pragma unroll
;         for (int j = 0; j < 4; ++j) ps += pa[j] + pb[j];
;     } else {
; #pragma unroll
;         for (int j = 0; j < 4; ++j) { pa[j] = vd[j] ? __builtin_amdgcn_exp2f(sc[j] - mref) : 0.f; pb[j] = vd[4 + j] ? __builtin_amdgcn_exp2f(sc[4 + j] - mref) : 0.f; ps += pa[j] + pb[j]; }
;     }
;     st.l += ps;
;     const u32x2 pw = pack8_fp8(pa, pb);
;     const i64_t pf = __builtin_bit_cast(i64_t, pw);
; #pragma unroll
;     for (int db = 0; db < 8; ++db) st.o[db] = __builtin_amdgcn_mfma_f32_16x16x32_fp8_fp8(cur.v[db], pf, st.o[db], 0, 0, 0);
.LBB0_765:
	v_add_f32_e32 v0, -4.0, v207
	v_sub_f32_e32 v2, v2, v0
	v_exp_f32_e32 v2, v2
	v_sub_f32_e32 v6, v6, v0
	v_exp_f32_e32 v6, v6
	v_sub_f32_e32 v4, v4, v0
	v_cndmask_b32_e64 v22, 0, v2, s[10:11]
	v_sub_f32_e32 v2, v3, v0
	v_exp_f32_e32 v2, v2
	v_sub_f32_e32 v3, v7, v0
	v_exp_f32_e32 v3, v3
	v_cndmask_b32_e64 v23, 0, v6, s[18:19]
	v_sub_f32_e32 v6, v8, v0
	v_cndmask_b32_e64 v24, 0, v2, s[6:7]
	v_sub_f32_e32 v2, v5, v0
	v_sub_f32_e32 v0, v9, v0
	v_exp_f32_e32 v4, v4
	v_exp_f32_e32 v6, v6
	v_cndmask_b32_e64 v25, 0, v3, s[14:15]
	v_exp_f32_e32 v2, v2
	v_exp_f32_e32 v0, v0
	v_mov_b32_e32 v26, v1
	v_mov_b32_e32 v27, v1
	v_cvt_pk_fp8_f32 v26, v22, v24
	v_cvt_pk_fp8_f32 v27, v23, v25
	v_cndmask_b32_e64 v28, 0, v4, s[8:9]
	v_cndmask_b32_e64 v29, 0, v6, s[16:17]
	v_cndmask_b32_e64 v66, 0, v2, s[4:5]
	v_cndmask_b32_e64 v0, 0, v0, s[12:13]
	v_cvt_pk_fp8_f32 v26, v28, v66 op_sel:[0,0,1]
	v_cvt_pk_fp8_f32 v27, v29, v0 op_sel:[0,0,1]
	v_add_f32_e32 v22, v22, v23
	v_add_f32_e32 v30, 0, v22
	v_add_f32_e32 v31, v24, v25
	v_add_f32_e32 v30, v31, v30
	v_add_f32_e32 v28, v28, v29
	v_add_f32_e32 v28, v28, v30
	v_add_f32_e32 v0, v66, v0
	s_waitcnt vmcnt(19)
	v_mfma_f32_16x16x32_fp8_fp8 v[2:5], v[164:165], v[26:27], v[34:37]
	v_add_f32_e32 v0, v0, v28
	v_add_f32_e32 v206, v208, v0
	v_mov_b32_e32 v205, v207
	v_mfma_f32_16x16x32_fp8_fp8 v[6:9], v[166:167], v[26:27], v[38:41]
	s_waitcnt vmcnt(18)
	v_mfma_f32_16x16x32_fp8_fp8 v[10:13], v[168:169], v[26:27], v[42:45]
	v_mfma_f32_16x16x32_fp8_fp8 v[14:17], v[170:171], v[26:27], v[46:49]
	s_waitcnt vmcnt(17)
	v_mfma_f32_16x16x32_fp8_fp8 v[18:21], v[172:173], v[26:27], v[50:53]
	v_mfma_f32_16x16x32_fp8_fp8 v[22:25], v[174:175], v[26:27], v[54:57]
	s_waitcnt vmcnt(16)
	v_mfma_f32_16x16x32_fp8_fp8 v[30:33], v[176:177], v[26:27], v[58:61]
	v_mfma_f32_16x16x32_fp8_fp8 v[26:29], v[178:179], v[26:27], v[62:65]

; __device__ __forceinline__ float bf2f(unsigned short b) { return __uint_as_float(((unsigned)b) << 16); }
; __device__ __forceinline__ void dilated_unit(int unit, const bf16_t* proj, const bf16_t* kbf, bf16_t* nsaout, int lane) {
;     ...
;     for (int pt = 0; pt < 3; ++pt) {
;         const int sh = 2 * pt, head = 4 * pt + hg;
;         const bf16_t* qrow = proj + (size_t)tc * PLD + PC_QB + head * 128 + 8 * kq;
;         i64_t q8[4];
; #pragma unroll
;         for (int s = 0; s < 4; ++s) { const bf16x8 qv = *(const bf16x8*)(qrow + 32 * s); f32x4 a, b;
; #pragma unroll
;             for (int j = 0; j < 4; ++j) { a[j] = bf2f((unsigned short)qv[j]) * SL2; b[j] = bf2f((unsigned short)qv[4 + j]) * SL2; }
;             q8[s] = __builtin_bit_cast(i64_t, pack8_fp8(a, b)); }
;         const int base = (r16 & ((1 << sh) - 1)) << (14 - sh), u0 = t0 >> sh, ui = u0 + (16 >> sh) * l16;
;         const int lo = base + (ui - 128 < 0 ? 0 : ui - 128), hi = base + ui;
;         const int first = (base + (u0 - 128 < 0 ? 0 : u0 - 128)) >> 5, last = (base + u0 + 15 * (16 >> sh)) >> 5;
;         unsigned long long hoff = (unsigned long long)head * S * 128; asm volatile("" : "+s"(hoff));
;         auto desc = [&](int i) { return 32 * (first + i); };
;         attn_run_frag8<false>(q8, kb8 + hoff, vb8 + hoff, desc, last - first + 1, lo, hi, 0, st, lane);
;     }
.LBB0_768:
	s_waitcnt vmcnt(8)
	s_nop 1
	v_mov_b64_e32 v[68:69], v[28:29]
	s_waitcnt vmcnt(0)
	v_mov_b64_e32 v[96:97], v[4:5]
	v_mov_b64_e32 v[92:93], v[8:9]
	v_mov_b64_e32 v[88:89], v[12:13]
	v_mov_b64_e32 v[84:85], v[16:17]
	v_mov_b64_e32 v[80:81], v[20:21]
	v_mov_b64_e32 v[76:77], v[24:25]
	v_mov_b64_e32 v[72:73], v[32:33]
	v_mov_b64_e32 v[66:67], v[26:27]
	v_mov_b64_e32 v[94:95], v[2:3]
	v_mov_b64_e32 v[90:91], v[6:7]
	v_mov_b64_e32 v[86:87], v[10:11]
	v_mov_b64_e32 v[82:83], v[14:15]
	v_mov_b64_e32 v[78:79], v[18:19]
	v_mov_b64_e32 v[74:75], v[22:23]
	v_mov_b64_e32 v[70:71], v[30:31]
	s_add_i32 s59, s59, 1
	s_cmp_lg_u32 s59, 3
	s_cbranch_scc0 .LBB0_733
